# mid-block s_setprio 0/1 flip removed: each 32-MFMA segment runs at one priority
# speedup vs baseline: 1.0001x; 1.0001x over previous
; #define PG8_STAGE(bufoff, gbase, voff) do { _Pragma("unroll") for (int _i = 0; _i < 2; ++_i) \
;         __builtin_amdgcn_global_load_lds((const unsigned*)((const char*)(gbase) + (voff)[_i]), (LAS unsigned*)(lds + (bufoff) + ldsw + _i * 8192), 16, 0, 0); } while (0)
; #define PG8_LDA(dst, b, h) do { _Pragma("unroll") for (int m = 0; m < 4; ++m) _Pragma("unroll") for (int k = 0; k < 2; ++k) dst[m][k] = *(const LAS bf16x8*)(lds + PG8_SA(b, h) + aoff + m * 2048 + k * 1024); } while (0)
; #define PG8_LDB(dst, b, h) do { _Pragma("unroll") for (int n = 0; n < 2; ++n) _Pragma("unroll") for (int k = 0; k < 2; ++k) dst[n][k] = *(const LAS bf16x8*)(lds + PG8_SB(b, h) + boff + n * 2048 + k * 1024); } while (0)
; #define PG8_MMA(ai, bj, At, Bt) do { __builtin_amdgcn_s_setprio(1); _Pragma("unroll") for (int m = 0; m < 4; ++m) _Pragma("unroll") for (int n = 0; n < 2; ++n) _Pragma("unroll") for (int k = 0; k < 2; ++k) \
;         acc[ai][bj][m][n] = __builtin_amdgcn_mfma_f32_16x16x32_bf16(Bt[n][k], At[m][k], acc[ai][bj][m][n], 0, 0, 0); __builtin_amdgcn_s_setprio(0); } while (0)
; #define PG8_WAIT_V(n) asm volatile("s_waitcnt vmcnt(" #n ")" ::: "memory")
; #define PG8_WAIT_L(n) asm volatile("s_waitcnt lgkmcnt(" #n ")" ::: "memory")
; #define PG8_BAR __builtin_amdgcn_s_barrier()
; #define PG8_SCHED __builtin_amdgcn_sched_barrier(0)
; template <class EpiT>
; __device__ __forceinline__ void gemm_phase(LAS unsigned char* lds, const Gemm g, const StaticOrder& S, const EpiT& E) {
;     ...
;             const bool last = (t == nt - 2);
;             const char* a1 = cA + (size_t)(t + 1) * kstep;
;             const char* a2 = last ? nA : cA + (size_t)(t + 2) * kstep; const char* b2 = last ? nB : cB + (size_t)(t + 2) * kstep;
;             const char* a3 = a2 + kstep; const char* b3 = b2 + kstep;
;             PG8_LDB(B0, 0, 0); PG8_LDB(B1, 0, 1); PG8_SCHED; PG8_LDA(At, 0, 0); PG8_STAGE(PG8_SA(1, 1), a1 + hstepA, voffA);
;             PG8_WAIT_V(8); PG8_WAIT_L(0); PG8_BAR; PG8_MMA(0, 0, At, B0); PG8_MMA(0, 1, At, B1); PG8_BAR; PG8_SCHED;
;             PG8_LDA(At, 0, 1); PG8_STAGE(PG8_SB(0, 0), b2, voffB); PG8_STAGE(PG8_SB(0, 1), b2 + hstepB, voffB); PG8_STAGE(PG8_SA(0, 0), a2, voffA);
.LBB0_100:
	ds_read_b128 v[128:131], v160
	ds_read_b128 v[170:173], v160 offset:1024
	ds_read_b128 v[174:177], v160 offset:2048
	ds_read_b128 v[178:181], v160 offset:3072
	ds_read_b128 v[182:185], v161
	ds_read_b128 v[186:189], v161 offset:1024
	ds_read_b128 v[190:193], v161 offset:2048
	ds_read_b128 v[194:197], v161 offset:3072
	s_add_u32 s18, s16, 0xfff7c080
	s_addc_u32 s19, s17, -1
	s_cmp_eq_u32 s53, 28
	s_cselect_b32 s21, s3, s19
	s_cselect_b32 s20, s2, s18
	s_cselect_b32 s19, s15, s52
	s_cselect_b32 s18, s14, s51
	v_lshl_add_u64 v[158:159], s[16:17], 0, v[150:151]
	s_add_i32 m0, s35, 0xc000
	ds_read_b128 v[198:201], v162
	ds_read_b128 v[202:205], v162 offset:1024
	ds_read_b128 v[206:209], v162 offset:2048
	ds_read_b128 v[210:213], v162 offset:3072
	ds_read_b128 v[214:217], v162 offset:4096
	ds_read_b128 v[218:221], v162 offset:5120
	ds_read_b128 v[222:225], v162 offset:6144
	ds_read_b128 v[226:229], v162 offset:7168
	global_load_lds_dwordx4 v[158:159], off
	v_lshl_add_u64 v[158:159], s[16:17], 0, v[152:153]
	s_add_i32 m0, s35, 0xe000
	s_nop 0
	global_load_lds_dwordx4 v[158:159], off
	s_waitcnt vmcnt(8)
	s_waitcnt lgkmcnt(0)
	s_barrier
	s_setprio 1
	s_waitcnt lgkmcnt(0)
	v_mfma_f32_16x16x32_bf16 v[124:127], v[128:131], v[198:201], v[124:127]
	v_mfma_f32_16x16x32_bf16 v[124:127], v[170:173], v[202:205], v[124:127]
	v_mfma_f32_16x16x32_bf16 v[108:111], v[128:131], v[206:209], v[108:111]
	v_mfma_f32_16x16x32_bf16 v[108:111], v[170:173], v[210:213], v[108:111]
	v_mfma_f32_16x16x32_bf16 v[92:95], v[128:131], v[214:217], v[92:95]
	v_mfma_f32_16x16x32_bf16 v[92:95], v[170:173], v[218:221], v[92:95]
	v_mfma_f32_16x16x32_bf16 v[76:79], v[128:131], v[222:225], v[76:79]
	v_mfma_f32_16x16x32_bf16 v[76:79], v[170:173], v[226:229], v[76:79]
	v_mfma_f32_16x16x32_bf16 v[120:123], v[174:177], v[198:201], v[120:123]
	v_mfma_f32_16x16x32_bf16 v[120:123], v[178:181], v[202:205], v[120:123]
	v_mfma_f32_16x16x32_bf16 v[104:107], v[174:177], v[206:209], v[104:107]
	v_mfma_f32_16x16x32_bf16 v[104:107], v[178:181], v[210:213], v[104:107]
	v_mfma_f32_16x16x32_bf16 v[88:91], v[174:177], v[214:217], v[88:91]
	v_mfma_f32_16x16x32_bf16 v[88:91], v[178:181], v[218:221], v[88:91]
	v_mfma_f32_16x16x32_bf16 v[72:75], v[174:177], v[222:225], v[72:75]
	v_mfma_f32_16x16x32_bf16 v[72:75], v[178:181], v[226:229], v[72:75]
	v_mfma_f32_16x16x32_bf16 v[116:119], v[182:185], v[198:201], v[116:119]
	v_mfma_f32_16x16x32_bf16 v[116:119], v[186:189], v[202:205], v[116:119]
	v_mfma_f32_16x16x32_bf16 v[100:103], v[182:185], v[206:209], v[100:103]
	v_mfma_f32_16x16x32_bf16 v[100:103], v[186:189], v[210:213], v[100:103]
	v_mfma_f32_16x16x32_bf16 v[84:87], v[182:185], v[214:217], v[84:87]
	v_mfma_f32_16x16x32_bf16 v[84:87], v[186:189], v[218:221], v[84:87]
	v_mfma_f32_16x16x32_bf16 v[68:71], v[182:185], v[222:225], v[68:71]
	v_mfma_f32_16x16x32_bf16 v[68:71], v[186:189], v[226:229], v[68:71]
	v_mfma_f32_16x16x32_bf16 v[112:115], v[190:193], v[198:201], v[112:115]
	v_mfma_f32_16x16x32_bf16 v[112:115], v[194:197], v[202:205], v[112:115]
	v_mfma_f32_16x16x32_bf16 v[96:99], v[190:193], v[206:209], v[96:99]
	v_mfma_f32_16x16x32_bf16 v[96:99], v[194:197], v[210:213], v[96:99]
	v_mfma_f32_16x16x32_bf16 v[80:83], v[190:193], v[214:217], v[80:83]
	v_mfma_f32_16x16x32_bf16 v[80:83], v[194:197], v[218:221], v[80:83]
	v_mfma_f32_16x16x32_bf16 v[64:67], v[190:193], v[222:225], v[64:67]
	v_mfma_f32_16x16x32_bf16 v[64:67], v[194:197], v[226:229], v[64:67]
	s_setprio 0
	s_barrier
	s_add_i32 s54, s43, s25
	v_lshl_add_u64 v[158:159], s[18:19], 0, v[136:137]
	s_mov_b32 m0, s54
	ds_read_b128 v[198:201], v162 offset:16384
	ds_read_b128 v[202:205], v162 offset:17408
	ds_read_b128 v[206:209], v162 offset:18432
	ds_read_b128 v[210:213], v162 offset:19456
	ds_read_b128 v[214:217], v162 offset:20480
	ds_read_b128 v[218:221], v162 offset:21504
	ds_read_b128 v[222:225], v162 offset:22528
	ds_read_b128 v[226:229], v162 offset:23552
	global_load_lds_dwordx4 v[158:159], off
	s_add_i32 m0, s54, 0x2000
	s_add_u32 s54, s18, 0x84000
	v_lshl_add_u64 v[166:167], s[18:19], 0, v[132:133]
	s_addc_u32 s55, s19, 0
	s_add_i32 s56, s44, s25
	global_load_lds_dwordx4 v[166:167], off
	v_lshl_add_u64 v[230:231], s[54:55], 0, v[136:137]
	s_mov_b32 m0, s56
	v_lshl_add_u64 v[232:233], s[20:21], 0, v[134:135]
	global_load_lds_dwordx4 v[230:231], off
	v_lshl_add_u64 v[230:231], s[54:55], 0, v[132:133]
	s_add_i32 m0, s56, 0x2000
	s_nop 0
	global_load_lds_dwordx4 v[230:231], off
	v_lshl_add_u64 v[230:231], s[20:21], 0, v[138:139]
	s_mov_b32 m0, s35
	s_nop 0
	global_load_lds_dwordx4 v[230:231], off
	s_mov_b32 m0, s36
	s_nop 0
	global_load_lds_dwordx4 v[232:233], off
	s_waitcnt vmcnt(8)
	s_waitcnt lgkmcnt(0)
	s_barrier
; #define PG8_STAGE(bufoff, gbase, voff) do { _Pragma("unroll") for (int _i = 0; _i < 2; ++_i) \
;         __builtin_amdgcn_global_load_lds((const unsigned*)((const char*)(gbase) + (voff)[_i]), (LAS unsigned*)(lds + (bufoff) + ldsw + _i * 8192), 16, 0, 0); } while (0)
; #define PG8_LDA(dst, b, h) do { _Pragma("unroll") for (int m = 0; m < 4; ++m) _Pragma("unroll") for (int k = 0; k < 2; ++k) dst[m][k] = *(const LAS bf16x8*)(lds + PG8_SA(b, h) + aoff + m * 2048 + k * 1024); } while (0)
; #define PG8_LDB(dst, b, h) do { _Pragma("unroll") for (int n = 0; n < 2; ++n) _Pragma("unroll") for (int k = 0; k < 2; ++k) dst[n][k] = *(const LAS bf16x8*)(lds + PG8_SB(b, h) + boff + n * 2048 + k * 1024); } while (0)
; #define PG8_MMA(ai, bj, At, Bt) do { __builtin_amdgcn_s_setprio(1); _Pragma("unroll") for (int m = 0; m < 4; ++m) _Pragma("unroll") for (int n = 0; n < 2; ++n) _Pragma("unroll") for (int k = 0; k < 2; ++k) \
;         acc[ai][bj][m][n] = __builtin_amdgcn_mfma_f32_16x16x32_bf16(Bt[n][k], At[m][k], acc[ai][bj][m][n], 0, 0, 0); __builtin_amdgcn_s_setprio(0); } while (0)
; #define PG8_WAIT_V(n) asm volatile("s_waitcnt vmcnt(" #n ")" ::: "memory")
; #define PG8_WAIT_L(n) asm volatile("s_waitcnt lgkmcnt(" #n ")" ::: "memory")
; #define PG8_BAR __builtin_amdgcn_s_barrier()
; #define PG8_SCHED __builtin_amdgcn_sched_barrier(0)
; template <class EpiT>
; __device__ __forceinline__ void gemm_phase(LAS unsigned char* lds, const Gemm g, const StaticOrder& S, const EpiT& E) {
;     ...
;             PG8_WAIT_V(8); PG8_WAIT_L(0); PG8_BAR; PG8_MMA(1, 0, At, B0); PG8_MMA(1, 1, At, B1); PG8_BAR; PG8_SCHED;
;             PG8_LDB(B0, 1, 0); PG8_LDB(B1, 1, 1); PG8_SCHED; PG8_LDA(At, 1, 0); PG8_STAGE(PG8_SA(0, 1), a2 + hstepA, voffA);
;             PG8_WAIT_V(8); PG8_WAIT_L(0); PG8_BAR; PG8_MMA(0, 0, At, B0); PG8_MMA(0, 1, At, B1); PG8_BAR; PG8_SCHED;
	s_setprio 1
	s_waitcnt lgkmcnt(0)
	v_mfma_f32_16x16x32_bf16 v[60:63], v[128:131], v[198:201], v[60:63]
	v_mfma_f32_16x16x32_bf16 v[60:63], v[170:173], v[202:205], v[60:63]
	v_mfma_f32_16x16x32_bf16 v[44:47], v[128:131], v[206:209], v[44:47]
	v_mfma_f32_16x16x32_bf16 v[44:47], v[170:173], v[210:213], v[44:47]
	v_mfma_f32_16x16x32_bf16 v[28:31], v[128:131], v[214:217], v[28:31]
	v_mfma_f32_16x16x32_bf16 v[28:31], v[170:173], v[218:221], v[28:31]
	v_mfma_f32_16x16x32_bf16 v[12:15], v[128:131], v[222:225], v[12:15]
	v_mfma_f32_16x16x32_bf16 v[12:15], v[170:173], v[226:229], v[12:15]
	v_mfma_f32_16x16x32_bf16 v[56:59], v[174:177], v[198:201], v[56:59]
	v_mfma_f32_16x16x32_bf16 v[56:59], v[178:181], v[202:205], v[56:59]
	v_mfma_f32_16x16x32_bf16 v[40:43], v[174:177], v[206:209], v[40:43]
	v_mfma_f32_16x16x32_bf16 v[40:43], v[178:181], v[210:213], v[40:43]
	v_mfma_f32_16x16x32_bf16 v[24:27], v[174:177], v[214:217], v[24:27]
	v_mfma_f32_16x16x32_bf16 v[24:27], v[178:181], v[218:221], v[24:27]
	v_mfma_f32_16x16x32_bf16 v[8:11], v[174:177], v[222:225], v[8:11]
	v_mfma_f32_16x16x32_bf16 v[8:11], v[178:181], v[226:229], v[8:11]
	v_mfma_f32_16x16x32_bf16 v[52:55], v[182:185], v[198:201], v[52:55]
	v_mfma_f32_16x16x32_bf16 v[52:55], v[186:189], v[202:205], v[52:55]
	v_mfma_f32_16x16x32_bf16 v[36:39], v[182:185], v[206:209], v[36:39]
	v_mfma_f32_16x16x32_bf16 v[36:39], v[186:189], v[210:213], v[36:39]
	v_mfma_f32_16x16x32_bf16 v[20:23], v[182:185], v[214:217], v[20:23]
	v_mfma_f32_16x16x32_bf16 v[20:23], v[186:189], v[218:221], v[20:23]
	v_mfma_f32_16x16x32_bf16 v[4:7], v[182:185], v[222:225], v[4:7]
	v_mfma_f32_16x16x32_bf16 v[4:7], v[186:189], v[226:229], v[4:7]
	v_mfma_f32_16x16x32_bf16 v[48:51], v[190:193], v[198:201], v[48:51]
	v_mfma_f32_16x16x32_bf16 v[48:51], v[194:197], v[202:205], v[48:51]
	v_mfma_f32_16x16x32_bf16 v[32:35], v[190:193], v[206:209], v[32:35]
	v_mfma_f32_16x16x32_bf16 v[32:35], v[194:197], v[210:213], v[32:35]
	v_mfma_f32_16x16x32_bf16 v[16:19], v[190:193], v[214:217], v[16:19]
	v_mfma_f32_16x16x32_bf16 v[16:19], v[194:197], v[218:221], v[16:19]
	v_mfma_f32_16x16x32_bf16 v[0:3], v[190:193], v[222:225], v[0:3]
	v_mfma_f32_16x16x32_bf16 v[0:3], v[194:197], v[226:229], v[0:3]
	s_setprio 0
	s_barrier
	s_add_i32 s54, 0, 0x18000
	v_add_u32_e32 v140, s54, v145
	s_add_i32 s55, 0, 0x1c000
	ds_read_b128 v[128:131], v140
	ds_read_b128 v[170:173], v140 offset:1024
	ds_read_b128 v[174:177], v140 offset:2048
	ds_read_b128 v[178:181], v140 offset:3072
	v_add_u32_e32 v140, s55, v145
	ds_read_b128 v[182:185], v140
	ds_read_b128 v[186:189], v140 offset:1024
	ds_read_b128 v[190:193], v140 offset:2048
	ds_read_b128 v[194:197], v140 offset:3072
	s_add_u32 s20, s20, 0x84000
	s_addc_u32 s21, s21, 0
	s_mov_b32 m0, s37
	v_lshl_add_u64 v[234:235], s[20:21], 0, v[138:139]
	ds_read_b128 v[198:201], v162 offset:32768
	ds_read_b128 v[202:205], v162 offset:33792
	ds_read_b128 v[206:209], v162 offset:34816
	ds_read_b128 v[210:213], v162 offset:35840
	ds_read_b128 v[214:217], v162 offset:36864
	ds_read_b128 v[218:221], v162 offset:37888
	ds_read_b128 v[222:225], v162 offset:38912
	ds_read_b128 v[226:229], v162 offset:39936
	global_load_lds_dwordx4 v[234:235], off
	v_lshl_add_u64 v[234:235], s[20:21], 0, v[134:135]
	s_mov_b32 m0, s38
	s_nop 0
	global_load_lds_dwordx4 v[234:235], off
	s_waitcnt vmcnt(8)
	s_waitcnt lgkmcnt(0)
	s_barrier
	s_setprio 1
	s_waitcnt lgkmcnt(0)
	v_mfma_f32_16x16x32_bf16 v[124:127], v[128:131], v[198:201], v[124:127]
	v_mfma_f32_16x16x32_bf16 v[124:127], v[170:173], v[202:205], v[124:127]
	v_mfma_f32_16x16x32_bf16 v[108:111], v[128:131], v[206:209], v[108:111]
	v_mfma_f32_16x16x32_bf16 v[108:111], v[170:173], v[210:213], v[108:111]
	v_mfma_f32_16x16x32_bf16 v[92:95], v[128:131], v[214:217], v[92:95]
	v_mfma_f32_16x16x32_bf16 v[92:95], v[170:173], v[218:221], v[92:95]
	v_mfma_f32_16x16x32_bf16 v[76:79], v[128:131], v[222:225], v[76:79]
	v_mfma_f32_16x16x32_bf16 v[76:79], v[170:173], v[226:229], v[76:79]
	v_mfma_f32_16x16x32_bf16 v[120:123], v[174:177], v[198:201], v[120:123]
	v_mfma_f32_16x16x32_bf16 v[120:123], v[178:181], v[202:205], v[120:123]
	v_mfma_f32_16x16x32_bf16 v[104:107], v[174:177], v[206:209], v[104:107]
	v_mfma_f32_16x16x32_bf16 v[104:107], v[178:181], v[210:213], v[104:107]
	v_mfma_f32_16x16x32_bf16 v[88:91], v[174:177], v[214:217], v[88:91]
	v_mfma_f32_16x16x32_bf16 v[88:91], v[178:181], v[218:221], v[88:91]
	v_mfma_f32_16x16x32_bf16 v[72:75], v[174:177], v[222:225], v[72:75]
	v_mfma_f32_16x16x32_bf16 v[72:75], v[178:181], v[226:229], v[72:75]
	v_mfma_f32_16x16x32_bf16 v[116:119], v[182:185], v[198:201], v[116:119]
	v_mfma_f32_16x16x32_bf16 v[116:119], v[186:189], v[202:205], v[116:119]
	v_mfma_f32_16x16x32_bf16 v[100:103], v[182:185], v[206:209], v[100:103]
	v_mfma_f32_16x16x32_bf16 v[100:103], v[186:189], v[210:213], v[100:103]
	v_mfma_f32_16x16x32_bf16 v[84:87], v[182:185], v[214:217], v[84:87]
	v_mfma_f32_16x16x32_bf16 v[84:87], v[186:189], v[218:221], v[84:87]
	v_mfma_f32_16x16x32_bf16 v[68:71], v[182:185], v[222:225], v[68:71]
	v_mfma_f32_16x16x32_bf16 v[68:71], v[186:189], v[226:229], v[68:71]
	v_mfma_f32_16x16x32_bf16 v[112:115], v[190:193], v[198:201], v[112:115]
	v_mfma_f32_16x16x32_bf16 v[112:115], v[194:197], v[202:205], v[112:115]
	v_mfma_f32_16x16x32_bf16 v[96:99], v[190:193], v[206:209], v[96:99]
	v_mfma_f32_16x16x32_bf16 v[96:99], v[194:197], v[210:213], v[96:99]
	v_mfma_f32_16x16x32_bf16 v[80:83], v[190:193], v[214:217], v[80:83]
	v_mfma_f32_16x16x32_bf16 v[80:83], v[194:197], v[218:221], v[80:83]
	v_mfma_f32_16x16x32_bf16 v[64:67], v[190:193], v[222:225], v[64:67]
	v_mfma_f32_16x16x32_bf16 v[64:67], v[194:197], v[226:229], v[64:67]
	s_setprio 0
	s_barrier
; #define PG8_STAGE(bufoff, gbase, voff) do { _Pragma("unroll") for (int _i = 0; _i < 2; ++_i) \
;         __builtin_amdgcn_global_load_lds((const unsigned*)((const char*)(gbase) + (voff)[_i]), (LAS unsigned*)(lds + (bufoff) + ldsw + _i * 8192), 16, 0, 0); } while (0)
; #define PG8_LDA(dst, b, h) do { _Pragma("unroll") for (int m = 0; m < 4; ++m) _Pragma("unroll") for (int k = 0; k < 2; ++k) dst[m][k] = *(const LAS bf16x8*)(lds + PG8_SA(b, h) + aoff + m * 2048 + k * 1024); } while (0)
; #define PG8_MMA(ai, bj, At, Bt) do { __builtin_amdgcn_s_setprio(1); _Pragma("unroll") for (int m = 0; m < 4; ++m) _Pragma("unroll") for (int n = 0; n < 2; ++n) _Pragma("unroll") for (int k = 0; k < 2; ++k) \
;         acc[ai][bj][m][n] = __builtin_amdgcn_mfma_f32_16x16x32_bf16(Bt[n][k], At[m][k], acc[ai][bj][m][n], 0, 0, 0); __builtin_amdgcn_s_setprio(0); } while (0)
; #define PG8_WAIT_V(n) asm volatile("s_waitcnt vmcnt(" #n ")" ::: "memory")
; #define PG8_WAIT_L(n) asm volatile("s_waitcnt lgkmcnt(" #n ")" ::: "memory")
; #define PG8_BAR __builtin_amdgcn_s_barrier()
; #define PG8_SCHED __builtin_amdgcn_sched_barrier(0)
; template <class EpiT>
; __device__ __forceinline__ void gemm_phase(LAS unsigned char* lds, const Gemm g, const StaticOrder& S, const EpiT& E) {
;     ...
;             PG8_LDA(At, 1, 1); PG8_STAGE(PG8_SB(1, 0), b3, voffB); PG8_STAGE(PG8_SB(1, 1), b3 + hstepB, voffB); PG8_STAGE(PG8_SA(1, 0), a3, voffA);
;             PG8_WAIT_V(8); PG8_WAIT_L(0); PG8_BAR; PG8_MMA(1, 0, At, B0); PG8_MMA(1, 1, At, B1); PG8_BAR; PG8_SCHED;
;         }
;         if (wr == 0) PG8_BAR;
	s_add_i32 s20, s54, s25
	v_lshl_add_u64 v[158:159], v[158:159], 0, s[10:11]
	s_mov_b32 m0, s20
	ds_read_b128 v[198:201], v162 offset:49152
	ds_read_b128 v[202:205], v162 offset:50176
	ds_read_b128 v[206:209], v162 offset:51200
	ds_read_b128 v[210:213], v162 offset:52224
	ds_read_b128 v[214:217], v162 offset:53248
	ds_read_b128 v[218:221], v162 offset:54272
	ds_read_b128 v[222:225], v162 offset:55296
	ds_read_b128 v[226:229], v162 offset:56320
	global_load_lds_dwordx4 v[158:159], off
	s_add_i32 m0, s20, 0x2000
	s_add_u32 s18, s18, 0x84080
	v_lshl_add_u64 v[158:159], v[166:167], 0, s[10:11]
	s_addc_u32 s19, s19, 0
	s_add_i32 s20, s55, s25
	global_load_lds_dwordx4 v[158:159], off
	v_lshl_add_u64 v[158:159], s[18:19], 0, v[136:137]
	s_mov_b32 m0, s20
	s_nop 0
	global_load_lds_dwordx4 v[158:159], off
	v_lshl_add_u64 v[158:159], s[18:19], 0, v[132:133]
	s_add_i32 m0, s20, 0x2000
	s_nop 0
	global_load_lds_dwordx4 v[158:159], off
	v_lshl_add_u64 v[158:159], v[230:231], 0, s[10:11]
	s_mov_b32 m0, s40
	s_nop 0
	global_load_lds_dwordx4 v[158:159], off
	v_lshl_add_u64 v[158:159], v[232:233], 0, s[10:11]
	s_mov_b32 m0, s41
	s_nop 0
	global_load_lds_dwordx4 v[158:159], off
	s_waitcnt vmcnt(8)
	s_waitcnt lgkmcnt(0)
	s_barrier
	s_setprio 1
	s_waitcnt lgkmcnt(0)
	v_mfma_f32_16x16x32_bf16 v[60:63], v[128:131], v[198:201], v[60:63]
	v_mfma_f32_16x16x32_bf16 v[60:63], v[170:173], v[202:205], v[60:63]
	v_mfma_f32_16x16x32_bf16 v[44:47], v[128:131], v[206:209], v[44:47]
	v_mfma_f32_16x16x32_bf16 v[44:47], v[170:173], v[210:213], v[44:47]
	v_mfma_f32_16x16x32_bf16 v[28:31], v[128:131], v[214:217], v[28:31]
	v_mfma_f32_16x16x32_bf16 v[28:31], v[170:173], v[218:221], v[28:31]
	v_mfma_f32_16x16x32_bf16 v[12:15], v[128:131], v[222:225], v[12:15]
	v_mfma_f32_16x16x32_bf16 v[12:15], v[170:173], v[226:229], v[12:15]
	v_mfma_f32_16x16x32_bf16 v[56:59], v[174:177], v[198:201], v[56:59]
	v_mfma_f32_16x16x32_bf16 v[56:59], v[178:181], v[202:205], v[56:59]
	v_mfma_f32_16x16x32_bf16 v[40:43], v[174:177], v[206:209], v[40:43]
	v_mfma_f32_16x16x32_bf16 v[40:43], v[178:181], v[210:213], v[40:43]
	v_mfma_f32_16x16x32_bf16 v[24:27], v[174:177], v[214:217], v[24:27]
	v_mfma_f32_16x16x32_bf16 v[24:27], v[178:181], v[218:221], v[24:27]
	v_mfma_f32_16x16x32_bf16 v[8:11], v[174:177], v[222:225], v[8:11]
	v_mfma_f32_16x16x32_bf16 v[8:11], v[178:181], v[226:229], v[8:11]
	v_mfma_f32_16x16x32_bf16 v[52:55], v[182:185], v[198:201], v[52:55]
	v_mfma_f32_16x16x32_bf16 v[52:55], v[186:189], v[202:205], v[52:55]
	v_mfma_f32_16x16x32_bf16 v[36:39], v[182:185], v[206:209], v[36:39]
	v_mfma_f32_16x16x32_bf16 v[36:39], v[186:189], v[210:213], v[36:39]
	v_mfma_f32_16x16x32_bf16 v[20:23], v[182:185], v[214:217], v[20:23]
	v_mfma_f32_16x16x32_bf16 v[20:23], v[186:189], v[218:221], v[20:23]
	v_mfma_f32_16x16x32_bf16 v[4:7], v[182:185], v[222:225], v[4:7]
	v_mfma_f32_16x16x32_bf16 v[4:7], v[186:189], v[226:229], v[4:7]
	v_mfma_f32_16x16x32_bf16 v[48:51], v[190:193], v[198:201], v[48:51]
	v_mfma_f32_16x16x32_bf16 v[48:51], v[194:197], v[202:205], v[48:51]
	v_mfma_f32_16x16x32_bf16 v[32:35], v[190:193], v[206:209], v[32:35]
	v_mfma_f32_16x16x32_bf16 v[32:35], v[194:197], v[210:213], v[32:35]
	v_mfma_f32_16x16x32_bf16 v[16:19], v[190:193], v[214:217], v[16:19]
	v_mfma_f32_16x16x32_bf16 v[16:19], v[194:197], v[218:221], v[16:19]
	v_mfma_f32_16x16x32_bf16 v[0:3], v[190:193], v[222:225], v[0:3]
	v_mfma_f32_16x16x32_bf16 v[0:3], v[194:197], v[226:229], v[0:3]
	s_setprio 0
	s_barrier
	s_add_i32 s53, s53, 2
	s_add_u32 s16, s16, 0x100
	s_addc_u32 s17, s17, 0
	s_add_u32 s51, s51, 0x100
	s_addc_u32 s52, s52, 0
	s_cmp_gt_u32 s53, 29
	s_cbranch_scc0 .LBB0_100
	s_and_b64 vcc, exec, s[12:13]
	s_cbranch_vccz .LBB0_103
	s_barrier

; #define PG8_STAGE(bufoff, gbase, voff) do { _Pragma("unroll") for (int _i = 0; _i < 2; ++_i) \
;         __builtin_amdgcn_global_load_lds((const unsigned*)((const char*)(gbase) + (voff)[_i]), (LAS unsigned*)(lds + (bufoff) + ldsw + _i * 8192), 16, 0, 0); } while (0)
; #define PG8_LDA(dst, b, h) do { _Pragma("unroll") for (int m = 0; m < 4; ++m) _Pragma("unroll") for (int k = 0; k < 2; ++k) dst[m][k] = *(const LAS bf16x8*)(lds + PG8_SA(b, h) + aoff + m * 2048 + k * 1024); } while (0)
; #define PG8_LDB(dst, b, h) do { _Pragma("unroll") for (int n = 0; n < 2; ++n) _Pragma("unroll") for (int k = 0; k < 2; ++k) dst[n][k] = *(const LAS bf16x8*)(lds + PG8_SB(b, h) + boff + n * 2048 + k * 1024); } while (0)
; #define PG8_MMA(ai, bj, At, Bt) do { __builtin_amdgcn_s_setprio(1); _Pragma("unroll") for (int m = 0; m < 4; ++m) _Pragma("unroll") for (int n = 0; n < 2; ++n) _Pragma("unroll") for (int k = 0; k < 2; ++k) \
;         acc[ai][bj][m][n] = __builtin_amdgcn_mfma_f32_16x16x32_bf16(Bt[n][k], At[m][k], acc[ai][bj][m][n], 0, 0, 0); __builtin_amdgcn_s_setprio(0); } while (0)
; #define PG8_WAIT_V(n) asm volatile("s_waitcnt vmcnt(" #n ")" ::: "memory")
; #define PG8_WAIT_L(n) asm volatile("s_waitcnt lgkmcnt(" #n ")" ::: "memory")
; template <class EpiT>
; __device__ __forceinline__ void gemm_phase(LAS unsigned char* lds, const Gemm g, const StaticOrder& S, const EpiT& E) {
;     ...
;         const bool has_next = S.next(ui + 1, nxt);
;         const char* nA = has_next ? (const char*)g.A + (size_t)nxt.pm * tstepA + (size_t)nxt.pn * g.a_koff * 2 : cA; const char* nB = has_next ? (const char*)g.Bt + (size_t)nxt.pn * tstepB : cB;
;         for (int t = 0; t < nt; t += 2) {
;             const bool last = (t == nt - 2);
;             const char* a1 = cA + (size_t)(t + 1) * kstep;
;             const char* a2 = last ? nA : cA + (size_t)(t + 2) * kstep; const char* b2 = last ? nB : cB + (size_t)(t + 2) * kstep;
;             const char* a3 = a2 + kstep; const char* b3 = b2 + kstep;
;             PG8_LDB(B0, 0, 0); PG8_LDB(B1, 0, 1); PG8_SCHED; PG8_LDA(At, 0, 0); PG8_STAGE(PG8_SA(1, 1), a1 + hstepA, voffA);
;             PG8_WAIT_V(8); PG8_WAIT_L(0); PG8_BAR; PG8_MMA(0, 0, At, B0); PG8_MMA(0, 1, At, B1); PG8_BAR; PG8_SCHED;
;             PG8_LDA(At, 0, 1); PG8_STAGE(PG8_SB(0, 0), b2, voffB); PG8_STAGE(PG8_SB(0, 1), b2 + hstepB, voffB); PG8_STAGE(PG8_SA(0, 0), a2, voffA);
.LBB0_296:
	s_add_u32 s58, s66, s54
	s_addc_u32 s59, s67, 0
	s_add_u32 s55, s58, 0x100
	s_addc_u32 s61, s59, 0
	s_and_b64 s[56:57], s[68:69], exec
	s_cselect_b32 s73, s21, s61
	s_cselect_b32 s72, s20, s55
	s_add_u32 s54, s46, s54
	s_addc_u32 s55, s47, 0
	s_add_u32 s56, s54, 0x100
	s_addc_u32 s57, s55, 0
	s_and_b64 s[54:55], s[68:69], exec
	s_cselect_b32 s75, s17, s57
	s_cselect_b32 s74, s19, s56
	s_add_u32 s78, s58, 0x40080
	s_addc_u32 s79, s59, 0
	s_add_i32 s80, s51, s36
	ds_read_b128 v[128:131], v167
	ds_read_b128 v[132:135], v167 offset:1024
	ds_read_b128 v[136:139], v167 offset:2048
	ds_read_b128 v[140:143], v167 offset:3072
	ds_read_b128 v[160:163], v169
	ds_read_b128 v[172:175], v169 offset:1024
	ds_read_b128 v[176:179], v169 offset:2048
	ds_read_b128 v[180:183], v169 offset:3072
	s_add_i32 m0, s37, 0xc000
	s_add_i32 s84, s37, 0xe000
	s_add_i32 s61, s80, 0x2000
	s_add_u32 s76, s74, 0x10000
	s_addc_u32 s77, s75, 0
	s_add_i32 s65, s52, s36
	s_add_i32 s64, s65, 0x2000
	s_add_i32 s59, 0, 0x18000
	s_add_i32 s58, 0, 0x1c000
	s_add_u32 s70, s72, 0x40000
	s_addc_u32 s71, s73, 0
	s_add_i32 s57, s59, s36
	s_add_i32 s55, s57, 0x2000
	s_add_u32 s68, s74, 0x10080
	s_addc_u32 s69, s75, 0
	s_add_i32 s56, s58, s36
	s_add_i32 s54, s56, 0x2000
	v_lshl_add_u64 v[216:217], s[78:79], 0, v[146:147]
	ds_read_b128 v[184:187], v170
	ds_read_b128 v[188:191], v170 offset:1024
	ds_read_b128 v[192:195], v170 offset:2048
	ds_read_b128 v[196:199], v170 offset:3072
	ds_read_b128 v[200:203], v170 offset:4096
	ds_read_b128 v[204:207], v170 offset:5120
	ds_read_b128 v[208:211], v170 offset:6144
	ds_read_b128 v[212:215], v170 offset:7168
	global_load_lds_dwordx4 v[216:217], off
	v_lshl_add_u64 v[216:217], s[78:79], 0, v[150:151]
	s_mov_b32 m0, s84
	s_nop 0
	global_load_lds_dwordx4 v[216:217], off
	s_waitcnt vmcnt(8)
	s_waitcnt lgkmcnt(0)
	s_barrier
	s_setprio 1
	s_waitcnt lgkmcnt(0)
	v_mfma_f32_16x16x32_bf16 v[124:127], v[128:131], v[184:187], v[124:127]
	v_mfma_f32_16x16x32_bf16 v[120:123], v[136:139], v[184:187], v[120:123]
	v_mfma_f32_16x16x32_bf16 v[108:111], v[128:131], v[192:195], v[108:111]
	v_mfma_f32_16x16x32_bf16 v[104:107], v[136:139], v[192:195], v[104:107]
	v_mfma_f32_16x16x32_bf16 v[92:95], v[128:131], v[200:203], v[92:95]
	v_mfma_f32_16x16x32_bf16 v[88:91], v[136:139], v[200:203], v[88:91]
	v_mfma_f32_16x16x32_bf16 v[76:79], v[128:131], v[208:211], v[76:79]
	v_mfma_f32_16x16x32_bf16 v[72:75], v[136:139], v[208:211], v[72:75]
	v_mfma_f32_16x16x32_bf16 v[124:127], v[132:135], v[188:191], v[124:127]
	v_mfma_f32_16x16x32_bf16 v[120:123], v[140:143], v[188:191], v[120:123]
	v_mfma_f32_16x16x32_bf16 v[108:111], v[132:135], v[196:199], v[108:111]
	v_mfma_f32_16x16x32_bf16 v[104:107], v[140:143], v[196:199], v[104:107]
	v_mfma_f32_16x16x32_bf16 v[92:95], v[132:135], v[204:207], v[92:95]
	v_mfma_f32_16x16x32_bf16 v[88:91], v[140:143], v[204:207], v[88:91]
	v_mfma_f32_16x16x32_bf16 v[76:79], v[132:135], v[212:215], v[76:79]
	v_mfma_f32_16x16x32_bf16 v[72:75], v[140:143], v[212:215], v[72:75]
	v_mfma_f32_16x16x32_bf16 v[116:119], v[160:163], v[184:187], v[116:119]
	v_mfma_f32_16x16x32_bf16 v[112:115], v[176:179], v[184:187], v[112:115]
	v_mfma_f32_16x16x32_bf16 v[100:103], v[160:163], v[192:195], v[100:103]
	v_mfma_f32_16x16x32_bf16 v[96:99], v[176:179], v[192:195], v[96:99]
	v_mfma_f32_16x16x32_bf16 v[84:87], v[160:163], v[200:203], v[84:87]
	v_mfma_f32_16x16x32_bf16 v[80:83], v[176:179], v[200:203], v[80:83]
	v_mfma_f32_16x16x32_bf16 v[68:71], v[160:163], v[208:211], v[68:71]
	v_mfma_f32_16x16x32_bf16 v[64:67], v[176:179], v[208:211], v[64:67]
	v_mfma_f32_16x16x32_bf16 v[116:119], v[172:175], v[188:191], v[116:119]
	v_mfma_f32_16x16x32_bf16 v[112:115], v[180:183], v[188:191], v[112:115]
	v_mfma_f32_16x16x32_bf16 v[100:103], v[172:175], v[196:199], v[100:103]
	v_mfma_f32_16x16x32_bf16 v[96:99], v[180:183], v[196:199], v[96:99]
	v_mfma_f32_16x16x32_bf16 v[84:87], v[172:175], v[204:207], v[84:87]
	v_mfma_f32_16x16x32_bf16 v[80:83], v[180:183], v[204:207], v[80:83]
	v_mfma_f32_16x16x32_bf16 v[68:71], v[172:175], v[212:215], v[68:71]
	v_mfma_f32_16x16x32_bf16 v[64:67], v[180:183], v[212:215], v[64:67]
	s_setprio 0
	s_barrier
	s_mov_b32 m0, s80
	v_lshl_add_u64 v[216:217], s[74:75], 0, v[148:149]
	ds_read_b128 v[184:187], v170 offset:16384
	ds_read_b128 v[188:191], v170 offset:17408
	ds_read_b128 v[192:195], v170 offset:18432
	ds_read_b128 v[196:199], v170 offset:19456
	ds_read_b128 v[200:203], v170 offset:20480
	ds_read_b128 v[204:207], v170 offset:21504
	ds_read_b128 v[208:211], v170 offset:22528
	ds_read_b128 v[212:215], v170 offset:23552
	global_load_lds_dwordx4 v[216:217], off
	v_lshl_add_u64 v[218:219], s[74:75], 0, v[152:153]
	s_mov_b32 m0, s61
	v_lshl_add_u64 v[220:221], s[76:77], 0, v[148:149]
	global_load_lds_dwordx4 v[218:219], off
	s_mov_b32 m0, s65
	v_lshl_add_u64 v[222:223], s[72:73], 0, v[150:151]
	global_load_lds_dwordx4 v[220:221], off
	v_lshl_add_u64 v[220:221], s[76:77], 0, v[152:153]
	s_mov_b32 m0, s64
	s_nop 0
	global_load_lds_dwordx4 v[220:221], off
	v_lshl_add_u64 v[220:221], s[72:73], 0, v[146:147]
	s_mov_b32 m0, s37
	s_nop 0
	global_load_lds_dwordx4 v[220:221], off
	s_mov_b32 m0, s38
	s_nop 0
	global_load_lds_dwordx4 v[222:223], off
	s_waitcnt vmcnt(8)
	s_waitcnt lgkmcnt(0)
	s_barrier
; #define PG8_STAGE(bufoff, gbase, voff) do { _Pragma("unroll") for (int _i = 0; _i < 2; ++_i) \
;         __builtin_amdgcn_global_load_lds((const unsigned*)((const char*)(gbase) + (voff)[_i]), (LAS unsigned*)(lds + (bufoff) + ldsw + _i * 8192), 16, 0, 0); } while (0)
; #define PG8_LDA(dst, b, h) do { _Pragma("unroll") for (int m = 0; m < 4; ++m) _Pragma("unroll") for (int k = 0; k < 2; ++k) dst[m][k] = *(const LAS bf16x8*)(lds + PG8_SA(b, h) + aoff + m * 2048 + k * 1024); } while (0)
; #define PG8_LDB(dst, b, h) do { _Pragma("unroll") for (int n = 0; n < 2; ++n) _Pragma("unroll") for (int k = 0; k < 2; ++k) dst[n][k] = *(const LAS bf16x8*)(lds + PG8_SB(b, h) + boff + n * 2048 + k * 1024); } while (0)
; #define PG8_MMA(ai, bj, At, Bt) do { __builtin_amdgcn_s_setprio(1); _Pragma("unroll") for (int m = 0; m < 4; ++m) _Pragma("unroll") for (int n = 0; n < 2; ++n) _Pragma("unroll") for (int k = 0; k < 2; ++k) \
;         acc[ai][bj][m][n] = __builtin_amdgcn_mfma_f32_16x16x32_bf16(Bt[n][k], At[m][k], acc[ai][bj][m][n], 0, 0, 0); __builtin_amdgcn_s_setprio(0); } while (0)
; #define PG8_WAIT_V(n) asm volatile("s_waitcnt vmcnt(" #n ")" ::: "memory")
; #define PG8_WAIT_L(n) asm volatile("s_waitcnt lgkmcnt(" #n ")" ::: "memory")
; #define PG8_BAR __builtin_amdgcn_s_barrier()
; #define PG8_SCHED __builtin_amdgcn_sched_barrier(0)
; template <class EpiT>
; __device__ __forceinline__ void gemm_phase(LAS unsigned char* lds, const Gemm g, const StaticOrder& S, const EpiT& E) {
;     ...
;             PG8_WAIT_V(8); PG8_WAIT_L(0); PG8_BAR; PG8_MMA(1, 0, At, B0); PG8_MMA(1, 1, At, B1); PG8_BAR; PG8_SCHED;
;             PG8_LDB(B0, 1, 0); PG8_LDB(B1, 1, 1); PG8_SCHED; PG8_LDA(At, 1, 0); PG8_STAGE(PG8_SA(0, 1), a2 + hstepA, voffA);
;             PG8_WAIT_V(8); PG8_WAIT_L(0); PG8_BAR; PG8_MMA(0, 0, At, B0); PG8_MMA(0, 1, At, B1); PG8_BAR; PG8_SCHED;
	s_setprio 1
	s_waitcnt lgkmcnt(0)
	v_mfma_f32_16x16x32_bf16 v[60:63], v[128:131], v[184:187], v[60:63]
	v_mfma_f32_16x16x32_bf16 v[56:59], v[136:139], v[184:187], v[56:59]
	v_mfma_f32_16x16x32_bf16 v[44:47], v[128:131], v[192:195], v[44:47]
	v_mfma_f32_16x16x32_bf16 v[40:43], v[136:139], v[192:195], v[40:43]
	v_mfma_f32_16x16x32_bf16 v[28:31], v[128:131], v[200:203], v[28:31]
	v_mfma_f32_16x16x32_bf16 v[24:27], v[136:139], v[200:203], v[24:27]
	v_mfma_f32_16x16x32_bf16 v[12:15], v[128:131], v[208:211], v[12:15]
	v_mfma_f32_16x16x32_bf16 v[8:11], v[136:139], v[208:211], v[8:11]
	v_mfma_f32_16x16x32_bf16 v[60:63], v[132:135], v[188:191], v[60:63]
	v_mfma_f32_16x16x32_bf16 v[56:59], v[140:143], v[188:191], v[56:59]
	v_mfma_f32_16x16x32_bf16 v[44:47], v[132:135], v[196:199], v[44:47]
	v_mfma_f32_16x16x32_bf16 v[40:43], v[140:143], v[196:199], v[40:43]
	v_mfma_f32_16x16x32_bf16 v[28:31], v[132:135], v[204:207], v[28:31]
	v_mfma_f32_16x16x32_bf16 v[24:27], v[140:143], v[204:207], v[24:27]
	v_mfma_f32_16x16x32_bf16 v[12:15], v[132:135], v[212:215], v[12:15]
	v_mfma_f32_16x16x32_bf16 v[8:11], v[140:143], v[212:215], v[8:11]
	v_mfma_f32_16x16x32_bf16 v[52:55], v[160:163], v[184:187], v[52:55]
	v_mfma_f32_16x16x32_bf16 v[48:51], v[176:179], v[184:187], v[48:51]
	v_mfma_f32_16x16x32_bf16 v[36:39], v[160:163], v[192:195], v[36:39]
	v_mfma_f32_16x16x32_bf16 v[32:35], v[176:179], v[192:195], v[32:35]
	v_mfma_f32_16x16x32_bf16 v[20:23], v[160:163], v[200:203], v[20:23]
	v_mfma_f32_16x16x32_bf16 v[16:19], v[176:179], v[200:203], v[16:19]
	v_mfma_f32_16x16x32_bf16 v[4:7], v[160:163], v[208:211], v[4:7]
	v_mfma_f32_16x16x32_bf16 v[0:3], v[176:179], v[208:211], v[0:3]
	v_mfma_f32_16x16x32_bf16 v[52:55], v[172:175], v[188:191], v[52:55]
	v_mfma_f32_16x16x32_bf16 v[48:51], v[180:183], v[188:191], v[48:51]
	v_mfma_f32_16x16x32_bf16 v[36:39], v[172:175], v[196:199], v[36:39]
	v_mfma_f32_16x16x32_bf16 v[32:35], v[180:183], v[196:199], v[32:35]
	v_mfma_f32_16x16x32_bf16 v[20:23], v[172:175], v[204:207], v[20:23]
	v_mfma_f32_16x16x32_bf16 v[16:19], v[180:183], v[204:207], v[16:19]
	v_mfma_f32_16x16x32_bf16 v[4:7], v[172:175], v[212:215], v[4:7]
	v_mfma_f32_16x16x32_bf16 v[0:3], v[180:183], v[212:215], v[0:3]
	s_setprio 0
	s_barrier
	v_add_u32_e32 v140, s59, v145
	v_add_u32_e32 v180, s58, v145
	ds_read_b128 v[128:131], v140
	ds_read_b128 v[132:135], v140 offset:1024
	ds_read_b128 v[136:139], v140 offset:2048
	ds_read_b128 v[140:143], v140 offset:3072
	ds_read_b128 v[160:163], v180
	ds_read_b128 v[172:175], v180 offset:1024
	ds_read_b128 v[176:179], v180 offset:2048
	ds_read_b128 v[180:183], v180 offset:3072
	s_mov_b32 m0, s39
	v_lshl_add_u64 v[224:225], s[70:71], 0, v[146:147]
	ds_read_b128 v[184:187], v170 offset:32768
	ds_read_b128 v[188:191], v170 offset:33792
	ds_read_b128 v[192:195], v170 offset:34816
	ds_read_b128 v[196:199], v170 offset:35840
	ds_read_b128 v[200:203], v170 offset:36864
	ds_read_b128 v[204:207], v170 offset:37888
	ds_read_b128 v[208:211], v170 offset:38912
	ds_read_b128 v[212:215], v170 offset:39936
	global_load_lds_dwordx4 v[224:225], off
	v_lshl_add_u64 v[224:225], s[70:71], 0, v[150:151]
	s_mov_b32 m0, s41
	s_nop 0
	global_load_lds_dwordx4 v[224:225], off
	s_waitcnt vmcnt(8)
	s_waitcnt lgkmcnt(0)
	s_barrier
	s_setprio 1
	s_waitcnt lgkmcnt(0)
	v_mfma_f32_16x16x32_bf16 v[124:127], v[128:131], v[184:187], v[124:127]
	v_mfma_f32_16x16x32_bf16 v[120:123], v[136:139], v[184:187], v[120:123]
	v_mfma_f32_16x16x32_bf16 v[108:111], v[128:131], v[192:195], v[108:111]
	v_mfma_f32_16x16x32_bf16 v[104:107], v[136:139], v[192:195], v[104:107]
	v_mfma_f32_16x16x32_bf16 v[92:95], v[128:131], v[200:203], v[92:95]
	v_mfma_f32_16x16x32_bf16 v[88:91], v[136:139], v[200:203], v[88:91]
	v_mfma_f32_16x16x32_bf16 v[76:79], v[128:131], v[208:211], v[76:79]
	v_mfma_f32_16x16x32_bf16 v[72:75], v[136:139], v[208:211], v[72:75]
	v_mfma_f32_16x16x32_bf16 v[124:127], v[132:135], v[188:191], v[124:127]
	v_mfma_f32_16x16x32_bf16 v[120:123], v[140:143], v[188:191], v[120:123]
	v_mfma_f32_16x16x32_bf16 v[108:111], v[132:135], v[196:199], v[108:111]
	v_mfma_f32_16x16x32_bf16 v[104:107], v[140:143], v[196:199], v[104:107]
	v_mfma_f32_16x16x32_bf16 v[92:95], v[132:135], v[204:207], v[92:95]
	v_mfma_f32_16x16x32_bf16 v[88:91], v[140:143], v[204:207], v[88:91]
	v_mfma_f32_16x16x32_bf16 v[76:79], v[132:135], v[212:215], v[76:79]
	v_mfma_f32_16x16x32_bf16 v[72:75], v[140:143], v[212:215], v[72:75]
	v_mfma_f32_16x16x32_bf16 v[116:119], v[160:163], v[184:187], v[116:119]
	v_mfma_f32_16x16x32_bf16 v[112:115], v[176:179], v[184:187], v[112:115]
	v_mfma_f32_16x16x32_bf16 v[100:103], v[160:163], v[192:195], v[100:103]
	v_mfma_f32_16x16x32_bf16 v[96:99], v[176:179], v[192:195], v[96:99]
	v_mfma_f32_16x16x32_bf16 v[84:87], v[160:163], v[200:203], v[84:87]
	v_mfma_f32_16x16x32_bf16 v[80:83], v[176:179], v[200:203], v[80:83]
	v_mfma_f32_16x16x32_bf16 v[68:71], v[160:163], v[208:211], v[68:71]
	v_mfma_f32_16x16x32_bf16 v[64:67], v[176:179], v[208:211], v[64:67]
	v_mfma_f32_16x16x32_bf16 v[116:119], v[172:175], v[188:191], v[116:119]
	v_mfma_f32_16x16x32_bf16 v[112:115], v[180:183], v[188:191], v[112:115]
	v_mfma_f32_16x16x32_bf16 v[100:103], v[172:175], v[196:199], v[100:103]
	v_mfma_f32_16x16x32_bf16 v[96:99], v[180:183], v[196:199], v[96:99]
	v_mfma_f32_16x16x32_bf16 v[84:87], v[172:175], v[204:207], v[84:87]
	v_mfma_f32_16x16x32_bf16 v[80:83], v[180:183], v[204:207], v[80:83]
	v_mfma_f32_16x16x32_bf16 v[68:71], v[172:175], v[212:215], v[68:71]
	v_mfma_f32_16x16x32_bf16 v[64:67], v[180:183], v[212:215], v[64:67]
	s_setprio 0
	s_barrier
; #define PG8_STAGE(bufoff, gbase, voff) do { _Pragma("unroll") for (int _i = 0; _i < 2; ++_i) \
;         __builtin_amdgcn_global_load_lds((const unsigned*)((const char*)(gbase) + (voff)[_i]), (LAS unsigned*)(lds + (bufoff) + ldsw + _i * 8192), 16, 0, 0); } while (0)
; #define PG8_LDA(dst, b, h) do { _Pragma("unroll") for (int m = 0; m < 4; ++m) _Pragma("unroll") for (int k = 0; k < 2; ++k) dst[m][k] = *(const LAS bf16x8*)(lds + PG8_SA(b, h) + aoff + m * 2048 + k * 1024); } while (0)
; #define PG8_MMA(ai, bj, At, Bt) do { __builtin_amdgcn_s_setprio(1); _Pragma("unroll") for (int m = 0; m < 4; ++m) _Pragma("unroll") for (int n = 0; n < 2; ++n) _Pragma("unroll") for (int k = 0; k < 2; ++k) \
;         acc[ai][bj][m][n] = __builtin_amdgcn_mfma_f32_16x16x32_bf16(Bt[n][k], At[m][k], acc[ai][bj][m][n], 0, 0, 0); __builtin_amdgcn_s_setprio(0); } while (0)
; #define PG8_WAIT_V(n) asm volatile("s_waitcnt vmcnt(" #n ")" ::: "memory")
; #define PG8_WAIT_L(n) asm volatile("s_waitcnt lgkmcnt(" #n ")" ::: "memory")
; #define PG8_BAR __builtin_amdgcn_s_barrier()
; #define PG8_SCHED __builtin_amdgcn_sched_barrier(0)
; template <class EpiT>
; __device__ __forceinline__ void gemm_phase(LAS unsigned char* lds, const Gemm g, const StaticOrder& S, const EpiT& E) {
;     ...
;             PG8_LDA(At, 1, 1); PG8_STAGE(PG8_SB(1, 0), b3, voffB); PG8_STAGE(PG8_SB(1, 1), b3 + hstepB, voffB); PG8_STAGE(PG8_SA(1, 0), a3, voffA);
;             PG8_WAIT_V(8); PG8_WAIT_L(0); PG8_BAR; PG8_MMA(1, 0, At, B0); PG8_MMA(1, 1, At, B1); PG8_BAR; PG8_SCHED;
;         }
;         if (wr == 0) PG8_BAR;
	s_mov_b32 m0, s57
	v_lshl_add_u64 v[216:217], v[216:217], 0, s[10:11]
	ds_read_b128 v[184:187], v170 offset:49152
	ds_read_b128 v[188:191], v170 offset:50176
	ds_read_b128 v[192:195], v170 offset:51200
	ds_read_b128 v[196:199], v170 offset:52224
	ds_read_b128 v[200:203], v170 offset:53248
	ds_read_b128 v[204:207], v170 offset:54272
	ds_read_b128 v[208:211], v170 offset:55296
	ds_read_b128 v[212:215], v170 offset:56320
	global_load_lds_dwordx4 v[216:217], off
	v_lshl_add_u64 v[216:217], v[218:219], 0, s[10:11]
	s_mov_b32 m0, s55
	s_nop 0
	global_load_lds_dwordx4 v[216:217], off
	v_lshl_add_u64 v[216:217], s[68:69], 0, v[148:149]
	s_mov_b32 m0, s56
	s_nop 0
	global_load_lds_dwordx4 v[216:217], off
	v_lshl_add_u64 v[216:217], s[68:69], 0, v[152:153]
	s_mov_b32 m0, s54
	s_nop 0
	global_load_lds_dwordx4 v[216:217], off
	v_lshl_add_u64 v[216:217], v[220:221], 0, s[10:11]
	s_mov_b32 m0, s44
	s_nop 0
	global_load_lds_dwordx4 v[216:217], off
	v_lshl_add_u64 v[216:217], v[222:223], 0, s[10:11]
	s_mov_b32 m0, s45
	s_nop 0
	global_load_lds_dwordx4 v[216:217], off
	s_waitcnt vmcnt(8)
	s_waitcnt lgkmcnt(0)
	s_barrier
	s_setprio 1
	s_waitcnt lgkmcnt(0)
	v_mfma_f32_16x16x32_bf16 v[60:63], v[128:131], v[184:187], v[60:63]
	v_mfma_f32_16x16x32_bf16 v[56:59], v[136:139], v[184:187], v[56:59]
	v_mfma_f32_16x16x32_bf16 v[44:47], v[128:131], v[192:195], v[44:47]
	v_mfma_f32_16x16x32_bf16 v[40:43], v[136:139], v[192:195], v[40:43]
	v_mfma_f32_16x16x32_bf16 v[28:31], v[128:131], v[200:203], v[28:31]
	v_mfma_f32_16x16x32_bf16 v[24:27], v[136:139], v[200:203], v[24:27]
	v_mfma_f32_16x16x32_bf16 v[12:15], v[128:131], v[208:211], v[12:15]
	v_mfma_f32_16x16x32_bf16 v[8:11], v[136:139], v[208:211], v[8:11]
	v_mfma_f32_16x16x32_bf16 v[60:63], v[132:135], v[188:191], v[60:63]
	v_mfma_f32_16x16x32_bf16 v[56:59], v[140:143], v[188:191], v[56:59]
	v_mfma_f32_16x16x32_bf16 v[44:47], v[132:135], v[196:199], v[44:47]
	v_mfma_f32_16x16x32_bf16 v[40:43], v[140:143], v[196:199], v[40:43]
	v_mfma_f32_16x16x32_bf16 v[28:31], v[132:135], v[204:207], v[28:31]
	v_mfma_f32_16x16x32_bf16 v[24:27], v[140:143], v[204:207], v[24:27]
	v_mfma_f32_16x16x32_bf16 v[12:15], v[132:135], v[212:215], v[12:15]
	v_mfma_f32_16x16x32_bf16 v[8:11], v[140:143], v[212:215], v[8:11]
	v_mfma_f32_16x16x32_bf16 v[52:55], v[160:163], v[184:187], v[52:55]
	v_mfma_f32_16x16x32_bf16 v[48:51], v[176:179], v[184:187], v[48:51]
	v_mfma_f32_16x16x32_bf16 v[36:39], v[160:163], v[192:195], v[36:39]
	v_mfma_f32_16x16x32_bf16 v[32:35], v[176:179], v[192:195], v[32:35]
	v_mfma_f32_16x16x32_bf16 v[20:23], v[160:163], v[200:203], v[20:23]
	v_mfma_f32_16x16x32_bf16 v[16:19], v[176:179], v[200:203], v[16:19]
	v_mfma_f32_16x16x32_bf16 v[4:7], v[160:163], v[208:211], v[4:7]
	v_mfma_f32_16x16x32_bf16 v[0:3], v[176:179], v[208:211], v[0:3]
	v_mfma_f32_16x16x32_bf16 v[52:55], v[172:175], v[188:191], v[52:55]
	v_mfma_f32_16x16x32_bf16 v[48:51], v[180:183], v[188:191], v[48:51]
	v_mfma_f32_16x16x32_bf16 v[36:39], v[172:175], v[196:199], v[36:39]
	v_mfma_f32_16x16x32_bf16 v[32:35], v[180:183], v[196:199], v[32:35]
	v_mfma_f32_16x16x32_bf16 v[20:23], v[172:175], v[204:207], v[20:23]
	v_mfma_f32_16x16x32_bf16 v[16:19], v[180:183], v[204:207], v[16:19]
	v_mfma_f32_16x16x32_bf16 v[4:7], v[172:175], v[212:215], v[4:7]
	v_mfma_f32_16x16x32_bf16 v[0:3], v[180:183], v[212:215], v[0:3]
	s_setprio 0
	s_barrier
	s_movk_i32 s54, 0x100
	s_andn2_b64 vcc, exec, s[4:5]
	s_mov_b64 s[68:69], -1
	s_mov_b64 s[4:5], 0
	s_cbranch_vccz .LBB0_296
	s_and_b64 vcc, exec, s[12:13]
	s_cbranch_vccz .LBB0_299
	s_barrier

; #define PG8_STAGE(bufoff, gbase, voff) do { _Pragma("unroll") for (int _i = 0; _i < 2; ++_i) \
;         __builtin_amdgcn_global_load_lds((const unsigned*)((const char*)(gbase) + (voff)[_i]), (LAS unsigned*)(lds + (bufoff) + ldsw + _i * 8192), 16, 0, 0); } while (0)
; #define PG8_LDA(dst, b, h) do { _Pragma("unroll") for (int m = 0; m < 4; ++m) _Pragma("unroll") for (int k = 0; k < 2; ++k) dst[m][k] = *(const LAS bf16x8*)(lds + PG8_SA(b, h) + aoff + m * 2048 + k * 1024); } while (0)
; #define PG8_LDB(dst, b, h) do { _Pragma("unroll") for (int n = 0; n < 2; ++n) _Pragma("unroll") for (int k = 0; k < 2; ++k) dst[n][k] = *(const LAS bf16x8*)(lds + PG8_SB(b, h) + boff + n * 2048 + k * 1024); } while (0)
; #define PG8_MMA(ai, bj, At, Bt) do { __builtin_amdgcn_s_setprio(1); _Pragma("unroll") for (int m = 0; m < 4; ++m) _Pragma("unroll") for (int n = 0; n < 2; ++n) _Pragma("unroll") for (int k = 0; k < 2; ++k) \
;         acc[ai][bj][m][n] = __builtin_amdgcn_mfma_f32_16x16x32_bf16(Bt[n][k], At[m][k], acc[ai][bj][m][n], 0, 0, 0); __builtin_amdgcn_s_setprio(0); } while (0)
; #define PG8_WAIT_V(n) asm volatile("s_waitcnt vmcnt(" #n ")" ::: "memory")
; #define PG8_WAIT_L(n) asm volatile("s_waitcnt lgkmcnt(" #n ")" ::: "memory")
; #define PG8_BAR __builtin_amdgcn_s_barrier()
; #define PG8_SCHED __builtin_amdgcn_sched_barrier(0)
; template <class EpiT>
; __device__ __forceinline__ void gemm_phase(LAS unsigned char* lds, const Gemm g, const StaticOrder& S, const EpiT& E) {
;     ...
;             const bool last = (t == nt - 2);
;             const char* a1 = cA + (size_t)(t + 1) * kstep;
;             const char* a2 = last ? nA : cA + (size_t)(t + 2) * kstep; const char* b2 = last ? nB : cB + (size_t)(t + 2) * kstep;
;             const char* a3 = a2 + kstep; const char* b3 = b2 + kstep;
;             PG8_LDB(B0, 0, 0); PG8_LDB(B1, 0, 1); PG8_SCHED; PG8_LDA(At, 0, 0); PG8_STAGE(PG8_SA(1, 1), a1 + hstepA, voffA);
;             PG8_WAIT_V(8); PG8_WAIT_L(0); PG8_BAR; PG8_MMA(0, 0, At, B0); PG8_MMA(0, 1, At, B1); PG8_BAR; PG8_SCHED;
;             PG8_LDA(At, 0, 1); PG8_STAGE(PG8_SB(0, 0), b2, voffB); PG8_STAGE(PG8_SB(0, 1), b2 + hstepB, voffB); PG8_STAGE(PG8_SA(0, 0), a2, voffA);
.LBB0_392:
	ds_read_b128 v[154:157], v149
	ds_read_b128 v[158:161], v149 offset:1024
	ds_read_b128 v[170:173], v149 offset:2048
	ds_read_b128 v[174:177], v149 offset:3072
	ds_read_b128 v[178:181], v150
	ds_read_b128 v[182:185], v150 offset:1024
	ds_read_b128 v[186:189], v150 offset:2048
	ds_read_b128 v[190:193], v150 offset:3072
	s_add_u32 s20, s18, 0xfff7c080
	s_addc_u32 s21, s19, -1
	s_cmp_eq_u32 s53, 28
	s_cselect_b32 s23, s5, s21
	s_cselect_b32 s22, s4, s20
	s_cselect_b32 s21, s17, s52
	s_cselect_b32 s20, s16, s51
	v_lshl_add_u64 v[162:163], s[18:19], 0, v[138:139]
	s_add_i32 m0, s35, 0xc000
	ds_read_b128 v[194:197], v151
	ds_read_b128 v[198:201], v151 offset:1024
	ds_read_b128 v[202:205], v151 offset:2048
	ds_read_b128 v[206:209], v151 offset:3072
	ds_read_b128 v[210:213], v151 offset:4096
	ds_read_b128 v[214:217], v151 offset:5120
	ds_read_b128 v[218:221], v151 offset:6144
	ds_read_b128 v[222:225], v151 offset:7168
	global_load_lds_dwordx4 v[162:163], off
	v_lshl_add_u64 v[162:163], s[18:19], 0, v[140:141]
	s_add_i32 m0, s35, 0xe000
	s_nop 0
	global_load_lds_dwordx4 v[162:163], off
	s_waitcnt vmcnt(8)
	s_waitcnt lgkmcnt(0)
	s_barrier
	s_setprio 1
	s_waitcnt lgkmcnt(0)
	v_mfma_f32_16x16x32_bf16 v[124:127], v[154:157], v[194:197], v[124:127]
	v_mfma_f32_16x16x32_bf16 v[124:127], v[158:161], v[198:201], v[124:127]
	v_mfma_f32_16x16x32_bf16 v[108:111], v[154:157], v[202:205], v[108:111]
	v_mfma_f32_16x16x32_bf16 v[108:111], v[158:161], v[206:209], v[108:111]
	v_mfma_f32_16x16x32_bf16 v[92:95], v[154:157], v[210:213], v[92:95]
	v_mfma_f32_16x16x32_bf16 v[92:95], v[158:161], v[214:217], v[92:95]
	v_mfma_f32_16x16x32_bf16 v[76:79], v[154:157], v[218:221], v[76:79]
	v_mfma_f32_16x16x32_bf16 v[76:79], v[158:161], v[222:225], v[76:79]
	v_mfma_f32_16x16x32_bf16 v[120:123], v[170:173], v[194:197], v[120:123]
	v_mfma_f32_16x16x32_bf16 v[120:123], v[174:177], v[198:201], v[120:123]
	v_mfma_f32_16x16x32_bf16 v[104:107], v[170:173], v[202:205], v[104:107]
	v_mfma_f32_16x16x32_bf16 v[104:107], v[174:177], v[206:209], v[104:107]
	v_mfma_f32_16x16x32_bf16 v[88:91], v[170:173], v[210:213], v[88:91]
	v_mfma_f32_16x16x32_bf16 v[88:91], v[174:177], v[214:217], v[88:91]
	v_mfma_f32_16x16x32_bf16 v[72:75], v[170:173], v[218:221], v[72:75]
	v_mfma_f32_16x16x32_bf16 v[72:75], v[174:177], v[222:225], v[72:75]
	v_mfma_f32_16x16x32_bf16 v[116:119], v[178:181], v[194:197], v[116:119]
	v_mfma_f32_16x16x32_bf16 v[116:119], v[182:185], v[198:201], v[116:119]
	v_mfma_f32_16x16x32_bf16 v[100:103], v[178:181], v[202:205], v[100:103]
	v_mfma_f32_16x16x32_bf16 v[100:103], v[182:185], v[206:209], v[100:103]
	v_mfma_f32_16x16x32_bf16 v[84:87], v[178:181], v[210:213], v[84:87]
	v_mfma_f32_16x16x32_bf16 v[84:87], v[182:185], v[214:217], v[84:87]
	v_mfma_f32_16x16x32_bf16 v[68:71], v[178:181], v[218:221], v[68:71]
	v_mfma_f32_16x16x32_bf16 v[68:71], v[182:185], v[222:225], v[68:71]
	v_mfma_f32_16x16x32_bf16 v[112:115], v[186:189], v[194:197], v[112:115]
	v_mfma_f32_16x16x32_bf16 v[112:115], v[190:193], v[198:201], v[112:115]
	v_mfma_f32_16x16x32_bf16 v[96:99], v[186:189], v[202:205], v[96:99]
	v_mfma_f32_16x16x32_bf16 v[96:99], v[190:193], v[206:209], v[96:99]
	v_mfma_f32_16x16x32_bf16 v[80:83], v[186:189], v[210:213], v[80:83]
	v_mfma_f32_16x16x32_bf16 v[80:83], v[190:193], v[214:217], v[80:83]
	v_mfma_f32_16x16x32_bf16 v[64:67], v[186:189], v[218:221], v[64:67]
	v_mfma_f32_16x16x32_bf16 v[64:67], v[190:193], v[222:225], v[64:67]
	s_setprio 0
	s_barrier
	s_add_i32 s54, s44, s33
	v_lshl_add_u64 v[162:163], s[20:21], 0, v[130:131]
	s_mov_b32 m0, s54
	ds_read_b128 v[194:197], v151 offset:16384
	ds_read_b128 v[198:201], v151 offset:17408
	ds_read_b128 v[202:205], v151 offset:18432
	ds_read_b128 v[206:209], v151 offset:19456
	ds_read_b128 v[210:213], v151 offset:20480
	ds_read_b128 v[214:217], v151 offset:21504
	ds_read_b128 v[218:221], v151 offset:22528
	ds_read_b128 v[222:225], v151 offset:23552
	global_load_lds_dwordx4 v[162:163], off
	s_add_i32 m0, s54, 0x2000
	s_add_u32 s54, s20, 0x84000
	v_lshl_add_u64 v[166:167], s[20:21], 0, v[134:135]
	s_addc_u32 s55, s21, 0
	s_add_i32 s56, s45, s33
	global_load_lds_dwordx4 v[166:167], off
	v_lshl_add_u64 v[226:227], s[54:55], 0, v[130:131]
	s_mov_b32 m0, s56
	v_lshl_add_u64 v[228:229], s[22:23], 0, v[132:133]
	global_load_lds_dwordx4 v[226:227], off
	v_lshl_add_u64 v[226:227], s[54:55], 0, v[134:135]
	s_add_i32 m0, s56, 0x2000
	s_nop 0
	global_load_lds_dwordx4 v[226:227], off
	v_lshl_add_u64 v[226:227], s[22:23], 0, v[128:129]
	s_mov_b32 m0, s35
	s_nop 0
	global_load_lds_dwordx4 v[226:227], off
	s_mov_b32 m0, s36
	s_nop 0
	global_load_lds_dwordx4 v[228:229], off
	s_waitcnt vmcnt(8)
	s_waitcnt lgkmcnt(0)
	s_barrier
; #define PG8_STAGE(bufoff, gbase, voff) do { _Pragma("unroll") for (int _i = 0; _i < 2; ++_i) \
;         __builtin_amdgcn_global_load_lds((const unsigned*)((const char*)(gbase) + (voff)[_i]), (LAS unsigned*)(lds + (bufoff) + ldsw + _i * 8192), 16, 0, 0); } while (0)
; #define PG8_LDA(dst, b, h) do { _Pragma("unroll") for (int m = 0; m < 4; ++m) _Pragma("unroll") for (int k = 0; k < 2; ++k) dst[m][k] = *(const LAS bf16x8*)(lds + PG8_SA(b, h) + aoff + m * 2048 + k * 1024); } while (0)
; #define PG8_LDB(dst, b, h) do { _Pragma("unroll") for (int n = 0; n < 2; ++n) _Pragma("unroll") for (int k = 0; k < 2; ++k) dst[n][k] = *(const LAS bf16x8*)(lds + PG8_SB(b, h) + boff + n * 2048 + k * 1024); } while (0)
; #define PG8_MMA(ai, bj, At, Bt) do { __builtin_amdgcn_s_setprio(1); _Pragma("unroll") for (int m = 0; m < 4; ++m) _Pragma("unroll") for (int n = 0; n < 2; ++n) _Pragma("unroll") for (int k = 0; k < 2; ++k) \
;         acc[ai][bj][m][n] = __builtin_amdgcn_mfma_f32_16x16x32_bf16(Bt[n][k], At[m][k], acc[ai][bj][m][n], 0, 0, 0); __builtin_amdgcn_s_setprio(0); } while (0)
; #define PG8_WAIT_V(n) asm volatile("s_waitcnt vmcnt(" #n ")" ::: "memory")
; #define PG8_WAIT_L(n) asm volatile("s_waitcnt lgkmcnt(" #n ")" ::: "memory")
; #define PG8_BAR __builtin_amdgcn_s_barrier()
; #define PG8_SCHED __builtin_amdgcn_sched_barrier(0)
; template <class EpiT>
; __device__ __forceinline__ void gemm_phase(LAS unsigned char* lds, const Gemm g, const StaticOrder& S, const EpiT& E) {
;     ...
;             PG8_WAIT_V(8); PG8_WAIT_L(0); PG8_BAR; PG8_MMA(1, 0, At, B0); PG8_MMA(1, 1, At, B1); PG8_BAR; PG8_SCHED;
;             PG8_LDB(B0, 1, 0); PG8_LDB(B1, 1, 1); PG8_SCHED; PG8_LDA(At, 1, 0); PG8_STAGE(PG8_SA(0, 1), a2 + hstepA, voffA);
;             PG8_WAIT_V(8); PG8_WAIT_L(0); PG8_BAR; PG8_MMA(0, 0, At, B0); PG8_MMA(0, 1, At, B1); PG8_BAR; PG8_SCHED;
	s_setprio 1
	s_waitcnt lgkmcnt(0)
	v_mfma_f32_16x16x32_bf16 v[60:63], v[154:157], v[194:197], v[60:63]
	v_mfma_f32_16x16x32_bf16 v[60:63], v[158:161], v[198:201], v[60:63]
	v_mfma_f32_16x16x32_bf16 v[44:47], v[154:157], v[202:205], v[44:47]
	v_mfma_f32_16x16x32_bf16 v[44:47], v[158:161], v[206:209], v[44:47]
	v_mfma_f32_16x16x32_bf16 v[28:31], v[154:157], v[210:213], v[28:31]
	v_mfma_f32_16x16x32_bf16 v[28:31], v[158:161], v[214:217], v[28:31]
	v_mfma_f32_16x16x32_bf16 v[12:15], v[154:157], v[218:221], v[12:15]
	v_mfma_f32_16x16x32_bf16 v[12:15], v[158:161], v[222:225], v[12:15]
	v_mfma_f32_16x16x32_bf16 v[56:59], v[170:173], v[194:197], v[56:59]
	v_mfma_f32_16x16x32_bf16 v[56:59], v[174:177], v[198:201], v[56:59]
	v_mfma_f32_16x16x32_bf16 v[40:43], v[170:173], v[202:205], v[40:43]
	v_mfma_f32_16x16x32_bf16 v[40:43], v[174:177], v[206:209], v[40:43]
	v_mfma_f32_16x16x32_bf16 v[24:27], v[170:173], v[210:213], v[24:27]
	v_mfma_f32_16x16x32_bf16 v[24:27], v[174:177], v[214:217], v[24:27]
	v_mfma_f32_16x16x32_bf16 v[8:11], v[170:173], v[218:221], v[8:11]
	v_mfma_f32_16x16x32_bf16 v[8:11], v[174:177], v[222:225], v[8:11]
	v_mfma_f32_16x16x32_bf16 v[52:55], v[178:181], v[194:197], v[52:55]
	v_mfma_f32_16x16x32_bf16 v[52:55], v[182:185], v[198:201], v[52:55]
	v_mfma_f32_16x16x32_bf16 v[36:39], v[178:181], v[202:205], v[36:39]
	v_mfma_f32_16x16x32_bf16 v[36:39], v[182:185], v[206:209], v[36:39]
	v_mfma_f32_16x16x32_bf16 v[20:23], v[178:181], v[210:213], v[20:23]
	v_mfma_f32_16x16x32_bf16 v[20:23], v[182:185], v[214:217], v[20:23]
	v_mfma_f32_16x16x32_bf16 v[4:7], v[178:181], v[218:221], v[4:7]
	v_mfma_f32_16x16x32_bf16 v[4:7], v[182:185], v[222:225], v[4:7]
	v_mfma_f32_16x16x32_bf16 v[48:51], v[186:189], v[194:197], v[48:51]
	v_mfma_f32_16x16x32_bf16 v[48:51], v[190:193], v[198:201], v[48:51]
	v_mfma_f32_16x16x32_bf16 v[32:35], v[186:189], v[202:205], v[32:35]
	v_mfma_f32_16x16x32_bf16 v[32:35], v[190:193], v[206:209], v[32:35]
	v_mfma_f32_16x16x32_bf16 v[16:19], v[186:189], v[210:213], v[16:19]
	v_mfma_f32_16x16x32_bf16 v[16:19], v[190:193], v[214:217], v[16:19]
	v_mfma_f32_16x16x32_bf16 v[0:3], v[186:189], v[218:221], v[0:3]
	v_mfma_f32_16x16x32_bf16 v[0:3], v[190:193], v[222:225], v[0:3]
	s_setprio 0
	s_barrier
	s_add_i32 s54, 0, 0x18000
	v_add_u32_e32 v153, s54, v146
	s_add_i32 s55, 0, 0x1c000
	ds_read_b128 v[154:157], v153
	ds_read_b128 v[158:161], v153 offset:1024
	ds_read_b128 v[170:173], v153 offset:2048
	ds_read_b128 v[174:177], v153 offset:3072
	v_add_u32_e32 v153, s55, v146
	ds_read_b128 v[178:181], v153
	ds_read_b128 v[182:185], v153 offset:1024
	ds_read_b128 v[186:189], v153 offset:2048
	ds_read_b128 v[190:193], v153 offset:3072
	s_add_u32 s22, s22, 0x84000
	s_addc_u32 s23, s23, 0
	s_mov_b32 m0, s37
	v_lshl_add_u64 v[230:231], s[22:23], 0, v[128:129]
	ds_read_b128 v[194:197], v151 offset:32768
	ds_read_b128 v[198:201], v151 offset:33792
	ds_read_b128 v[202:205], v151 offset:34816
	ds_read_b128 v[206:209], v151 offset:35840
	ds_read_b128 v[210:213], v151 offset:36864
	ds_read_b128 v[214:217], v151 offset:37888
	ds_read_b128 v[218:221], v151 offset:38912
	ds_read_b128 v[222:225], v151 offset:39936
	global_load_lds_dwordx4 v[230:231], off
	v_lshl_add_u64 v[230:231], s[22:23], 0, v[132:133]
	s_mov_b32 m0, s38
	s_nop 0
	global_load_lds_dwordx4 v[230:231], off
	s_waitcnt vmcnt(8)
	s_waitcnt lgkmcnt(0)
	s_barrier
	s_setprio 1
	s_waitcnt lgkmcnt(0)
	v_mfma_f32_16x16x32_bf16 v[124:127], v[154:157], v[194:197], v[124:127]
	v_mfma_f32_16x16x32_bf16 v[124:127], v[158:161], v[198:201], v[124:127]
	v_mfma_f32_16x16x32_bf16 v[108:111], v[154:157], v[202:205], v[108:111]
	v_mfma_f32_16x16x32_bf16 v[108:111], v[158:161], v[206:209], v[108:111]
	v_mfma_f32_16x16x32_bf16 v[92:95], v[154:157], v[210:213], v[92:95]
	v_mfma_f32_16x16x32_bf16 v[92:95], v[158:161], v[214:217], v[92:95]
	v_mfma_f32_16x16x32_bf16 v[76:79], v[154:157], v[218:221], v[76:79]
	v_mfma_f32_16x16x32_bf16 v[76:79], v[158:161], v[222:225], v[76:79]
	v_mfma_f32_16x16x32_bf16 v[120:123], v[170:173], v[194:197], v[120:123]
	v_mfma_f32_16x16x32_bf16 v[120:123], v[174:177], v[198:201], v[120:123]
	v_mfma_f32_16x16x32_bf16 v[104:107], v[170:173], v[202:205], v[104:107]
	v_mfma_f32_16x16x32_bf16 v[104:107], v[174:177], v[206:209], v[104:107]
	v_mfma_f32_16x16x32_bf16 v[88:91], v[170:173], v[210:213], v[88:91]
	v_mfma_f32_16x16x32_bf16 v[88:91], v[174:177], v[214:217], v[88:91]
	v_mfma_f32_16x16x32_bf16 v[72:75], v[170:173], v[218:221], v[72:75]
	v_mfma_f32_16x16x32_bf16 v[72:75], v[174:177], v[222:225], v[72:75]
	v_mfma_f32_16x16x32_bf16 v[116:119], v[178:181], v[194:197], v[116:119]
	v_mfma_f32_16x16x32_bf16 v[116:119], v[182:185], v[198:201], v[116:119]
	v_mfma_f32_16x16x32_bf16 v[100:103], v[178:181], v[202:205], v[100:103]
	v_mfma_f32_16x16x32_bf16 v[100:103], v[182:185], v[206:209], v[100:103]
	v_mfma_f32_16x16x32_bf16 v[84:87], v[178:181], v[210:213], v[84:87]
	v_mfma_f32_16x16x32_bf16 v[84:87], v[182:185], v[214:217], v[84:87]
	v_mfma_f32_16x16x32_bf16 v[68:71], v[178:181], v[218:221], v[68:71]
	v_mfma_f32_16x16x32_bf16 v[68:71], v[182:185], v[222:225], v[68:71]
	v_mfma_f32_16x16x32_bf16 v[112:115], v[186:189], v[194:197], v[112:115]
	v_mfma_f32_16x16x32_bf16 v[112:115], v[190:193], v[198:201], v[112:115]
	v_mfma_f32_16x16x32_bf16 v[96:99], v[186:189], v[202:205], v[96:99]
	v_mfma_f32_16x16x32_bf16 v[96:99], v[190:193], v[206:209], v[96:99]
	v_mfma_f32_16x16x32_bf16 v[80:83], v[186:189], v[210:213], v[80:83]
	v_mfma_f32_16x16x32_bf16 v[80:83], v[190:193], v[214:217], v[80:83]
	v_mfma_f32_16x16x32_bf16 v[64:67], v[186:189], v[218:221], v[64:67]
	v_mfma_f32_16x16x32_bf16 v[64:67], v[190:193], v[222:225], v[64:67]
	s_setprio 0
	s_barrier
; #define PG8_STAGE(bufoff, gbase, voff) do { _Pragma("unroll") for (int _i = 0; _i < 2; ++_i) \
;         __builtin_amdgcn_global_load_lds((const unsigned*)((const char*)(gbase) + (voff)[_i]), (LAS unsigned*)(lds + (bufoff) + ldsw + _i * 8192), 16, 0, 0); } while (0)
; #define PG8_LDA(dst, b, h) do { _Pragma("unroll") for (int m = 0; m < 4; ++m) _Pragma("unroll") for (int k = 0; k < 2; ++k) dst[m][k] = *(const LAS bf16x8*)(lds + PG8_SA(b, h) + aoff + m * 2048 + k * 1024); } while (0)
; #define PG8_MMA(ai, bj, At, Bt) do { __builtin_amdgcn_s_setprio(1); _Pragma("unroll") for (int m = 0; m < 4; ++m) _Pragma("unroll") for (int n = 0; n < 2; ++n) _Pragma("unroll") for (int k = 0; k < 2; ++k) \
;         acc[ai][bj][m][n] = __builtin_amdgcn_mfma_f32_16x16x32_bf16(Bt[n][k], At[m][k], acc[ai][bj][m][n], 0, 0, 0); __builtin_amdgcn_s_setprio(0); } while (0)
; #define PG8_WAIT_V(n) asm volatile("s_waitcnt vmcnt(" #n ")" ::: "memory")
; #define PG8_WAIT_L(n) asm volatile("s_waitcnt lgkmcnt(" #n ")" ::: "memory")
; #define PG8_BAR __builtin_amdgcn_s_barrier()
; #define PG8_SCHED __builtin_amdgcn_sched_barrier(0)
; template <class EpiT>
; __device__ __forceinline__ void gemm_phase(LAS unsigned char* lds, const Gemm g, const StaticOrder& S, const EpiT& E) {
;     ...
;             PG8_LDA(At, 1, 1); PG8_STAGE(PG8_SB(1, 0), b3, voffB); PG8_STAGE(PG8_SB(1, 1), b3 + hstepB, voffB); PG8_STAGE(PG8_SA(1, 0), a3, voffA);
;             PG8_WAIT_V(8); PG8_WAIT_L(0); PG8_BAR; PG8_MMA(1, 0, At, B0); PG8_MMA(1, 1, At, B1); PG8_BAR; PG8_SCHED;
;         }
;         if (wr == 0) PG8_BAR;
	s_add_i32 s22, s54, s33
	v_lshl_add_u64 v[162:163], v[162:163], 0, s[12:13]
	s_mov_b32 m0, s22
	ds_read_b128 v[194:197], v151 offset:49152
	ds_read_b128 v[198:201], v151 offset:50176
	ds_read_b128 v[202:205], v151 offset:51200
	ds_read_b128 v[206:209], v151 offset:52224
	ds_read_b128 v[210:213], v151 offset:53248
	ds_read_b128 v[214:217], v151 offset:54272
	ds_read_b128 v[218:221], v151 offset:55296
	ds_read_b128 v[222:225], v151 offset:56320
	global_load_lds_dwordx4 v[162:163], off
	s_add_i32 m0, s22, 0x2000
	s_add_u32 s20, s20, 0x84080
	v_lshl_add_u64 v[162:163], v[166:167], 0, s[12:13]
	s_addc_u32 s21, s21, 0
	s_add_i32 s22, s55, s33
	global_load_lds_dwordx4 v[162:163], off
	v_lshl_add_u64 v[162:163], s[20:21], 0, v[130:131]
	s_mov_b32 m0, s22
	s_nop 0
	global_load_lds_dwordx4 v[162:163], off
	v_lshl_add_u64 v[162:163], s[20:21], 0, v[134:135]
	s_add_i32 m0, s22, 0x2000
	s_nop 0
	global_load_lds_dwordx4 v[162:163], off
	v_lshl_add_u64 v[162:163], v[226:227], 0, s[12:13]
	s_mov_b32 m0, s40
	s_nop 0
	global_load_lds_dwordx4 v[162:163], off
	v_lshl_add_u64 v[162:163], v[228:229], 0, s[12:13]
	s_mov_b32 m0, s41
	s_nop 0
	global_load_lds_dwordx4 v[162:163], off
	s_waitcnt vmcnt(8)
	s_waitcnt lgkmcnt(0)
	s_barrier
	s_setprio 1
	s_waitcnt lgkmcnt(0)
	v_mfma_f32_16x16x32_bf16 v[60:63], v[154:157], v[194:197], v[60:63]
	v_mfma_f32_16x16x32_bf16 v[60:63], v[158:161], v[198:201], v[60:63]
	v_mfma_f32_16x16x32_bf16 v[44:47], v[154:157], v[202:205], v[44:47]
	v_mfma_f32_16x16x32_bf16 v[44:47], v[158:161], v[206:209], v[44:47]
	v_mfma_f32_16x16x32_bf16 v[28:31], v[154:157], v[210:213], v[28:31]
	v_mfma_f32_16x16x32_bf16 v[28:31], v[158:161], v[214:217], v[28:31]
	v_mfma_f32_16x16x32_bf16 v[12:15], v[154:157], v[218:221], v[12:15]
	v_mfma_f32_16x16x32_bf16 v[12:15], v[158:161], v[222:225], v[12:15]
	v_mfma_f32_16x16x32_bf16 v[56:59], v[170:173], v[194:197], v[56:59]
	v_mfma_f32_16x16x32_bf16 v[56:59], v[174:177], v[198:201], v[56:59]
	v_mfma_f32_16x16x32_bf16 v[40:43], v[170:173], v[202:205], v[40:43]
	v_mfma_f32_16x16x32_bf16 v[40:43], v[174:177], v[206:209], v[40:43]
	v_mfma_f32_16x16x32_bf16 v[24:27], v[170:173], v[210:213], v[24:27]
	v_mfma_f32_16x16x32_bf16 v[24:27], v[174:177], v[214:217], v[24:27]
	v_mfma_f32_16x16x32_bf16 v[8:11], v[170:173], v[218:221], v[8:11]
	v_mfma_f32_16x16x32_bf16 v[8:11], v[174:177], v[222:225], v[8:11]
	v_mfma_f32_16x16x32_bf16 v[52:55], v[178:181], v[194:197], v[52:55]
	v_mfma_f32_16x16x32_bf16 v[52:55], v[182:185], v[198:201], v[52:55]
	v_mfma_f32_16x16x32_bf16 v[36:39], v[178:181], v[202:205], v[36:39]
	v_mfma_f32_16x16x32_bf16 v[36:39], v[182:185], v[206:209], v[36:39]
	v_mfma_f32_16x16x32_bf16 v[20:23], v[178:181], v[210:213], v[20:23]
	v_mfma_f32_16x16x32_bf16 v[20:23], v[182:185], v[214:217], v[20:23]
	v_mfma_f32_16x16x32_bf16 v[4:7], v[178:181], v[218:221], v[4:7]
	v_mfma_f32_16x16x32_bf16 v[4:7], v[182:185], v[222:225], v[4:7]
	v_mfma_f32_16x16x32_bf16 v[48:51], v[186:189], v[194:197], v[48:51]
	v_mfma_f32_16x16x32_bf16 v[48:51], v[190:193], v[198:201], v[48:51]
	v_mfma_f32_16x16x32_bf16 v[32:35], v[186:189], v[202:205], v[32:35]
	v_mfma_f32_16x16x32_bf16 v[32:35], v[190:193], v[206:209], v[32:35]
	v_mfma_f32_16x16x32_bf16 v[16:19], v[186:189], v[210:213], v[16:19]
	v_mfma_f32_16x16x32_bf16 v[16:19], v[190:193], v[214:217], v[16:19]
	v_mfma_f32_16x16x32_bf16 v[0:3], v[186:189], v[218:221], v[0:3]
	v_mfma_f32_16x16x32_bf16 v[0:3], v[190:193], v[222:225], v[0:3]
	s_setprio 0
	s_barrier
	s_add_i32 s53, s53, 2
	s_add_u32 s18, s18, 0x100
	s_addc_u32 s19, s19, 0
	s_add_u32 s51, s51, 0x100
	s_addc_u32 s52, s52, 0
	s_cmp_gt_u32 s53, 29
	s_cbranch_scc0 .LBB0_392
	s_and_b64 vcc, exec, s[14:15]
	s_cbranch_vccz .LBB0_395
	s_barrier

; #define PG8_STAGE(bufoff, gbase, voff) do { _Pragma("unroll") for (int _i = 0; _i < 2; ++_i) \
;         __builtin_amdgcn_global_load_lds((const unsigned*)((const char*)(gbase) + (voff)[_i]), (LAS unsigned*)(lds + (bufoff) + ldsw + _i * 8192), 16, 0, 0); } while (0)
; #define PG8_LDA(dst, b, h) do { _Pragma("unroll") for (int m = 0; m < 4; ++m) _Pragma("unroll") for (int k = 0; k < 2; ++k) dst[m][k] = *(const LAS bf16x8*)(lds + PG8_SA(b, h) + aoff + m * 2048 + k * 1024); } while (0)
; #define PG8_LDB(dst, b, h) do { _Pragma("unroll") for (int n = 0; n < 2; ++n) _Pragma("unroll") for (int k = 0; k < 2; ++k) dst[n][k] = *(const LAS bf16x8*)(lds + PG8_SB(b, h) + boff + n * 2048 + k * 1024); } while (0)
; #define PG8_MMA(ai, bj, At, Bt) do { __builtin_amdgcn_s_setprio(1); _Pragma("unroll") for (int m = 0; m < 4; ++m) _Pragma("unroll") for (int n = 0; n < 2; ++n) _Pragma("unroll") for (int k = 0; k < 2; ++k) \
;         acc[ai][bj][m][n] = __builtin_amdgcn_mfma_f32_16x16x32_bf16(Bt[n][k], At[m][k], acc[ai][bj][m][n], 0, 0, 0); __builtin_amdgcn_s_setprio(0); } while (0)
; #define PG8_WAIT_V(n) asm volatile("s_waitcnt vmcnt(" #n ")" ::: "memory")
; #define PG8_WAIT_L(n) asm volatile("s_waitcnt lgkmcnt(" #n ")" ::: "memory")
; #define PG8_BAR __builtin_amdgcn_s_barrier()
; #define PG8_SCHED __builtin_amdgcn_sched_barrier(0)
; template <class EpiT>
; __device__ __forceinline__ void gemm_phase(LAS unsigned char* lds, const Gemm g, const StaticOrder& S, const EpiT& E) {
;     ...
;             const bool last = (t == nt - 2);
;             const char* a1 = cA + (size_t)(t + 1) * kstep;
;             const char* a2 = last ? nA : cA + (size_t)(t + 2) * kstep; const char* b2 = last ? nB : cB + (size_t)(t + 2) * kstep;
;             const char* a3 = a2 + kstep; const char* b3 = b2 + kstep;
;             PG8_LDB(B0, 0, 0); PG8_LDB(B1, 0, 1); PG8_SCHED; PG8_LDA(At, 0, 0); PG8_STAGE(PG8_SA(1, 1), a1 + hstepA, voffA);
;             PG8_WAIT_V(8); PG8_WAIT_L(0); PG8_BAR; PG8_MMA(0, 0, At, B0); PG8_MMA(0, 1, At, B1); PG8_BAR; PG8_SCHED;
;             PG8_LDA(At, 0, 1); PG8_STAGE(PG8_SB(0, 0), b2, voffB); PG8_STAGE(PG8_SB(0, 1), b2 + hstepB, voffB); PG8_STAGE(PG8_SA(0, 0), a2, voffA);
.LBB0_516:
	ds_read_b128 v[154:157], v150
	ds_read_b128 v[158:161], v150 offset:1024
	ds_read_b128 v[170:173], v150 offset:2048
	ds_read_b128 v[174:177], v150 offset:3072
	ds_read_b128 v[178:181], v151
	ds_read_b128 v[182:185], v151 offset:1024
	ds_read_b128 v[186:189], v151 offset:2048
	ds_read_b128 v[190:193], v151 offset:3072
	s_add_u32 s18, s16, 0xfff7c080
	s_addc_u32 s19, s17, -1
	s_cmp_eq_u32 s53, 28
	s_cselect_b32 s21, s3, s19
	s_cselect_b32 s20, s2, s18
	s_cselect_b32 s19, s15, s52
	s_cselect_b32 s18, s14, s51
	v_lshl_add_u64 v[144:145], s[16:17], 0, v[136:137]
	s_add_i32 m0, s36, 0xc000
	ds_read_b128 v[194:197], v152
	ds_read_b128 v[198:201], v152 offset:1024
	ds_read_b128 v[202:205], v152 offset:2048
	ds_read_b128 v[206:209], v152 offset:3072
	ds_read_b128 v[210:213], v152 offset:4096
	ds_read_b128 v[214:217], v152 offset:5120
	ds_read_b128 v[218:221], v152 offset:6144
	ds_read_b128 v[222:225], v152 offset:7168
	global_load_lds_dwordx4 v[144:145], off
	v_lshl_add_u64 v[144:145], s[16:17], 0, v[138:139]
	s_add_i32 m0, s36, 0xe000
	s_nop 0
	global_load_lds_dwordx4 v[144:145], off
	s_waitcnt vmcnt(8)
	s_waitcnt lgkmcnt(0)
	s_barrier
	s_setprio 1
	s_waitcnt lgkmcnt(0)
	v_mfma_f32_16x16x32_bf16 v[124:127], v[154:157], v[194:197], v[124:127]
	v_mfma_f32_16x16x32_bf16 v[124:127], v[158:161], v[198:201], v[124:127]
	v_mfma_f32_16x16x32_bf16 v[108:111], v[154:157], v[202:205], v[108:111]
	v_mfma_f32_16x16x32_bf16 v[108:111], v[158:161], v[206:209], v[108:111]
	v_mfma_f32_16x16x32_bf16 v[92:95], v[154:157], v[210:213], v[92:95]
	v_mfma_f32_16x16x32_bf16 v[92:95], v[158:161], v[214:217], v[92:95]
	v_mfma_f32_16x16x32_bf16 v[76:79], v[154:157], v[218:221], v[76:79]
	v_mfma_f32_16x16x32_bf16 v[76:79], v[158:161], v[222:225], v[76:79]
	v_mfma_f32_16x16x32_bf16 v[120:123], v[170:173], v[194:197], v[120:123]
	v_mfma_f32_16x16x32_bf16 v[120:123], v[174:177], v[198:201], v[120:123]
	v_mfma_f32_16x16x32_bf16 v[104:107], v[170:173], v[202:205], v[104:107]
	v_mfma_f32_16x16x32_bf16 v[104:107], v[174:177], v[206:209], v[104:107]
	v_mfma_f32_16x16x32_bf16 v[88:91], v[170:173], v[210:213], v[88:91]
	v_mfma_f32_16x16x32_bf16 v[88:91], v[174:177], v[214:217], v[88:91]
	v_mfma_f32_16x16x32_bf16 v[72:75], v[170:173], v[218:221], v[72:75]
	v_mfma_f32_16x16x32_bf16 v[72:75], v[174:177], v[222:225], v[72:75]
	v_mfma_f32_16x16x32_bf16 v[116:119], v[178:181], v[194:197], v[116:119]
	v_mfma_f32_16x16x32_bf16 v[116:119], v[182:185], v[198:201], v[116:119]
	v_mfma_f32_16x16x32_bf16 v[100:103], v[178:181], v[202:205], v[100:103]
	v_mfma_f32_16x16x32_bf16 v[100:103], v[182:185], v[206:209], v[100:103]
	v_mfma_f32_16x16x32_bf16 v[84:87], v[178:181], v[210:213], v[84:87]
	v_mfma_f32_16x16x32_bf16 v[84:87], v[182:185], v[214:217], v[84:87]
	v_mfma_f32_16x16x32_bf16 v[68:71], v[178:181], v[218:221], v[68:71]
	v_mfma_f32_16x16x32_bf16 v[68:71], v[182:185], v[222:225], v[68:71]
	v_mfma_f32_16x16x32_bf16 v[112:115], v[186:189], v[194:197], v[112:115]
	v_mfma_f32_16x16x32_bf16 v[112:115], v[190:193], v[198:201], v[112:115]
	v_mfma_f32_16x16x32_bf16 v[96:99], v[186:189], v[202:205], v[96:99]
	v_mfma_f32_16x16x32_bf16 v[96:99], v[190:193], v[206:209], v[96:99]
	v_mfma_f32_16x16x32_bf16 v[80:83], v[186:189], v[210:213], v[80:83]
	v_mfma_f32_16x16x32_bf16 v[80:83], v[190:193], v[214:217], v[80:83]
	v_mfma_f32_16x16x32_bf16 v[64:67], v[186:189], v[218:221], v[64:67]
	v_mfma_f32_16x16x32_bf16 v[64:67], v[190:193], v[222:225], v[64:67]
	s_setprio 0
	s_barrier
	s_add_i32 s54, s44, s27
	v_lshl_add_u64 v[144:145], s[18:19], 0, v[132:133]
	s_mov_b32 m0, s54
	ds_read_b128 v[194:197], v152 offset:16384
	ds_read_b128 v[198:201], v152 offset:17408
	ds_read_b128 v[202:205], v152 offset:18432
	ds_read_b128 v[206:209], v152 offset:19456
	ds_read_b128 v[210:213], v152 offset:20480
	ds_read_b128 v[214:217], v152 offset:21504
	ds_read_b128 v[218:221], v152 offset:22528
	ds_read_b128 v[222:225], v152 offset:23552
	global_load_lds_dwordx4 v[144:145], off
	s_add_i32 m0, s54, 0x2000
	s_add_u32 s54, s18, 0x84000
	v_lshl_add_u64 v[162:163], s[18:19], 0, v[128:129]
	s_addc_u32 s55, s19, 0
	s_add_i32 s56, s45, s27
	global_load_lds_dwordx4 v[162:163], off
	v_lshl_add_u64 v[166:167], s[54:55], 0, v[132:133]
	s_mov_b32 m0, s56
	v_lshl_add_u64 v[226:227], s[20:21], 0, v[130:131]
	global_load_lds_dwordx4 v[166:167], off
	v_lshl_add_u64 v[166:167], s[54:55], 0, v[128:129]
	s_add_i32 m0, s56, 0x2000
	s_nop 0
	global_load_lds_dwordx4 v[166:167], off
	v_lshl_add_u64 v[166:167], s[20:21], 0, v[134:135]
	s_mov_b32 m0, s36
	s_nop 0
	global_load_lds_dwordx4 v[166:167], off
	s_mov_b32 m0, s37
	s_nop 0
	global_load_lds_dwordx4 v[226:227], off
	s_waitcnt vmcnt(8)
	s_waitcnt lgkmcnt(0)
	s_barrier
; #define PG8_STAGE(bufoff, gbase, voff) do { _Pragma("unroll") for (int _i = 0; _i < 2; ++_i) \
;         __builtin_amdgcn_global_load_lds((const unsigned*)((const char*)(gbase) + (voff)[_i]), (LAS unsigned*)(lds + (bufoff) + ldsw + _i * 8192), 16, 0, 0); } while (0)
; #define PG8_LDA(dst, b, h) do { _Pragma("unroll") for (int m = 0; m < 4; ++m) _Pragma("unroll") for (int k = 0; k < 2; ++k) dst[m][k] = *(const LAS bf16x8*)(lds + PG8_SA(b, h) + aoff + m * 2048 + k * 1024); } while (0)
; #define PG8_LDB(dst, b, h) do { _Pragma("unroll") for (int n = 0; n < 2; ++n) _Pragma("unroll") for (int k = 0; k < 2; ++k) dst[n][k] = *(const LAS bf16x8*)(lds + PG8_SB(b, h) + boff + n * 2048 + k * 1024); } while (0)
; #define PG8_MMA(ai, bj, At, Bt) do { __builtin_amdgcn_s_setprio(1); _Pragma("unroll") for (int m = 0; m < 4; ++m) _Pragma("unroll") for (int n = 0; n < 2; ++n) _Pragma("unroll") for (int k = 0; k < 2; ++k) \
;         acc[ai][bj][m][n] = __builtin_amdgcn_mfma_f32_16x16x32_bf16(Bt[n][k], At[m][k], acc[ai][bj][m][n], 0, 0, 0); __builtin_amdgcn_s_setprio(0); } while (0)
; #define PG8_WAIT_V(n) asm volatile("s_waitcnt vmcnt(" #n ")" ::: "memory")
; #define PG8_WAIT_L(n) asm volatile("s_waitcnt lgkmcnt(" #n ")" ::: "memory")
; #define PG8_BAR __builtin_amdgcn_s_barrier()
; #define PG8_SCHED __builtin_amdgcn_sched_barrier(0)
; template <class EpiT>
; __device__ __forceinline__ void gemm_phase(LAS unsigned char* lds, const Gemm g, const StaticOrder& S, const EpiT& E) {
;     ...
;             PG8_WAIT_V(8); PG8_WAIT_L(0); PG8_BAR; PG8_MMA(1, 0, At, B0); PG8_MMA(1, 1, At, B1); PG8_BAR; PG8_SCHED;
;             PG8_LDB(B0, 1, 0); PG8_LDB(B1, 1, 1); PG8_SCHED; PG8_LDA(At, 1, 0); PG8_STAGE(PG8_SA(0, 1), a2 + hstepA, voffA);
;             PG8_WAIT_V(8); PG8_WAIT_L(0); PG8_BAR; PG8_MMA(0, 0, At, B0); PG8_MMA(0, 1, At, B1); PG8_BAR; PG8_SCHED;
	s_setprio 1
	s_waitcnt lgkmcnt(0)
	v_mfma_f32_16x16x32_bf16 v[60:63], v[154:157], v[194:197], v[60:63]
	v_mfma_f32_16x16x32_bf16 v[60:63], v[158:161], v[198:201], v[60:63]
	v_mfma_f32_16x16x32_bf16 v[44:47], v[154:157], v[202:205], v[44:47]
	v_mfma_f32_16x16x32_bf16 v[44:47], v[158:161], v[206:209], v[44:47]
	v_mfma_f32_16x16x32_bf16 v[28:31], v[154:157], v[210:213], v[28:31]
	v_mfma_f32_16x16x32_bf16 v[28:31], v[158:161], v[214:217], v[28:31]
	v_mfma_f32_16x16x32_bf16 v[12:15], v[154:157], v[218:221], v[12:15]
	v_mfma_f32_16x16x32_bf16 v[12:15], v[158:161], v[222:225], v[12:15]
	v_mfma_f32_16x16x32_bf16 v[56:59], v[170:173], v[194:197], v[56:59]
	v_mfma_f32_16x16x32_bf16 v[56:59], v[174:177], v[198:201], v[56:59]
	v_mfma_f32_16x16x32_bf16 v[40:43], v[170:173], v[202:205], v[40:43]
	v_mfma_f32_16x16x32_bf16 v[40:43], v[174:177], v[206:209], v[40:43]
	v_mfma_f32_16x16x32_bf16 v[24:27], v[170:173], v[210:213], v[24:27]
	v_mfma_f32_16x16x32_bf16 v[24:27], v[174:177], v[214:217], v[24:27]
	v_mfma_f32_16x16x32_bf16 v[8:11], v[170:173], v[218:221], v[8:11]
	v_mfma_f32_16x16x32_bf16 v[8:11], v[174:177], v[222:225], v[8:11]
	v_mfma_f32_16x16x32_bf16 v[52:55], v[178:181], v[194:197], v[52:55]
	v_mfma_f32_16x16x32_bf16 v[52:55], v[182:185], v[198:201], v[52:55]
	v_mfma_f32_16x16x32_bf16 v[36:39], v[178:181], v[202:205], v[36:39]
	v_mfma_f32_16x16x32_bf16 v[36:39], v[182:185], v[206:209], v[36:39]
	v_mfma_f32_16x16x32_bf16 v[20:23], v[178:181], v[210:213], v[20:23]
	v_mfma_f32_16x16x32_bf16 v[20:23], v[182:185], v[214:217], v[20:23]
	v_mfma_f32_16x16x32_bf16 v[4:7], v[178:181], v[218:221], v[4:7]
	v_mfma_f32_16x16x32_bf16 v[4:7], v[182:185], v[222:225], v[4:7]
	v_mfma_f32_16x16x32_bf16 v[48:51], v[186:189], v[194:197], v[48:51]
	v_mfma_f32_16x16x32_bf16 v[48:51], v[190:193], v[198:201], v[48:51]
	v_mfma_f32_16x16x32_bf16 v[32:35], v[186:189], v[202:205], v[32:35]
	v_mfma_f32_16x16x32_bf16 v[32:35], v[190:193], v[206:209], v[32:35]
	v_mfma_f32_16x16x32_bf16 v[16:19], v[186:189], v[210:213], v[16:19]
	v_mfma_f32_16x16x32_bf16 v[16:19], v[190:193], v[214:217], v[16:19]
	v_mfma_f32_16x16x32_bf16 v[0:3], v[186:189], v[218:221], v[0:3]
	v_mfma_f32_16x16x32_bf16 v[0:3], v[190:193], v[222:225], v[0:3]
	s_setprio 0
	s_barrier
	s_add_i32 s54, 0, 0x18000
	v_add_u32_e32 v153, s54, v147
	s_add_i32 s55, 0, 0x1c000
	ds_read_b128 v[154:157], v153
	ds_read_b128 v[158:161], v153 offset:1024
	ds_read_b128 v[170:173], v153 offset:2048
	ds_read_b128 v[174:177], v153 offset:3072
	v_add_u32_e32 v153, s55, v147
	ds_read_b128 v[178:181], v153
	ds_read_b128 v[182:185], v153 offset:1024
	ds_read_b128 v[186:189], v153 offset:2048
	ds_read_b128 v[190:193], v153 offset:3072
	s_add_u32 s20, s20, 0x84000
	s_addc_u32 s21, s21, 0
	s_mov_b32 m0, s38
	v_lshl_add_u64 v[228:229], s[20:21], 0, v[134:135]
	ds_read_b128 v[194:197], v152 offset:32768
	ds_read_b128 v[198:201], v152 offset:33792
	ds_read_b128 v[202:205], v152 offset:34816
	ds_read_b128 v[206:209], v152 offset:35840
	ds_read_b128 v[210:213], v152 offset:36864
	ds_read_b128 v[214:217], v152 offset:37888
	ds_read_b128 v[218:221], v152 offset:38912
	ds_read_b128 v[222:225], v152 offset:39936
	global_load_lds_dwordx4 v[228:229], off
	v_lshl_add_u64 v[228:229], s[20:21], 0, v[130:131]
	s_mov_b32 m0, s39
	s_nop 0
	global_load_lds_dwordx4 v[228:229], off
	s_waitcnt vmcnt(8)
	s_waitcnt lgkmcnt(0)
	s_barrier
	s_setprio 1
	s_waitcnt lgkmcnt(0)
	v_mfma_f32_16x16x32_bf16 v[124:127], v[154:157], v[194:197], v[124:127]
	v_mfma_f32_16x16x32_bf16 v[124:127], v[158:161], v[198:201], v[124:127]
	v_mfma_f32_16x16x32_bf16 v[108:111], v[154:157], v[202:205], v[108:111]
	v_mfma_f32_16x16x32_bf16 v[108:111], v[158:161], v[206:209], v[108:111]
	v_mfma_f32_16x16x32_bf16 v[92:95], v[154:157], v[210:213], v[92:95]
	v_mfma_f32_16x16x32_bf16 v[92:95], v[158:161], v[214:217], v[92:95]
	v_mfma_f32_16x16x32_bf16 v[76:79], v[154:157], v[218:221], v[76:79]
	v_mfma_f32_16x16x32_bf16 v[76:79], v[158:161], v[222:225], v[76:79]
	v_mfma_f32_16x16x32_bf16 v[120:123], v[170:173], v[194:197], v[120:123]
	v_mfma_f32_16x16x32_bf16 v[120:123], v[174:177], v[198:201], v[120:123]
	v_mfma_f32_16x16x32_bf16 v[104:107], v[170:173], v[202:205], v[104:107]
	v_mfma_f32_16x16x32_bf16 v[104:107], v[174:177], v[206:209], v[104:107]
	v_mfma_f32_16x16x32_bf16 v[88:91], v[170:173], v[210:213], v[88:91]
	v_mfma_f32_16x16x32_bf16 v[88:91], v[174:177], v[214:217], v[88:91]
	v_mfma_f32_16x16x32_bf16 v[72:75], v[170:173], v[218:221], v[72:75]
	v_mfma_f32_16x16x32_bf16 v[72:75], v[174:177], v[222:225], v[72:75]
	v_mfma_f32_16x16x32_bf16 v[116:119], v[178:181], v[194:197], v[116:119]
	v_mfma_f32_16x16x32_bf16 v[116:119], v[182:185], v[198:201], v[116:119]
	v_mfma_f32_16x16x32_bf16 v[100:103], v[178:181], v[202:205], v[100:103]
	v_mfma_f32_16x16x32_bf16 v[100:103], v[182:185], v[206:209], v[100:103]
	v_mfma_f32_16x16x32_bf16 v[84:87], v[178:181], v[210:213], v[84:87]
	v_mfma_f32_16x16x32_bf16 v[84:87], v[182:185], v[214:217], v[84:87]
	v_mfma_f32_16x16x32_bf16 v[68:71], v[178:181], v[218:221], v[68:71]
	v_mfma_f32_16x16x32_bf16 v[68:71], v[182:185], v[222:225], v[68:71]
	v_mfma_f32_16x16x32_bf16 v[112:115], v[186:189], v[194:197], v[112:115]
	v_mfma_f32_16x16x32_bf16 v[112:115], v[190:193], v[198:201], v[112:115]
	v_mfma_f32_16x16x32_bf16 v[96:99], v[186:189], v[202:205], v[96:99]
	v_mfma_f32_16x16x32_bf16 v[96:99], v[190:193], v[206:209], v[96:99]
	v_mfma_f32_16x16x32_bf16 v[80:83], v[186:189], v[210:213], v[80:83]
	v_mfma_f32_16x16x32_bf16 v[80:83], v[190:193], v[214:217], v[80:83]
	v_mfma_f32_16x16x32_bf16 v[64:67], v[186:189], v[218:221], v[64:67]
	v_mfma_f32_16x16x32_bf16 v[64:67], v[190:193], v[222:225], v[64:67]
	s_setprio 0
	s_barrier
; #define PG8_STAGE(bufoff, gbase, voff) do { _Pragma("unroll") for (int _i = 0; _i < 2; ++_i) \
;         __builtin_amdgcn_global_load_lds((const unsigned*)((const char*)(gbase) + (voff)[_i]), (LAS unsigned*)(lds + (bufoff) + ldsw + _i * 8192), 16, 0, 0); } while (0)
; #define PG8_LDA(dst, b, h) do { _Pragma("unroll") for (int m = 0; m < 4; ++m) _Pragma("unroll") for (int k = 0; k < 2; ++k) dst[m][k] = *(const LAS bf16x8*)(lds + PG8_SA(b, h) + aoff + m * 2048 + k * 1024); } while (0)
; #define PG8_MMA(ai, bj, At, Bt) do { __builtin_amdgcn_s_setprio(1); _Pragma("unroll") for (int m = 0; m < 4; ++m) _Pragma("unroll") for (int n = 0; n < 2; ++n) _Pragma("unroll") for (int k = 0; k < 2; ++k) \
;         acc[ai][bj][m][n] = __builtin_amdgcn_mfma_f32_16x16x32_bf16(Bt[n][k], At[m][k], acc[ai][bj][m][n], 0, 0, 0); __builtin_amdgcn_s_setprio(0); } while (0)
; #define PG8_WAIT_V(n) asm volatile("s_waitcnt vmcnt(" #n ")" ::: "memory")
; #define PG8_WAIT_L(n) asm volatile("s_waitcnt lgkmcnt(" #n ")" ::: "memory")
; #define PG8_BAR __builtin_amdgcn_s_barrier()
; #define PG8_SCHED __builtin_amdgcn_sched_barrier(0)
; template <class EpiT>
; __device__ __forceinline__ void gemm_phase(LAS unsigned char* lds, const Gemm g, const StaticOrder& S, const EpiT& E) {
;     ...
;             PG8_LDA(At, 1, 1); PG8_STAGE(PG8_SB(1, 0), b3, voffB); PG8_STAGE(PG8_SB(1, 1), b3 + hstepB, voffB); PG8_STAGE(PG8_SA(1, 0), a3, voffA);
;             PG8_WAIT_V(8); PG8_WAIT_L(0); PG8_BAR; PG8_MMA(1, 0, At, B0); PG8_MMA(1, 1, At, B1); PG8_BAR; PG8_SCHED;
;         }
;         if (wr == 0) PG8_BAR;
	s_add_i32 s20, s54, s27
	v_lshl_add_u64 v[144:145], v[144:145], 0, s[10:11]
	s_mov_b32 m0, s20
	ds_read_b128 v[194:197], v152 offset:49152
	ds_read_b128 v[198:201], v152 offset:50176
	ds_read_b128 v[202:205], v152 offset:51200
	ds_read_b128 v[206:209], v152 offset:52224
	ds_read_b128 v[210:213], v152 offset:53248
	ds_read_b128 v[214:217], v152 offset:54272
	ds_read_b128 v[218:221], v152 offset:55296
	ds_read_b128 v[222:225], v152 offset:56320
	global_load_lds_dwordx4 v[144:145], off
	s_add_i32 m0, s20, 0x2000
	s_add_u32 s18, s18, 0x84080
	v_lshl_add_u64 v[144:145], v[162:163], 0, s[10:11]
	s_addc_u32 s19, s19, 0
	s_add_i32 s20, s55, s27
	global_load_lds_dwordx4 v[144:145], off
	v_lshl_add_u64 v[144:145], s[18:19], 0, v[132:133]
	s_mov_b32 m0, s20
	s_nop 0
	global_load_lds_dwordx4 v[144:145], off
	v_lshl_add_u64 v[144:145], s[18:19], 0, v[128:129]
	s_add_i32 m0, s20, 0x2000
	s_nop 0
	global_load_lds_dwordx4 v[144:145], off
	v_lshl_add_u64 v[144:145], v[166:167], 0, s[10:11]
	s_mov_b32 m0, s41
	s_nop 0
	global_load_lds_dwordx4 v[144:145], off
	v_lshl_add_u64 v[144:145], v[226:227], 0, s[10:11]
	s_mov_b32 m0, s42
	s_nop 0
	global_load_lds_dwordx4 v[144:145], off
	s_waitcnt vmcnt(8)
	s_waitcnt lgkmcnt(0)
	s_barrier
	s_setprio 1
	s_waitcnt lgkmcnt(0)
	v_mfma_f32_16x16x32_bf16 v[60:63], v[154:157], v[194:197], v[60:63]
	v_mfma_f32_16x16x32_bf16 v[60:63], v[158:161], v[198:201], v[60:63]
	v_mfma_f32_16x16x32_bf16 v[44:47], v[154:157], v[202:205], v[44:47]
	v_mfma_f32_16x16x32_bf16 v[44:47], v[158:161], v[206:209], v[44:47]
	v_mfma_f32_16x16x32_bf16 v[28:31], v[154:157], v[210:213], v[28:31]
	v_mfma_f32_16x16x32_bf16 v[28:31], v[158:161], v[214:217], v[28:31]
	v_mfma_f32_16x16x32_bf16 v[12:15], v[154:157], v[218:221], v[12:15]
	v_mfma_f32_16x16x32_bf16 v[12:15], v[158:161], v[222:225], v[12:15]
	v_mfma_f32_16x16x32_bf16 v[56:59], v[170:173], v[194:197], v[56:59]
	v_mfma_f32_16x16x32_bf16 v[56:59], v[174:177], v[198:201], v[56:59]
	v_mfma_f32_16x16x32_bf16 v[40:43], v[170:173], v[202:205], v[40:43]
	v_mfma_f32_16x16x32_bf16 v[40:43], v[174:177], v[206:209], v[40:43]
	v_mfma_f32_16x16x32_bf16 v[24:27], v[170:173], v[210:213], v[24:27]
	v_mfma_f32_16x16x32_bf16 v[24:27], v[174:177], v[214:217], v[24:27]
	v_mfma_f32_16x16x32_bf16 v[8:11], v[170:173], v[218:221], v[8:11]
	v_mfma_f32_16x16x32_bf16 v[8:11], v[174:177], v[222:225], v[8:11]
	v_mfma_f32_16x16x32_bf16 v[52:55], v[178:181], v[194:197], v[52:55]
	v_mfma_f32_16x16x32_bf16 v[52:55], v[182:185], v[198:201], v[52:55]
	v_mfma_f32_16x16x32_bf16 v[36:39], v[178:181], v[202:205], v[36:39]
	v_mfma_f32_16x16x32_bf16 v[36:39], v[182:185], v[206:209], v[36:39]
	v_mfma_f32_16x16x32_bf16 v[20:23], v[178:181], v[210:213], v[20:23]
	v_mfma_f32_16x16x32_bf16 v[20:23], v[182:185], v[214:217], v[20:23]
	v_mfma_f32_16x16x32_bf16 v[4:7], v[178:181], v[218:221], v[4:7]
	v_mfma_f32_16x16x32_bf16 v[4:7], v[182:185], v[222:225], v[4:7]
	v_mfma_f32_16x16x32_bf16 v[48:51], v[186:189], v[194:197], v[48:51]
	v_mfma_f32_16x16x32_bf16 v[48:51], v[190:193], v[198:201], v[48:51]
	v_mfma_f32_16x16x32_bf16 v[32:35], v[186:189], v[202:205], v[32:35]
	v_mfma_f32_16x16x32_bf16 v[32:35], v[190:193], v[206:209], v[32:35]
	v_mfma_f32_16x16x32_bf16 v[16:19], v[186:189], v[210:213], v[16:19]
	v_mfma_f32_16x16x32_bf16 v[16:19], v[190:193], v[214:217], v[16:19]
	v_mfma_f32_16x16x32_bf16 v[0:3], v[186:189], v[218:221], v[0:3]
	v_mfma_f32_16x16x32_bf16 v[0:3], v[190:193], v[222:225], v[0:3]
	s_setprio 0
	s_barrier
	s_add_i32 s53, s53, 2
	s_add_u32 s16, s16, 0x100
	s_addc_u32 s17, s17, 0
	s_add_u32 s51, s51, 0x100
	s_addc_u32 s52, s52, 0
	s_cmp_gt_u32 s53, 29
	s_cbranch_scc0 .LBB0_516
	s_and_b64 vcc, exec, s[12:13]
	s_cbranch_vccz .LBB0_519
	s_barrier

; #define PG8_STAGE(bufoff, gbase, voff) do { _Pragma("unroll") for (int _i = 0; _i < 2; ++_i) \
;         __builtin_amdgcn_global_load_lds((const unsigned*)((const char*)(gbase) + (voff)[_i]), (LAS unsigned*)(lds + (bufoff) + ldsw + _i * 8192), 16, 0, 0); } while (0)
; #define PG8_LDA(dst, b, h) do { _Pragma("unroll") for (int m = 0; m < 4; ++m) _Pragma("unroll") for (int k = 0; k < 2; ++k) dst[m][k] = *(const LAS bf16x8*)(lds + PG8_SA(b, h) + aoff + m * 2048 + k * 1024); } while (0)
; #define PG8_LDB(dst, b, h) do { _Pragma("unroll") for (int n = 0; n < 2; ++n) _Pragma("unroll") for (int k = 0; k < 2; ++k) dst[n][k] = *(const LAS bf16x8*)(lds + PG8_SB(b, h) + boff + n * 2048 + k * 1024); } while (0)
; #define PG8_MMA(ai, bj, At, Bt) do { __builtin_amdgcn_s_setprio(1); _Pragma("unroll") for (int m = 0; m < 4; ++m) _Pragma("unroll") for (int n = 0; n < 2; ++n) _Pragma("unroll") for (int k = 0; k < 2; ++k) \
;         acc[ai][bj][m][n] = __builtin_amdgcn_mfma_f32_16x16x32_bf16(Bt[n][k], At[m][k], acc[ai][bj][m][n], 0, 0, 0); __builtin_amdgcn_s_setprio(0); } while (0)
; #define PG8_WAIT_V(n) asm volatile("s_waitcnt vmcnt(" #n ")" ::: "memory")
; #define PG8_WAIT_L(n) asm volatile("s_waitcnt lgkmcnt(" #n ")" ::: "memory")
; #define PG8_BAR __builtin_amdgcn_s_barrier()
; #define PG8_SCHED __builtin_amdgcn_sched_barrier(0)
; template <class EpiT>
; __device__ __forceinline__ void gemm_phase(LAS unsigned char* lds, const Gemm g, const StaticOrder& S, const EpiT& E) {
;     ...
;             const bool last = (t == nt - 2);
;             const char* a1 = cA + (size_t)(t + 1) * kstep;
;             const char* a2 = last ? nA : cA + (size_t)(t + 2) * kstep; const char* b2 = last ? nB : cB + (size_t)(t + 2) * kstep;
;             const char* a3 = a2 + kstep; const char* b3 = b2 + kstep;
;             PG8_LDB(B0, 0, 0); PG8_LDB(B1, 0, 1); PG8_SCHED; PG8_LDA(At, 0, 0); PG8_STAGE(PG8_SA(1, 1), a1 + hstepA, voffA);
;             PG8_WAIT_V(8); PG8_WAIT_L(0); PG8_BAR; PG8_MMA(0, 0, At, B0); PG8_MMA(0, 1, At, B1); PG8_BAR; PG8_SCHED;
;             PG8_LDA(At, 0, 1); PG8_STAGE(PG8_SB(0, 0), b2, voffB); PG8_STAGE(PG8_SB(0, 1), b2 + hstepB, voffB); PG8_STAGE(PG8_SA(0, 0), a2, voffA);
.LBB0_595:
	ds_read_b128 v[154:157], v150
	ds_read_b128 v[158:161], v150 offset:1024
	ds_read_b128 v[170:173], v150 offset:2048
	ds_read_b128 v[174:177], v150 offset:3072
	ds_read_b128 v[178:181], v151
	ds_read_b128 v[182:185], v151 offset:1024
	ds_read_b128 v[186:189], v151 offset:2048
	ds_read_b128 v[190:193], v151 offset:3072
	s_add_u32 s20, s18, 0xffe9c080
	s_addc_u32 s21, s19, -1
	s_cmpk_eq_i32 s55, 0x54
	s_cselect_b32 s23, s5, s21
	s_cselect_b32 s22, s4, s20
	s_cselect_b32 s21, s17, s54
	s_cselect_b32 s20, s16, s53
	v_lshl_add_u64 v[162:163], s[18:19], 0, v[138:139]
	s_add_i32 m0, s37, 0xc000
	ds_read_b128 v[194:197], v152
	ds_read_b128 v[198:201], v152 offset:1024
	ds_read_b128 v[202:205], v152 offset:2048
	ds_read_b128 v[206:209], v152 offset:3072
	ds_read_b128 v[210:213], v152 offset:4096
	ds_read_b128 v[214:217], v152 offset:5120
	ds_read_b128 v[218:221], v152 offset:6144
	ds_read_b128 v[222:225], v152 offset:7168
	global_load_lds_dwordx4 v[162:163], off
	v_lshl_add_u64 v[162:163], s[18:19], 0, v[140:141]
	s_add_i32 m0, s37, 0xe000
	s_nop 0
	global_load_lds_dwordx4 v[162:163], off
	s_waitcnt vmcnt(8)
	s_waitcnt lgkmcnt(0)
	s_barrier
	s_setprio 1
	s_waitcnt lgkmcnt(0)
	v_mfma_f32_16x16x32_bf16 v[124:127], v[154:157], v[194:197], v[124:127]
	v_mfma_f32_16x16x32_bf16 v[124:127], v[158:161], v[198:201], v[124:127]
	v_mfma_f32_16x16x32_bf16 v[108:111], v[154:157], v[202:205], v[108:111]
	v_mfma_f32_16x16x32_bf16 v[108:111], v[158:161], v[206:209], v[108:111]
	v_mfma_f32_16x16x32_bf16 v[92:95], v[154:157], v[210:213], v[92:95]
	v_mfma_f32_16x16x32_bf16 v[92:95], v[158:161], v[214:217], v[92:95]
	v_mfma_f32_16x16x32_bf16 v[76:79], v[154:157], v[218:221], v[76:79]
	v_mfma_f32_16x16x32_bf16 v[76:79], v[158:161], v[222:225], v[76:79]
	v_mfma_f32_16x16x32_bf16 v[120:123], v[170:173], v[194:197], v[120:123]
	v_mfma_f32_16x16x32_bf16 v[120:123], v[174:177], v[198:201], v[120:123]
	v_mfma_f32_16x16x32_bf16 v[104:107], v[170:173], v[202:205], v[104:107]
	v_mfma_f32_16x16x32_bf16 v[104:107], v[174:177], v[206:209], v[104:107]
	v_mfma_f32_16x16x32_bf16 v[88:91], v[170:173], v[210:213], v[88:91]
	v_mfma_f32_16x16x32_bf16 v[88:91], v[174:177], v[214:217], v[88:91]
	v_mfma_f32_16x16x32_bf16 v[72:75], v[170:173], v[218:221], v[72:75]
	v_mfma_f32_16x16x32_bf16 v[72:75], v[174:177], v[222:225], v[72:75]
	v_mfma_f32_16x16x32_bf16 v[116:119], v[178:181], v[194:197], v[116:119]
	v_mfma_f32_16x16x32_bf16 v[116:119], v[182:185], v[198:201], v[116:119]
	v_mfma_f32_16x16x32_bf16 v[100:103], v[178:181], v[202:205], v[100:103]
	v_mfma_f32_16x16x32_bf16 v[100:103], v[182:185], v[206:209], v[100:103]
	v_mfma_f32_16x16x32_bf16 v[84:87], v[178:181], v[210:213], v[84:87]
	v_mfma_f32_16x16x32_bf16 v[84:87], v[182:185], v[214:217], v[84:87]
	v_mfma_f32_16x16x32_bf16 v[68:71], v[178:181], v[218:221], v[68:71]
	v_mfma_f32_16x16x32_bf16 v[68:71], v[182:185], v[222:225], v[68:71]
	v_mfma_f32_16x16x32_bf16 v[112:115], v[186:189], v[194:197], v[112:115]
	v_mfma_f32_16x16x32_bf16 v[112:115], v[190:193], v[198:201], v[112:115]
	v_mfma_f32_16x16x32_bf16 v[96:99], v[186:189], v[202:205], v[96:99]
	v_mfma_f32_16x16x32_bf16 v[96:99], v[190:193], v[206:209], v[96:99]
	v_mfma_f32_16x16x32_bf16 v[80:83], v[186:189], v[210:213], v[80:83]
	v_mfma_f32_16x16x32_bf16 v[80:83], v[190:193], v[214:217], v[80:83]
	v_mfma_f32_16x16x32_bf16 v[64:67], v[186:189], v[218:221], v[64:67]
	v_mfma_f32_16x16x32_bf16 v[64:67], v[190:193], v[222:225], v[64:67]
	s_setprio 0
	s_barrier
	s_add_i32 s56, s46, s36
	v_lshl_add_u64 v[162:163], s[20:21], 0, v[130:131]
	s_mov_b32 m0, s56
	ds_read_b128 v[194:197], v152 offset:16384
	ds_read_b128 v[198:201], v152 offset:17408
	ds_read_b128 v[202:205], v152 offset:18432
	ds_read_b128 v[206:209], v152 offset:19456
	ds_read_b128 v[210:213], v152 offset:20480
	ds_read_b128 v[214:217], v152 offset:21504
	ds_read_b128 v[218:221], v152 offset:22528
	ds_read_b128 v[222:225], v152 offset:23552
	global_load_lds_dwordx4 v[162:163], off
	s_add_i32 m0, s56, 0x2000
	s_add_u32 s56, s20, 0x164000
	v_lshl_add_u64 v[166:167], s[20:21], 0, v[134:135]
	s_addc_u32 s57, s21, 0
	s_add_i32 s58, s47, s36
	global_load_lds_dwordx4 v[166:167], off
	v_lshl_add_u64 v[226:227], s[56:57], 0, v[130:131]
	s_mov_b32 m0, s58
	v_lshl_add_u64 v[228:229], s[22:23], 0, v[132:133]
	global_load_lds_dwordx4 v[226:227], off
	v_lshl_add_u64 v[226:227], s[56:57], 0, v[134:135]
	s_add_i32 m0, s58, 0x2000
	s_nop 0
	global_load_lds_dwordx4 v[226:227], off
	v_lshl_add_u64 v[226:227], s[22:23], 0, v[128:129]
	s_mov_b32 m0, s37
	s_nop 0
	global_load_lds_dwordx4 v[226:227], off
	s_mov_b32 m0, s38
	s_nop 0
	global_load_lds_dwordx4 v[228:229], off
	s_waitcnt vmcnt(8)
	s_waitcnt lgkmcnt(0)
	s_barrier
; #define PG8_STAGE(bufoff, gbase, voff) do { _Pragma("unroll") for (int _i = 0; _i < 2; ++_i) \
;         __builtin_amdgcn_global_load_lds((const unsigned*)((const char*)(gbase) + (voff)[_i]), (LAS unsigned*)(lds + (bufoff) + ldsw + _i * 8192), 16, 0, 0); } while (0)
; #define PG8_LDA(dst, b, h) do { _Pragma("unroll") for (int m = 0; m < 4; ++m) _Pragma("unroll") for (int k = 0; k < 2; ++k) dst[m][k] = *(const LAS bf16x8*)(lds + PG8_SA(b, h) + aoff + m * 2048 + k * 1024); } while (0)
; #define PG8_LDB(dst, b, h) do { _Pragma("unroll") for (int n = 0; n < 2; ++n) _Pragma("unroll") for (int k = 0; k < 2; ++k) dst[n][k] = *(const LAS bf16x8*)(lds + PG8_SB(b, h) + boff + n * 2048 + k * 1024); } while (0)
; #define PG8_MMA(ai, bj, At, Bt) do { __builtin_amdgcn_s_setprio(1); _Pragma("unroll") for (int m = 0; m < 4; ++m) _Pragma("unroll") for (int n = 0; n < 2; ++n) _Pragma("unroll") for (int k = 0; k < 2; ++k) \
;         acc[ai][bj][m][n] = __builtin_amdgcn_mfma_f32_16x16x32_bf16(Bt[n][k], At[m][k], acc[ai][bj][m][n], 0, 0, 0); __builtin_amdgcn_s_setprio(0); } while (0)
; #define PG8_WAIT_V(n) asm volatile("s_waitcnt vmcnt(" #n ")" ::: "memory")
; #define PG8_WAIT_L(n) asm volatile("s_waitcnt lgkmcnt(" #n ")" ::: "memory")
; #define PG8_BAR __builtin_amdgcn_s_barrier()
; #define PG8_SCHED __builtin_amdgcn_sched_barrier(0)
; template <class EpiT>
; __device__ __forceinline__ void gemm_phase(LAS unsigned char* lds, const Gemm g, const StaticOrder& S, const EpiT& E) {
;     ...
;             PG8_WAIT_V(8); PG8_WAIT_L(0); PG8_BAR; PG8_MMA(1, 0, At, B0); PG8_MMA(1, 1, At, B1); PG8_BAR; PG8_SCHED;
;             PG8_LDB(B0, 1, 0); PG8_LDB(B1, 1, 1); PG8_SCHED; PG8_LDA(At, 1, 0); PG8_STAGE(PG8_SA(0, 1), a2 + hstepA, voffA);
;             PG8_WAIT_V(8); PG8_WAIT_L(0); PG8_BAR; PG8_MMA(0, 0, At, B0); PG8_MMA(0, 1, At, B1); PG8_BAR; PG8_SCHED;
	s_setprio 1
	s_waitcnt lgkmcnt(0)
	v_mfma_f32_16x16x32_bf16 v[60:63], v[154:157], v[194:197], v[60:63]
	v_mfma_f32_16x16x32_bf16 v[60:63], v[158:161], v[198:201], v[60:63]
	v_mfma_f32_16x16x32_bf16 v[44:47], v[154:157], v[202:205], v[44:47]
	v_mfma_f32_16x16x32_bf16 v[44:47], v[158:161], v[206:209], v[44:47]
	v_mfma_f32_16x16x32_bf16 v[28:31], v[154:157], v[210:213], v[28:31]
	v_mfma_f32_16x16x32_bf16 v[28:31], v[158:161], v[214:217], v[28:31]
	v_mfma_f32_16x16x32_bf16 v[12:15], v[154:157], v[218:221], v[12:15]
	v_mfma_f32_16x16x32_bf16 v[12:15], v[158:161], v[222:225], v[12:15]
	v_mfma_f32_16x16x32_bf16 v[56:59], v[170:173], v[194:197], v[56:59]
	v_mfma_f32_16x16x32_bf16 v[56:59], v[174:177], v[198:201], v[56:59]
	v_mfma_f32_16x16x32_bf16 v[40:43], v[170:173], v[202:205], v[40:43]
	v_mfma_f32_16x16x32_bf16 v[40:43], v[174:177], v[206:209], v[40:43]
	v_mfma_f32_16x16x32_bf16 v[24:27], v[170:173], v[210:213], v[24:27]
	v_mfma_f32_16x16x32_bf16 v[24:27], v[174:177], v[214:217], v[24:27]
	v_mfma_f32_16x16x32_bf16 v[8:11], v[170:173], v[218:221], v[8:11]
	v_mfma_f32_16x16x32_bf16 v[8:11], v[174:177], v[222:225], v[8:11]
	v_mfma_f32_16x16x32_bf16 v[52:55], v[178:181], v[194:197], v[52:55]
	v_mfma_f32_16x16x32_bf16 v[52:55], v[182:185], v[198:201], v[52:55]
	v_mfma_f32_16x16x32_bf16 v[36:39], v[178:181], v[202:205], v[36:39]
	v_mfma_f32_16x16x32_bf16 v[36:39], v[182:185], v[206:209], v[36:39]
	v_mfma_f32_16x16x32_bf16 v[20:23], v[178:181], v[210:213], v[20:23]
	v_mfma_f32_16x16x32_bf16 v[20:23], v[182:185], v[214:217], v[20:23]
	v_mfma_f32_16x16x32_bf16 v[4:7], v[178:181], v[218:221], v[4:7]
	v_mfma_f32_16x16x32_bf16 v[4:7], v[182:185], v[222:225], v[4:7]
	v_mfma_f32_16x16x32_bf16 v[48:51], v[186:189], v[194:197], v[48:51]
	v_mfma_f32_16x16x32_bf16 v[48:51], v[190:193], v[198:201], v[48:51]
	v_mfma_f32_16x16x32_bf16 v[32:35], v[186:189], v[202:205], v[32:35]
	v_mfma_f32_16x16x32_bf16 v[32:35], v[190:193], v[206:209], v[32:35]
	v_mfma_f32_16x16x32_bf16 v[16:19], v[186:189], v[210:213], v[16:19]
	v_mfma_f32_16x16x32_bf16 v[16:19], v[190:193], v[214:217], v[16:19]
	v_mfma_f32_16x16x32_bf16 v[0:3], v[186:189], v[218:221], v[0:3]
	v_mfma_f32_16x16x32_bf16 v[0:3], v[190:193], v[222:225], v[0:3]
	s_setprio 0
	s_barrier
	s_add_i32 s56, 0, 0x18000
	v_add_u32_e32 v165, s56, v146
	s_add_i32 s57, 0, 0x1c000
	ds_read_b128 v[154:157], v165
	ds_read_b128 v[158:161], v165 offset:1024
	ds_read_b128 v[170:173], v165 offset:2048
	ds_read_b128 v[174:177], v165 offset:3072
	v_add_u32_e32 v165, s57, v146
	ds_read_b128 v[178:181], v165
	ds_read_b128 v[182:185], v165 offset:1024
	ds_read_b128 v[186:189], v165 offset:2048
	ds_read_b128 v[190:193], v165 offset:3072
	s_add_u32 s22, s22, 0x164000
	s_addc_u32 s23, s23, 0
	s_mov_b32 m0, s39
	v_lshl_add_u64 v[230:231], s[22:23], 0, v[128:129]
	ds_read_b128 v[194:197], v152 offset:32768
	ds_read_b128 v[198:201], v152 offset:33792
	ds_read_b128 v[202:205], v152 offset:34816
	ds_read_b128 v[206:209], v152 offset:35840
	ds_read_b128 v[210:213], v152 offset:36864
	ds_read_b128 v[214:217], v152 offset:37888
	ds_read_b128 v[218:221], v152 offset:38912
	ds_read_b128 v[222:225], v152 offset:39936
	global_load_lds_dwordx4 v[230:231], off
	v_lshl_add_u64 v[230:231], s[22:23], 0, v[132:133]
	s_mov_b32 m0, s40
	s_nop 0
	global_load_lds_dwordx4 v[230:231], off
	s_waitcnt vmcnt(8)
	s_waitcnt lgkmcnt(0)
	s_barrier
	s_setprio 1
	s_waitcnt lgkmcnt(0)
	v_mfma_f32_16x16x32_bf16 v[124:127], v[154:157], v[194:197], v[124:127]
	v_mfma_f32_16x16x32_bf16 v[124:127], v[158:161], v[198:201], v[124:127]
	v_mfma_f32_16x16x32_bf16 v[108:111], v[154:157], v[202:205], v[108:111]
	v_mfma_f32_16x16x32_bf16 v[108:111], v[158:161], v[206:209], v[108:111]
	v_mfma_f32_16x16x32_bf16 v[92:95], v[154:157], v[210:213], v[92:95]
	v_mfma_f32_16x16x32_bf16 v[92:95], v[158:161], v[214:217], v[92:95]
	v_mfma_f32_16x16x32_bf16 v[76:79], v[154:157], v[218:221], v[76:79]
	v_mfma_f32_16x16x32_bf16 v[76:79], v[158:161], v[222:225], v[76:79]
	v_mfma_f32_16x16x32_bf16 v[120:123], v[170:173], v[194:197], v[120:123]
	v_mfma_f32_16x16x32_bf16 v[120:123], v[174:177], v[198:201], v[120:123]
	v_mfma_f32_16x16x32_bf16 v[104:107], v[170:173], v[202:205], v[104:107]
	v_mfma_f32_16x16x32_bf16 v[104:107], v[174:177], v[206:209], v[104:107]
	v_mfma_f32_16x16x32_bf16 v[88:91], v[170:173], v[210:213], v[88:91]
	v_mfma_f32_16x16x32_bf16 v[88:91], v[174:177], v[214:217], v[88:91]
	v_mfma_f32_16x16x32_bf16 v[72:75], v[170:173], v[218:221], v[72:75]
	v_mfma_f32_16x16x32_bf16 v[72:75], v[174:177], v[222:225], v[72:75]
	v_mfma_f32_16x16x32_bf16 v[116:119], v[178:181], v[194:197], v[116:119]
	v_mfma_f32_16x16x32_bf16 v[116:119], v[182:185], v[198:201], v[116:119]
	v_mfma_f32_16x16x32_bf16 v[100:103], v[178:181], v[202:205], v[100:103]
	v_mfma_f32_16x16x32_bf16 v[100:103], v[182:185], v[206:209], v[100:103]
	v_mfma_f32_16x16x32_bf16 v[84:87], v[178:181], v[210:213], v[84:87]
	v_mfma_f32_16x16x32_bf16 v[84:87], v[182:185], v[214:217], v[84:87]
	v_mfma_f32_16x16x32_bf16 v[68:71], v[178:181], v[218:221], v[68:71]
	v_mfma_f32_16x16x32_bf16 v[68:71], v[182:185], v[222:225], v[68:71]
	v_mfma_f32_16x16x32_bf16 v[112:115], v[186:189], v[194:197], v[112:115]
	v_mfma_f32_16x16x32_bf16 v[112:115], v[190:193], v[198:201], v[112:115]
	v_mfma_f32_16x16x32_bf16 v[96:99], v[186:189], v[202:205], v[96:99]
	v_mfma_f32_16x16x32_bf16 v[96:99], v[190:193], v[206:209], v[96:99]
	v_mfma_f32_16x16x32_bf16 v[80:83], v[186:189], v[210:213], v[80:83]
	v_mfma_f32_16x16x32_bf16 v[80:83], v[190:193], v[214:217], v[80:83]
	v_mfma_f32_16x16x32_bf16 v[64:67], v[186:189], v[218:221], v[64:67]
	v_mfma_f32_16x16x32_bf16 v[64:67], v[190:193], v[222:225], v[64:67]
	s_setprio 0
	s_barrier
; #define PG8_STAGE(bufoff, gbase, voff) do { _Pragma("unroll") for (int _i = 0; _i < 2; ++_i) \
;         __builtin_amdgcn_global_load_lds((const unsigned*)((const char*)(gbase) + (voff)[_i]), (LAS unsigned*)(lds + (bufoff) + ldsw + _i * 8192), 16, 0, 0); } while (0)
; #define PG8_LDA(dst, b, h) do { _Pragma("unroll") for (int m = 0; m < 4; ++m) _Pragma("unroll") for (int k = 0; k < 2; ++k) dst[m][k] = *(const LAS bf16x8*)(lds + PG8_SA(b, h) + aoff + m * 2048 + k * 1024); } while (0)
; #define PG8_MMA(ai, bj, At, Bt) do { __builtin_amdgcn_s_setprio(1); _Pragma("unroll") for (int m = 0; m < 4; ++m) _Pragma("unroll") for (int n = 0; n < 2; ++n) _Pragma("unroll") for (int k = 0; k < 2; ++k) \
;         acc[ai][bj][m][n] = __builtin_amdgcn_mfma_f32_16x16x32_bf16(Bt[n][k], At[m][k], acc[ai][bj][m][n], 0, 0, 0); __builtin_amdgcn_s_setprio(0); } while (0)
; #define PG8_WAIT_V(n) asm volatile("s_waitcnt vmcnt(" #n ")" ::: "memory")
; #define PG8_WAIT_L(n) asm volatile("s_waitcnt lgkmcnt(" #n ")" ::: "memory")
; #define PG8_BAR __builtin_amdgcn_s_barrier()
; #define PG8_SCHED __builtin_amdgcn_sched_barrier(0)
; template <class EpiT>
; __device__ __forceinline__ void gemm_phase(LAS unsigned char* lds, const Gemm g, const StaticOrder& S, const EpiT& E) {
;     ...
;             PG8_LDA(At, 1, 1); PG8_STAGE(PG8_SB(1, 0), b3, voffB); PG8_STAGE(PG8_SB(1, 1), b3 + hstepB, voffB); PG8_STAGE(PG8_SA(1, 0), a3, voffA);
;             PG8_WAIT_V(8); PG8_WAIT_L(0); PG8_BAR; PG8_MMA(1, 0, At, B0); PG8_MMA(1, 1, At, B1); PG8_BAR; PG8_SCHED;
;         }
;         if (wr == 0) PG8_BAR;
	s_add_i32 s22, s56, s36
	v_lshl_add_u64 v[162:163], v[162:163], 0, s[12:13]
	s_mov_b32 m0, s22
	ds_read_b128 v[194:197], v152 offset:49152
	ds_read_b128 v[198:201], v152 offset:50176
	ds_read_b128 v[202:205], v152 offset:51200
	ds_read_b128 v[206:209], v152 offset:52224
	ds_read_b128 v[210:213], v152 offset:53248
	ds_read_b128 v[214:217], v152 offset:54272
	ds_read_b128 v[218:221], v152 offset:55296
	ds_read_b128 v[222:225], v152 offset:56320
	global_load_lds_dwordx4 v[162:163], off
	s_add_i32 m0, s22, 0x2000
	s_add_u32 s20, s20, 0x164080
	v_lshl_add_u64 v[162:163], v[166:167], 0, s[12:13]
	s_addc_u32 s21, s21, 0
	s_add_i32 s22, s57, s36
	global_load_lds_dwordx4 v[162:163], off
	v_lshl_add_u64 v[162:163], s[20:21], 0, v[130:131]
	s_mov_b32 m0, s22
	s_nop 0
	global_load_lds_dwordx4 v[162:163], off
	v_lshl_add_u64 v[162:163], s[20:21], 0, v[134:135]
	s_add_i32 m0, s22, 0x2000
	s_nop 0
	global_load_lds_dwordx4 v[162:163], off
	v_lshl_add_u64 v[162:163], v[226:227], 0, s[12:13]
	s_mov_b32 m0, s42
	s_nop 0
	global_load_lds_dwordx4 v[162:163], off
	v_lshl_add_u64 v[162:163], v[228:229], 0, s[12:13]
	s_mov_b32 m0, s43
	s_nop 0
	global_load_lds_dwordx4 v[162:163], off
	s_waitcnt vmcnt(8)
	s_waitcnt lgkmcnt(0)
	s_barrier
	s_setprio 1
	s_waitcnt lgkmcnt(0)
	v_mfma_f32_16x16x32_bf16 v[60:63], v[154:157], v[194:197], v[60:63]
	v_mfma_f32_16x16x32_bf16 v[60:63], v[158:161], v[198:201], v[60:63]
	v_mfma_f32_16x16x32_bf16 v[44:47], v[154:157], v[202:205], v[44:47]
	v_mfma_f32_16x16x32_bf16 v[44:47], v[158:161], v[206:209], v[44:47]
	v_mfma_f32_16x16x32_bf16 v[28:31], v[154:157], v[210:213], v[28:31]
	v_mfma_f32_16x16x32_bf16 v[28:31], v[158:161], v[214:217], v[28:31]
	v_mfma_f32_16x16x32_bf16 v[12:15], v[154:157], v[218:221], v[12:15]
	v_mfma_f32_16x16x32_bf16 v[12:15], v[158:161], v[222:225], v[12:15]
	v_mfma_f32_16x16x32_bf16 v[56:59], v[170:173], v[194:197], v[56:59]
	v_mfma_f32_16x16x32_bf16 v[56:59], v[174:177], v[198:201], v[56:59]
	v_mfma_f32_16x16x32_bf16 v[40:43], v[170:173], v[202:205], v[40:43]
	v_mfma_f32_16x16x32_bf16 v[40:43], v[174:177], v[206:209], v[40:43]
	v_mfma_f32_16x16x32_bf16 v[24:27], v[170:173], v[210:213], v[24:27]
	v_mfma_f32_16x16x32_bf16 v[24:27], v[174:177], v[214:217], v[24:27]
	v_mfma_f32_16x16x32_bf16 v[8:11], v[170:173], v[218:221], v[8:11]
	v_mfma_f32_16x16x32_bf16 v[8:11], v[174:177], v[222:225], v[8:11]
	v_mfma_f32_16x16x32_bf16 v[52:55], v[178:181], v[194:197], v[52:55]
	v_mfma_f32_16x16x32_bf16 v[52:55], v[182:185], v[198:201], v[52:55]
	v_mfma_f32_16x16x32_bf16 v[36:39], v[178:181], v[202:205], v[36:39]
	v_mfma_f32_16x16x32_bf16 v[36:39], v[182:185], v[206:209], v[36:39]
	v_mfma_f32_16x16x32_bf16 v[20:23], v[178:181], v[210:213], v[20:23]
	v_mfma_f32_16x16x32_bf16 v[20:23], v[182:185], v[214:217], v[20:23]
	v_mfma_f32_16x16x32_bf16 v[4:7], v[178:181], v[218:221], v[4:7]
	v_mfma_f32_16x16x32_bf16 v[4:7], v[182:185], v[222:225], v[4:7]
	v_mfma_f32_16x16x32_bf16 v[48:51], v[186:189], v[194:197], v[48:51]
	v_mfma_f32_16x16x32_bf16 v[48:51], v[190:193], v[198:201], v[48:51]
	v_mfma_f32_16x16x32_bf16 v[32:35], v[186:189], v[202:205], v[32:35]
	v_mfma_f32_16x16x32_bf16 v[32:35], v[190:193], v[206:209], v[32:35]
	v_mfma_f32_16x16x32_bf16 v[16:19], v[186:189], v[210:213], v[16:19]
	v_mfma_f32_16x16x32_bf16 v[16:19], v[190:193], v[214:217], v[16:19]
	v_mfma_f32_16x16x32_bf16 v[0:3], v[186:189], v[218:221], v[0:3]
	v_mfma_f32_16x16x32_bf16 v[0:3], v[190:193], v[222:225], v[0:3]
	s_setprio 0
	s_barrier
	s_add_i32 s55, s55, 2
	s_add_u32 s18, s18, 0x100
	s_addc_u32 s19, s19, 0
	s_add_u32 s53, s53, 0x100
	s_addc_u32 s54, s54, 0
	s_cmpk_gt_u32 s55, 0x55
	s_cbranch_scc0 .LBB0_595
	s_and_b64 vcc, exec, s[14:15]
	s_cbranch_vccz .LBB0_598
	s_barrier

; #define PG8_STAGE(bufoff, gbase, voff) do { _Pragma("unroll") for (int _i = 0; _i < 2; ++_i) \
;         __builtin_amdgcn_global_load_lds((const unsigned*)((const char*)(gbase) + (voff)[_i]), (LAS unsigned*)(lds + (bufoff) + ldsw + _i * 8192), 16, 0, 0); } while (0)
; #define PG8_LDA(dst, b, h) do { _Pragma("unroll") for (int m = 0; m < 4; ++m) _Pragma("unroll") for (int k = 0; k < 2; ++k) dst[m][k] = *(const LAS bf16x8*)(lds + PG8_SA(b, h) + aoff + m * 2048 + k * 1024); } while (0)
; #define PG8_LDB(dst, b, h) do { _Pragma("unroll") for (int n = 0; n < 2; ++n) _Pragma("unroll") for (int k = 0; k < 2; ++k) dst[n][k] = *(const LAS bf16x8*)(lds + PG8_SB(b, h) + boff + n * 2048 + k * 1024); } while (0)
; #define PG8_MMA(ai, bj, At, Bt) do { __builtin_amdgcn_s_setprio(1); _Pragma("unroll") for (int m = 0; m < 4; ++m) _Pragma("unroll") for (int n = 0; n < 2; ++n) _Pragma("unroll") for (int k = 0; k < 2; ++k) \
;         acc[ai][bj][m][n] = __builtin_amdgcn_mfma_f32_16x16x32_bf16(Bt[n][k], At[m][k], acc[ai][bj][m][n], 0, 0, 0); __builtin_amdgcn_s_setprio(0); } while (0)
; #define PG8_WAIT_V(n) asm volatile("s_waitcnt vmcnt(" #n ")" ::: "memory")
; #define PG8_WAIT_L(n) asm volatile("s_waitcnt lgkmcnt(" #n ")" ::: "memory")
; #define PG8_BAR __builtin_amdgcn_s_barrier()
; #define PG8_SCHED __builtin_amdgcn_sched_barrier(0)
; template <class EpiT>
; __device__ __forceinline__ void gemm_phase(LAS unsigned char* lds, const Gemm g, const StaticOrder& S, const EpiT& E) {
;     ...
;             const bool last = (t == nt - 2);
;             const char* a1 = cA + (size_t)(t + 1) * kstep;
;             const char* a2 = last ? nA : cA + (size_t)(t + 2) * kstep; const char* b2 = last ? nB : cB + (size_t)(t + 2) * kstep;
;             const char* a3 = a2 + kstep; const char* b3 = b2 + kstep;
;             PG8_LDB(B0, 0, 0); PG8_LDB(B1, 0, 1); PG8_SCHED; PG8_LDA(At, 0, 0); PG8_STAGE(PG8_SA(1, 1), a1 + hstepA, voffA);
;             PG8_WAIT_V(8); PG8_WAIT_L(0); PG8_BAR; PG8_MMA(0, 0, At, B0); PG8_MMA(0, 1, At, B1); PG8_BAR; PG8_SCHED;
;             PG8_LDA(At, 0, 1); PG8_STAGE(PG8_SB(0, 0), b2, voffB); PG8_STAGE(PG8_SB(0, 1), b2 + hstepB, voffB); PG8_STAGE(PG8_SA(0, 0), a2, voffA);
.LBB0_761:
	ds_read_b128 v[156:159], v160
	ds_read_b128 v[164:167], v160 offset:1024
	ds_read_b128 v[170:173], v160 offset:2048
	ds_read_b128 v[174:177], v160 offset:3072
	ds_read_b128 v[178:181], v161
	ds_read_b128 v[182:185], v161 offset:1024
	ds_read_b128 v[186:189], v161 offset:2048
	ds_read_b128 v[190:193], v161 offset:3072
	s_add_u32 s22, s20, 0xfff7c080
	s_addc_u32 s23, s21, -1
	s_cmp_eq_u32 s56, 28
	s_cselect_b32 s25, s5, s23
	s_cselect_b32 s24, s4, s22
	s_cselect_b32 s23, s19, s39
	s_cselect_b32 s22, s18, s8
	v_lshl_add_u64 v[226:227], s[20:21], 0, v[146:147]
	s_add_i32 m0, s40, 0xc000
	ds_read_b128 v[194:197], v162
	ds_read_b128 v[198:201], v162 offset:1024
	ds_read_b128 v[202:205], v162 offset:2048
	ds_read_b128 v[206:209], v162 offset:3072
	ds_read_b128 v[210:213], v162 offset:4096
	ds_read_b128 v[214:217], v162 offset:5120
	ds_read_b128 v[218:221], v162 offset:6144
	ds_read_b128 v[222:225], v162 offset:7168
	global_load_lds_dwordx4 v[226:227], off
	v_lshl_add_u64 v[226:227], s[20:21], 0, v[150:151]
	s_add_i32 m0, s40, 0xe000
	s_nop 0
	global_load_lds_dwordx4 v[226:227], off
	s_waitcnt vmcnt(8)
	s_waitcnt lgkmcnt(0)
	s_barrier
	s_setprio 1
	s_waitcnt lgkmcnt(0)
	v_mfma_f32_16x16x32_bf16 v[124:127], v[156:159], v[194:197], v[124:127]
	v_mfma_f32_16x16x32_bf16 v[124:127], v[164:167], v[198:201], v[124:127]
	v_mfma_f32_16x16x32_bf16 v[108:111], v[156:159], v[202:205], v[108:111]
	v_mfma_f32_16x16x32_bf16 v[108:111], v[164:167], v[206:209], v[108:111]
	v_mfma_f32_16x16x32_bf16 v[92:95], v[156:159], v[210:213], v[92:95]
	v_mfma_f32_16x16x32_bf16 v[92:95], v[164:167], v[214:217], v[92:95]
	v_mfma_f32_16x16x32_bf16 v[76:79], v[156:159], v[218:221], v[76:79]
	v_mfma_f32_16x16x32_bf16 v[76:79], v[164:167], v[222:225], v[76:79]
	v_mfma_f32_16x16x32_bf16 v[120:123], v[170:173], v[194:197], v[120:123]
	v_mfma_f32_16x16x32_bf16 v[120:123], v[174:177], v[198:201], v[120:123]
	v_mfma_f32_16x16x32_bf16 v[104:107], v[170:173], v[202:205], v[104:107]
	v_mfma_f32_16x16x32_bf16 v[104:107], v[174:177], v[206:209], v[104:107]
	v_mfma_f32_16x16x32_bf16 v[88:91], v[170:173], v[210:213], v[88:91]
	v_mfma_f32_16x16x32_bf16 v[88:91], v[174:177], v[214:217], v[88:91]
	v_mfma_f32_16x16x32_bf16 v[72:75], v[170:173], v[218:221], v[72:75]
	v_mfma_f32_16x16x32_bf16 v[72:75], v[174:177], v[222:225], v[72:75]
	v_mfma_f32_16x16x32_bf16 v[116:119], v[178:181], v[194:197], v[116:119]
	v_mfma_f32_16x16x32_bf16 v[116:119], v[182:185], v[198:201], v[116:119]
	v_mfma_f32_16x16x32_bf16 v[100:103], v[178:181], v[202:205], v[100:103]
	v_mfma_f32_16x16x32_bf16 v[100:103], v[182:185], v[206:209], v[100:103]
	v_mfma_f32_16x16x32_bf16 v[84:87], v[178:181], v[210:213], v[84:87]
	v_mfma_f32_16x16x32_bf16 v[84:87], v[182:185], v[214:217], v[84:87]
	v_mfma_f32_16x16x32_bf16 v[68:71], v[178:181], v[218:221], v[68:71]
	v_mfma_f32_16x16x32_bf16 v[68:71], v[182:185], v[222:225], v[68:71]
	v_mfma_f32_16x16x32_bf16 v[112:115], v[186:189], v[194:197], v[112:115]
	v_mfma_f32_16x16x32_bf16 v[112:115], v[190:193], v[198:201], v[112:115]
	v_mfma_f32_16x16x32_bf16 v[96:99], v[186:189], v[202:205], v[96:99]
	v_mfma_f32_16x16x32_bf16 v[96:99], v[190:193], v[206:209], v[96:99]
	v_mfma_f32_16x16x32_bf16 v[80:83], v[186:189], v[210:213], v[80:83]
	v_mfma_f32_16x16x32_bf16 v[80:83], v[190:193], v[214:217], v[80:83]
	v_mfma_f32_16x16x32_bf16 v[64:67], v[186:189], v[218:221], v[64:67]
	v_mfma_f32_16x16x32_bf16 v[64:67], v[190:193], v[222:225], v[64:67]
	s_setprio 0
	s_barrier
	s_add_i32 s57, s49, s37
	v_lshl_add_u64 v[226:227], s[22:23], 0, v[130:131]
	s_mov_b32 m0, s57
	ds_read_b128 v[194:197], v162 offset:16384
	ds_read_b128 v[198:201], v162 offset:17408
	ds_read_b128 v[202:205], v162 offset:18432
	ds_read_b128 v[206:209], v162 offset:19456
	ds_read_b128 v[210:213], v162 offset:20480
	ds_read_b128 v[214:217], v162 offset:21504
	ds_read_b128 v[218:221], v162 offset:22528
	ds_read_b128 v[222:225], v162 offset:23552
	global_load_lds_dwordx4 v[226:227], off
	s_add_i32 m0, s57, 0x2000
	s_add_u32 s58, s22, 0x84000
	v_lshl_add_u64 v[228:229], s[22:23], 0, v[134:135]
	s_addc_u32 s59, s23, 0
	s_add_i32 s57, s50, s37
	global_load_lds_dwordx4 v[228:229], off
	v_lshl_add_u64 v[230:231], s[58:59], 0, v[130:131]
	s_mov_b32 m0, s57
	v_lshl_add_u64 v[232:233], s[24:25], 0, v[132:133]
	global_load_lds_dwordx4 v[230:231], off
	v_lshl_add_u64 v[230:231], s[58:59], 0, v[134:135]
	s_add_i32 m0, s57, 0x2000
	s_nop 0
	global_load_lds_dwordx4 v[230:231], off
	v_lshl_add_u64 v[230:231], s[24:25], 0, v[128:129]
	s_mov_b32 m0, s40
	s_nop 0
	global_load_lds_dwordx4 v[230:231], off
	s_mov_b32 m0, s41
	s_nop 0
	global_load_lds_dwordx4 v[232:233], off
	s_waitcnt vmcnt(8)
	s_waitcnt lgkmcnt(0)
	s_barrier
; #define PG8_STAGE(bufoff, gbase, voff) do { _Pragma("unroll") for (int _i = 0; _i < 2; ++_i) \
;         __builtin_amdgcn_global_load_lds((const unsigned*)((const char*)(gbase) + (voff)[_i]), (LAS unsigned*)(lds + (bufoff) + ldsw + _i * 8192), 16, 0, 0); } while (0)
; #define PG8_LDA(dst, b, h) do { _Pragma("unroll") for (int m = 0; m < 4; ++m) _Pragma("unroll") for (int k = 0; k < 2; ++k) dst[m][k] = *(const LAS bf16x8*)(lds + PG8_SA(b, h) + aoff + m * 2048 + k * 1024); } while (0)
; #define PG8_LDB(dst, b, h) do { _Pragma("unroll") for (int n = 0; n < 2; ++n) _Pragma("unroll") for (int k = 0; k < 2; ++k) dst[n][k] = *(const LAS bf16x8*)(lds + PG8_SB(b, h) + boff + n * 2048 + k * 1024); } while (0)
; #define PG8_MMA(ai, bj, At, Bt) do { __builtin_amdgcn_s_setprio(1); _Pragma("unroll") for (int m = 0; m < 4; ++m) _Pragma("unroll") for (int n = 0; n < 2; ++n) _Pragma("unroll") for (int k = 0; k < 2; ++k) \
;         acc[ai][bj][m][n] = __builtin_amdgcn_mfma_f32_16x16x32_bf16(Bt[n][k], At[m][k], acc[ai][bj][m][n], 0, 0, 0); __builtin_amdgcn_s_setprio(0); } while (0)
; #define PG8_WAIT_V(n) asm volatile("s_waitcnt vmcnt(" #n ")" ::: "memory")
; #define PG8_WAIT_L(n) asm volatile("s_waitcnt lgkmcnt(" #n ")" ::: "memory")
; #define PG8_BAR __builtin_amdgcn_s_barrier()
; #define PG8_SCHED __builtin_amdgcn_sched_barrier(0)
; template <class EpiT>
; __device__ __forceinline__ void gemm_phase(LAS unsigned char* lds, const Gemm g, const StaticOrder& S, const EpiT& E) {
;     ...
;             PG8_WAIT_V(8); PG8_WAIT_L(0); PG8_BAR; PG8_MMA(1, 0, At, B0); PG8_MMA(1, 1, At, B1); PG8_BAR; PG8_SCHED;
;             PG8_LDB(B0, 1, 0); PG8_LDB(B1, 1, 1); PG8_SCHED; PG8_LDA(At, 1, 0); PG8_STAGE(PG8_SA(0, 1), a2 + hstepA, voffA);
;             PG8_WAIT_V(8); PG8_WAIT_L(0); PG8_BAR; PG8_MMA(0, 0, At, B0); PG8_MMA(0, 1, At, B1); PG8_BAR; PG8_SCHED;
	s_setprio 1
	s_waitcnt lgkmcnt(0)
	v_mfma_f32_16x16x32_bf16 v[60:63], v[156:159], v[194:197], v[60:63]
	v_mfma_f32_16x16x32_bf16 v[60:63], v[164:167], v[198:201], v[60:63]
	v_mfma_f32_16x16x32_bf16 v[44:47], v[156:159], v[202:205], v[44:47]
	v_mfma_f32_16x16x32_bf16 v[44:47], v[164:167], v[206:209], v[44:47]
	v_mfma_f32_16x16x32_bf16 v[28:31], v[156:159], v[210:213], v[28:31]
	v_mfma_f32_16x16x32_bf16 v[28:31], v[164:167], v[214:217], v[28:31]
	v_mfma_f32_16x16x32_bf16 v[12:15], v[156:159], v[218:221], v[12:15]
	v_mfma_f32_16x16x32_bf16 v[12:15], v[164:167], v[222:225], v[12:15]
	v_mfma_f32_16x16x32_bf16 v[56:59], v[170:173], v[194:197], v[56:59]
	v_mfma_f32_16x16x32_bf16 v[56:59], v[174:177], v[198:201], v[56:59]
	v_mfma_f32_16x16x32_bf16 v[40:43], v[170:173], v[202:205], v[40:43]
	v_mfma_f32_16x16x32_bf16 v[40:43], v[174:177], v[206:209], v[40:43]
	v_mfma_f32_16x16x32_bf16 v[24:27], v[170:173], v[210:213], v[24:27]
	v_mfma_f32_16x16x32_bf16 v[24:27], v[174:177], v[214:217], v[24:27]
	v_mfma_f32_16x16x32_bf16 v[8:11], v[170:173], v[218:221], v[8:11]
	v_mfma_f32_16x16x32_bf16 v[8:11], v[174:177], v[222:225], v[8:11]
	v_mfma_f32_16x16x32_bf16 v[52:55], v[178:181], v[194:197], v[52:55]
	v_mfma_f32_16x16x32_bf16 v[52:55], v[182:185], v[198:201], v[52:55]
	v_mfma_f32_16x16x32_bf16 v[36:39], v[178:181], v[202:205], v[36:39]
	v_mfma_f32_16x16x32_bf16 v[36:39], v[182:185], v[206:209], v[36:39]
	v_mfma_f32_16x16x32_bf16 v[20:23], v[178:181], v[210:213], v[20:23]
	v_mfma_f32_16x16x32_bf16 v[20:23], v[182:185], v[214:217], v[20:23]
	v_mfma_f32_16x16x32_bf16 v[4:7], v[178:181], v[218:221], v[4:7]
	v_mfma_f32_16x16x32_bf16 v[4:7], v[182:185], v[222:225], v[4:7]
	v_mfma_f32_16x16x32_bf16 v[48:51], v[186:189], v[194:197], v[48:51]
	v_mfma_f32_16x16x32_bf16 v[48:51], v[190:193], v[198:201], v[48:51]
	v_mfma_f32_16x16x32_bf16 v[32:35], v[186:189], v[202:205], v[32:35]
	v_mfma_f32_16x16x32_bf16 v[32:35], v[190:193], v[206:209], v[32:35]
	v_mfma_f32_16x16x32_bf16 v[16:19], v[186:189], v[210:213], v[16:19]
	v_mfma_f32_16x16x32_bf16 v[16:19], v[190:193], v[214:217], v[16:19]
	v_mfma_f32_16x16x32_bf16 v[0:3], v[186:189], v[218:221], v[0:3]
	v_mfma_f32_16x16x32_bf16 v[0:3], v[190:193], v[222:225], v[0:3]
	s_setprio 0
	s_barrier
	s_add_i32 s57, 0, 0x18000
	v_add_u32_e32 v136, s57, v149
	s_add_i32 s58, 0, 0x1c000
	ds_read_b128 v[156:159], v136
	ds_read_b128 v[164:167], v136 offset:1024
	ds_read_b128 v[170:173], v136 offset:2048
	ds_read_b128 v[174:177], v136 offset:3072
	v_add_u32_e32 v136, s58, v149
	ds_read_b128 v[178:181], v136
	ds_read_b128 v[182:185], v136 offset:1024
	ds_read_b128 v[186:189], v136 offset:2048
	ds_read_b128 v[190:193], v136 offset:3072
	s_add_u32 s24, s24, 0x84000
	s_addc_u32 s25, s25, 0
	s_mov_b32 m0, s42
	v_lshl_add_u64 v[234:235], s[24:25], 0, v[128:129]
	ds_read_b128 v[194:197], v162 offset:32768
	ds_read_b128 v[198:201], v162 offset:33792
	ds_read_b128 v[202:205], v162 offset:34816
	ds_read_b128 v[206:209], v162 offset:35840
	ds_read_b128 v[210:213], v162 offset:36864
	ds_read_b128 v[214:217], v162 offset:37888
	ds_read_b128 v[218:221], v162 offset:38912
	ds_read_b128 v[222:225], v162 offset:39936
	global_load_lds_dwordx4 v[234:235], off
	v_lshl_add_u64 v[234:235], s[24:25], 0, v[132:133]
	s_mov_b32 m0, s43
	s_nop 0
	global_load_lds_dwordx4 v[234:235], off
	s_waitcnt vmcnt(8)
	s_waitcnt lgkmcnt(0)
	s_barrier
	s_setprio 1
	s_waitcnt lgkmcnt(0)
	v_mfma_f32_16x16x32_bf16 v[124:127], v[156:159], v[194:197], v[124:127]
	v_mfma_f32_16x16x32_bf16 v[124:127], v[164:167], v[198:201], v[124:127]
	v_mfma_f32_16x16x32_bf16 v[108:111], v[156:159], v[202:205], v[108:111]
	v_mfma_f32_16x16x32_bf16 v[108:111], v[164:167], v[206:209], v[108:111]
	v_mfma_f32_16x16x32_bf16 v[92:95], v[156:159], v[210:213], v[92:95]
	v_mfma_f32_16x16x32_bf16 v[92:95], v[164:167], v[214:217], v[92:95]
	v_mfma_f32_16x16x32_bf16 v[76:79], v[156:159], v[218:221], v[76:79]
	v_mfma_f32_16x16x32_bf16 v[76:79], v[164:167], v[222:225], v[76:79]
	v_mfma_f32_16x16x32_bf16 v[120:123], v[170:173], v[194:197], v[120:123]
	v_mfma_f32_16x16x32_bf16 v[120:123], v[174:177], v[198:201], v[120:123]
	v_mfma_f32_16x16x32_bf16 v[104:107], v[170:173], v[202:205], v[104:107]
	v_mfma_f32_16x16x32_bf16 v[104:107], v[174:177], v[206:209], v[104:107]
	v_mfma_f32_16x16x32_bf16 v[88:91], v[170:173], v[210:213], v[88:91]
	v_mfma_f32_16x16x32_bf16 v[88:91], v[174:177], v[214:217], v[88:91]
	v_mfma_f32_16x16x32_bf16 v[72:75], v[170:173], v[218:221], v[72:75]
	v_mfma_f32_16x16x32_bf16 v[72:75], v[174:177], v[222:225], v[72:75]
	v_mfma_f32_16x16x32_bf16 v[116:119], v[178:181], v[194:197], v[116:119]
	v_mfma_f32_16x16x32_bf16 v[116:119], v[182:185], v[198:201], v[116:119]
	v_mfma_f32_16x16x32_bf16 v[100:103], v[178:181], v[202:205], v[100:103]
	v_mfma_f32_16x16x32_bf16 v[100:103], v[182:185], v[206:209], v[100:103]
	v_mfma_f32_16x16x32_bf16 v[84:87], v[178:181], v[210:213], v[84:87]
	v_mfma_f32_16x16x32_bf16 v[84:87], v[182:185], v[214:217], v[84:87]
	v_mfma_f32_16x16x32_bf16 v[68:71], v[178:181], v[218:221], v[68:71]
	v_mfma_f32_16x16x32_bf16 v[68:71], v[182:185], v[222:225], v[68:71]
	v_mfma_f32_16x16x32_bf16 v[112:115], v[186:189], v[194:197], v[112:115]
	v_mfma_f32_16x16x32_bf16 v[112:115], v[190:193], v[198:201], v[112:115]
	v_mfma_f32_16x16x32_bf16 v[96:99], v[186:189], v[202:205], v[96:99]
	v_mfma_f32_16x16x32_bf16 v[96:99], v[190:193], v[206:209], v[96:99]
	v_mfma_f32_16x16x32_bf16 v[80:83], v[186:189], v[210:213], v[80:83]
	v_mfma_f32_16x16x32_bf16 v[80:83], v[190:193], v[214:217], v[80:83]
	v_mfma_f32_16x16x32_bf16 v[64:67], v[186:189], v[218:221], v[64:67]
	v_mfma_f32_16x16x32_bf16 v[64:67], v[190:193], v[222:225], v[64:67]
	s_setprio 0
	s_barrier
; #define PG8_STAGE(bufoff, gbase, voff) do { _Pragma("unroll") for (int _i = 0; _i < 2; ++_i) \
;         __builtin_amdgcn_global_load_lds((const unsigned*)((const char*)(gbase) + (voff)[_i]), (LAS unsigned*)(lds + (bufoff) + ldsw + _i * 8192), 16, 0, 0); } while (0)
; #define PG8_LDA(dst, b, h) do { _Pragma("unroll") for (int m = 0; m < 4; ++m) _Pragma("unroll") for (int k = 0; k < 2; ++k) dst[m][k] = *(const LAS bf16x8*)(lds + PG8_SA(b, h) + aoff + m * 2048 + k * 1024); } while (0)
; #define PG8_MMA(ai, bj, At, Bt) do { __builtin_amdgcn_s_setprio(1); _Pragma("unroll") for (int m = 0; m < 4; ++m) _Pragma("unroll") for (int n = 0; n < 2; ++n) _Pragma("unroll") for (int k = 0; k < 2; ++k) \
;         acc[ai][bj][m][n] = __builtin_amdgcn_mfma_f32_16x16x32_bf16(Bt[n][k], At[m][k], acc[ai][bj][m][n], 0, 0, 0); __builtin_amdgcn_s_setprio(0); } while (0)
; #define PG8_WAIT_V(n) asm volatile("s_waitcnt vmcnt(" #n ")" ::: "memory")
; #define PG8_WAIT_L(n) asm volatile("s_waitcnt lgkmcnt(" #n ")" ::: "memory")
; #define PG8_BAR __builtin_amdgcn_s_barrier()
; #define PG8_SCHED __builtin_amdgcn_sched_barrier(0)
; template <class EpiT>
; __device__ __forceinline__ void gemm_phase(LAS unsigned char* lds, const Gemm g, const StaticOrder& S, const EpiT& E) {
;     ...
;             PG8_LDA(At, 1, 1); PG8_STAGE(PG8_SB(1, 0), b3, voffB); PG8_STAGE(PG8_SB(1, 1), b3 + hstepB, voffB); PG8_STAGE(PG8_SA(1, 0), a3, voffA);
;             PG8_WAIT_V(8); PG8_WAIT_L(0); PG8_BAR; PG8_MMA(1, 0, At, B0); PG8_MMA(1, 1, At, B1); PG8_BAR; PG8_SCHED;
;         }
;         if (wr == 0) PG8_BAR;
	s_add_i32 s24, s57, s37
	v_lshl_add_u64 v[226:227], v[226:227], 0, s[14:15]
	s_mov_b32 m0, s24
	ds_read_b128 v[194:197], v162 offset:49152
	ds_read_b128 v[198:201], v162 offset:50176
	ds_read_b128 v[202:205], v162 offset:51200
	ds_read_b128 v[206:209], v162 offset:52224
	ds_read_b128 v[210:213], v162 offset:53248
	ds_read_b128 v[214:217], v162 offset:54272
	ds_read_b128 v[218:221], v162 offset:55296
	ds_read_b128 v[222:225], v162 offset:56320
	global_load_lds_dwordx4 v[226:227], off
	s_add_i32 m0, s24, 0x2000
	s_add_u32 s22, s22, 0x84080
	v_lshl_add_u64 v[226:227], v[228:229], 0, s[14:15]
	s_addc_u32 s23, s23, 0
	s_add_i32 s24, s58, s37
	global_load_lds_dwordx4 v[226:227], off
	v_lshl_add_u64 v[226:227], s[22:23], 0, v[130:131]
	s_mov_b32 m0, s24
	s_nop 0
	global_load_lds_dwordx4 v[226:227], off
	v_lshl_add_u64 v[226:227], s[22:23], 0, v[134:135]
	s_add_i32 m0, s24, 0x2000
	s_nop 0
	global_load_lds_dwordx4 v[226:227], off
	v_lshl_add_u64 v[226:227], v[230:231], 0, s[14:15]
	s_mov_b32 m0, s44
	s_nop 0
	global_load_lds_dwordx4 v[226:227], off
	v_lshl_add_u64 v[226:227], v[232:233], 0, s[14:15]
	s_mov_b32 m0, s45
	s_nop 0
	global_load_lds_dwordx4 v[226:227], off
	s_waitcnt vmcnt(8)
	s_waitcnt lgkmcnt(0)
	s_barrier
	s_setprio 1
	s_waitcnt lgkmcnt(0)
	v_mfma_f32_16x16x32_bf16 v[60:63], v[156:159], v[194:197], v[60:63]
	v_mfma_f32_16x16x32_bf16 v[60:63], v[164:167], v[198:201], v[60:63]
	v_mfma_f32_16x16x32_bf16 v[44:47], v[156:159], v[202:205], v[44:47]
	v_mfma_f32_16x16x32_bf16 v[44:47], v[164:167], v[206:209], v[44:47]
	v_mfma_f32_16x16x32_bf16 v[28:31], v[156:159], v[210:213], v[28:31]
	v_mfma_f32_16x16x32_bf16 v[28:31], v[164:167], v[214:217], v[28:31]
	v_mfma_f32_16x16x32_bf16 v[12:15], v[156:159], v[218:221], v[12:15]
	v_mfma_f32_16x16x32_bf16 v[12:15], v[164:167], v[222:225], v[12:15]
	v_mfma_f32_16x16x32_bf16 v[56:59], v[170:173], v[194:197], v[56:59]
	v_mfma_f32_16x16x32_bf16 v[56:59], v[174:177], v[198:201], v[56:59]
	v_mfma_f32_16x16x32_bf16 v[40:43], v[170:173], v[202:205], v[40:43]
	v_mfma_f32_16x16x32_bf16 v[40:43], v[174:177], v[206:209], v[40:43]
	v_mfma_f32_16x16x32_bf16 v[24:27], v[170:173], v[210:213], v[24:27]
	v_mfma_f32_16x16x32_bf16 v[24:27], v[174:177], v[214:217], v[24:27]
	v_mfma_f32_16x16x32_bf16 v[8:11], v[170:173], v[218:221], v[8:11]
	v_mfma_f32_16x16x32_bf16 v[8:11], v[174:177], v[222:225], v[8:11]
	v_mfma_f32_16x16x32_bf16 v[52:55], v[178:181], v[194:197], v[52:55]
	v_mfma_f32_16x16x32_bf16 v[52:55], v[182:185], v[198:201], v[52:55]
	v_mfma_f32_16x16x32_bf16 v[36:39], v[178:181], v[202:205], v[36:39]
	v_mfma_f32_16x16x32_bf16 v[36:39], v[182:185], v[206:209], v[36:39]
	v_mfma_f32_16x16x32_bf16 v[20:23], v[178:181], v[210:213], v[20:23]
	v_mfma_f32_16x16x32_bf16 v[20:23], v[182:185], v[214:217], v[20:23]
	v_mfma_f32_16x16x32_bf16 v[4:7], v[178:181], v[218:221], v[4:7]
	v_mfma_f32_16x16x32_bf16 v[4:7], v[182:185], v[222:225], v[4:7]
	v_mfma_f32_16x16x32_bf16 v[48:51], v[186:189], v[194:197], v[48:51]
	v_mfma_f32_16x16x32_bf16 v[48:51], v[190:193], v[198:201], v[48:51]
	v_mfma_f32_16x16x32_bf16 v[32:35], v[186:189], v[202:205], v[32:35]
	v_mfma_f32_16x16x32_bf16 v[32:35], v[190:193], v[206:209], v[32:35]
	v_mfma_f32_16x16x32_bf16 v[16:19], v[186:189], v[210:213], v[16:19]
	v_mfma_f32_16x16x32_bf16 v[16:19], v[190:193], v[214:217], v[16:19]
	v_mfma_f32_16x16x32_bf16 v[0:3], v[186:189], v[218:221], v[0:3]
	v_mfma_f32_16x16x32_bf16 v[0:3], v[190:193], v[222:225], v[0:3]
	s_setprio 0
	s_barrier
	s_add_i32 s56, s56, 2
	s_add_u32 s20, s20, 0x100
	s_addc_u32 s21, s21, 0
	s_add_u32 s8, s8, 0x100
	s_addc_u32 s39, s39, 0
	s_cmp_gt_u32 s56, 29
	s_cbranch_scc0 .LBB0_761
	s_and_b64 vcc, exec, s[16:17]
	s_cbranch_vccz .LBB0_764
	s_barrier

; #define PG8_STAGE(bufoff, gbase, voff) do { _Pragma("unroll") for (int _i = 0; _i < 2; ++_i) \
;         __builtin_amdgcn_global_load_lds((const unsigned*)((const char*)(gbase) + (voff)[_i]), (LAS unsigned*)(lds + (bufoff) + ldsw + _i * 8192), 16, 0, 0); } while (0)
; #define PG8_LDA(dst, b, h) do { _Pragma("unroll") for (int m = 0; m < 4; ++m) _Pragma("unroll") for (int k = 0; k < 2; ++k) dst[m][k] = *(const LAS bf16x8*)(lds + PG8_SA(b, h) + aoff + m * 2048 + k * 1024); } while (0)
; #define PG8_LDB(dst, b, h) do { _Pragma("unroll") for (int n = 0; n < 2; ++n) _Pragma("unroll") for (int k = 0; k < 2; ++k) dst[n][k] = *(const LAS bf16x8*)(lds + PG8_SB(b, h) + boff + n * 2048 + k * 1024); } while (0)
; #define PG8_MMA(ai, bj, At, Bt) do { __builtin_amdgcn_s_setprio(1); _Pragma("unroll") for (int m = 0; m < 4; ++m) _Pragma("unroll") for (int n = 0; n < 2; ++n) _Pragma("unroll") for (int k = 0; k < 2; ++k) \
;         acc[ai][bj][m][n] = __builtin_amdgcn_mfma_f32_16x16x32_bf16(Bt[n][k], At[m][k], acc[ai][bj][m][n], 0, 0, 0); __builtin_amdgcn_s_setprio(0); } while (0)
; #define PG8_WAIT_V(n) asm volatile("s_waitcnt vmcnt(" #n ")" ::: "memory")
; #define PG8_WAIT_L(n) asm volatile("s_waitcnt lgkmcnt(" #n ")" ::: "memory")
; #define PG8_BAR __builtin_amdgcn_s_barrier()
; #define PG8_SCHED __builtin_amdgcn_sched_barrier(0)
; template <class EpiT>
; __device__ __forceinline__ void gemm_phase(LAS unsigned char* lds, const Gemm g, const StaticOrder& S, const EpiT& E) {
;     ...
;             const bool last = (t == nt - 2);
;             const char* a1 = cA + (size_t)(t + 1) * kstep;
;             const char* a2 = last ? nA : cA + (size_t)(t + 2) * kstep; const char* b2 = last ? nB : cB + (size_t)(t + 2) * kstep;
;             const char* a3 = a2 + kstep; const char* b3 = b2 + kstep;
;             PG8_LDB(B0, 0, 0); PG8_LDB(B1, 0, 1); PG8_SCHED; PG8_LDA(At, 0, 0); PG8_STAGE(PG8_SA(1, 1), a1 + hstepA, voffA);
;             PG8_WAIT_V(8); PG8_WAIT_L(0); PG8_BAR; PG8_MMA(0, 0, At, B0); PG8_MMA(0, 1, At, B1); PG8_BAR; PG8_SCHED;
;             PG8_LDA(At, 0, 1); PG8_STAGE(PG8_SB(0, 0), b2, voffB); PG8_STAGE(PG8_SB(0, 1), b2 + hstepB, voffB); PG8_STAGE(PG8_SA(0, 0), a2, voffA);
.LBB0_1032:
	ds_read_b128 v[154:157], v150
	ds_read_b128 v[158:161], v150 offset:1024
	ds_read_b128 v[162:165], v150 offset:2048
	ds_read_b128 v[170:173], v150 offset:3072
	ds_read_b128 v[174:177], v151
	ds_read_b128 v[178:181], v151 offset:1024
	ds_read_b128 v[182:185], v151 offset:2048
	ds_read_b128 v[186:189], v151 offset:3072
	s_add_u32 s20, s18, 0xfff7c080
	s_addc_u32 s21, s19, -1
	s_cmp_eq_u32 s55, 28
	s_cselect_b32 s23, s5, s21
	s_cselect_b32 s22, s4, s20
	s_cselect_b32 s21, s17, s54
	s_cselect_b32 s20, s16, s53
	v_lshl_add_u64 v[166:167], s[18:19], 0, v[138:139]
	s_add_i32 m0, s37, 0xc000
	ds_read_b128 v[190:193], v152
	ds_read_b128 v[194:197], v152 offset:1024
	ds_read_b128 v[198:201], v152 offset:2048
	ds_read_b128 v[202:205], v152 offset:3072
	ds_read_b128 v[206:209], v152 offset:4096
	ds_read_b128 v[210:213], v152 offset:5120
	ds_read_b128 v[214:217], v152 offset:6144
	ds_read_b128 v[218:221], v152 offset:7168
	global_load_lds_dwordx4 v[166:167], off
	v_lshl_add_u64 v[166:167], s[18:19], 0, v[140:141]
	s_add_i32 m0, s37, 0xe000
	s_nop 0
	global_load_lds_dwordx4 v[166:167], off
	s_waitcnt vmcnt(8)
	s_waitcnt lgkmcnt(0)
	s_barrier
	s_setprio 1
	s_waitcnt lgkmcnt(0)
	v_mfma_f32_16x16x32_bf16 v[124:127], v[154:157], v[190:193], v[124:127]
	v_mfma_f32_16x16x32_bf16 v[124:127], v[158:161], v[194:197], v[124:127]
	v_mfma_f32_16x16x32_bf16 v[108:111], v[154:157], v[198:201], v[108:111]
	v_mfma_f32_16x16x32_bf16 v[108:111], v[158:161], v[202:205], v[108:111]
	v_mfma_f32_16x16x32_bf16 v[92:95], v[154:157], v[206:209], v[92:95]
	v_mfma_f32_16x16x32_bf16 v[92:95], v[158:161], v[210:213], v[92:95]
	v_mfma_f32_16x16x32_bf16 v[76:79], v[154:157], v[214:217], v[76:79]
	v_mfma_f32_16x16x32_bf16 v[76:79], v[158:161], v[218:221], v[76:79]
	v_mfma_f32_16x16x32_bf16 v[120:123], v[162:165], v[190:193], v[120:123]
	v_mfma_f32_16x16x32_bf16 v[120:123], v[170:173], v[194:197], v[120:123]
	v_mfma_f32_16x16x32_bf16 v[104:107], v[162:165], v[198:201], v[104:107]
	v_mfma_f32_16x16x32_bf16 v[104:107], v[170:173], v[202:205], v[104:107]
	v_mfma_f32_16x16x32_bf16 v[88:91], v[162:165], v[206:209], v[88:91]
	v_mfma_f32_16x16x32_bf16 v[88:91], v[170:173], v[210:213], v[88:91]
	v_mfma_f32_16x16x32_bf16 v[72:75], v[162:165], v[214:217], v[72:75]
	v_mfma_f32_16x16x32_bf16 v[72:75], v[170:173], v[218:221], v[72:75]
	v_mfma_f32_16x16x32_bf16 v[116:119], v[174:177], v[190:193], v[116:119]
	v_mfma_f32_16x16x32_bf16 v[116:119], v[178:181], v[194:197], v[116:119]
	v_mfma_f32_16x16x32_bf16 v[100:103], v[174:177], v[198:201], v[100:103]
	v_mfma_f32_16x16x32_bf16 v[100:103], v[178:181], v[202:205], v[100:103]
	v_mfma_f32_16x16x32_bf16 v[84:87], v[174:177], v[206:209], v[84:87]
	v_mfma_f32_16x16x32_bf16 v[84:87], v[178:181], v[210:213], v[84:87]
	v_mfma_f32_16x16x32_bf16 v[68:71], v[174:177], v[214:217], v[68:71]
	v_mfma_f32_16x16x32_bf16 v[68:71], v[178:181], v[218:221], v[68:71]
	v_mfma_f32_16x16x32_bf16 v[112:115], v[182:185], v[190:193], v[112:115]
	v_mfma_f32_16x16x32_bf16 v[112:115], v[186:189], v[194:197], v[112:115]
	v_mfma_f32_16x16x32_bf16 v[96:99], v[182:185], v[198:201], v[96:99]
	v_mfma_f32_16x16x32_bf16 v[96:99], v[186:189], v[202:205], v[96:99]
	v_mfma_f32_16x16x32_bf16 v[80:83], v[182:185], v[206:209], v[80:83]
	v_mfma_f32_16x16x32_bf16 v[80:83], v[186:189], v[210:213], v[80:83]
	v_mfma_f32_16x16x32_bf16 v[64:67], v[182:185], v[214:217], v[64:67]
	v_mfma_f32_16x16x32_bf16 v[64:67], v[186:189], v[218:221], v[64:67]
	s_setprio 0
	s_barrier
	s_add_i32 s56, s46, s36
	v_lshl_add_u64 v[166:167], s[20:21], 0, v[130:131]
	s_mov_b32 m0, s56
	ds_read_b128 v[190:193], v152 offset:16384
	ds_read_b128 v[194:197], v152 offset:17408
	ds_read_b128 v[198:201], v152 offset:18432
	ds_read_b128 v[202:205], v152 offset:19456
	ds_read_b128 v[206:209], v152 offset:20480
	ds_read_b128 v[210:213], v152 offset:21504
	ds_read_b128 v[214:217], v152 offset:22528
	ds_read_b128 v[218:221], v152 offset:23552
	global_load_lds_dwordx4 v[166:167], off
	s_add_i32 m0, s56, 0x2000
	s_add_u32 s56, s20, 0x84000
	v_lshl_add_u64 v[222:223], s[20:21], 0, v[134:135]
	s_addc_u32 s57, s21, 0
	s_add_i32 s58, s47, s36
	global_load_lds_dwordx4 v[222:223], off
	v_lshl_add_u64 v[224:225], s[56:57], 0, v[130:131]
	s_mov_b32 m0, s58
	v_lshl_add_u64 v[226:227], s[22:23], 0, v[132:133]
	global_load_lds_dwordx4 v[224:225], off
	v_lshl_add_u64 v[224:225], s[56:57], 0, v[134:135]
	s_add_i32 m0, s58, 0x2000
	s_nop 0
	global_load_lds_dwordx4 v[224:225], off
	v_lshl_add_u64 v[224:225], s[22:23], 0, v[128:129]
	s_mov_b32 m0, s37
	s_nop 0
	global_load_lds_dwordx4 v[224:225], off
	s_mov_b32 m0, s38
	s_nop 0
	global_load_lds_dwordx4 v[226:227], off
	s_waitcnt vmcnt(8)
	s_waitcnt lgkmcnt(0)
	s_barrier
; #define PG8_STAGE(bufoff, gbase, voff) do { _Pragma("unroll") for (int _i = 0; _i < 2; ++_i) \
;         __builtin_amdgcn_global_load_lds((const unsigned*)((const char*)(gbase) + (voff)[_i]), (LAS unsigned*)(lds + (bufoff) + ldsw + _i * 8192), 16, 0, 0); } while (0)
; #define PG8_LDA(dst, b, h) do { _Pragma("unroll") for (int m = 0; m < 4; ++m) _Pragma("unroll") for (int k = 0; k < 2; ++k) dst[m][k] = *(const LAS bf16x8*)(lds + PG8_SA(b, h) + aoff + m * 2048 + k * 1024); } while (0)
; #define PG8_LDB(dst, b, h) do { _Pragma("unroll") for (int n = 0; n < 2; ++n) _Pragma("unroll") for (int k = 0; k < 2; ++k) dst[n][k] = *(const LAS bf16x8*)(lds + PG8_SB(b, h) + boff + n * 2048 + k * 1024); } while (0)
; #define PG8_MMA(ai, bj, At, Bt) do { __builtin_amdgcn_s_setprio(1); _Pragma("unroll") for (int m = 0; m < 4; ++m) _Pragma("unroll") for (int n = 0; n < 2; ++n) _Pragma("unroll") for (int k = 0; k < 2; ++k) \
;         acc[ai][bj][m][n] = __builtin_amdgcn_mfma_f32_16x16x32_bf16(Bt[n][k], At[m][k], acc[ai][bj][m][n], 0, 0, 0); __builtin_amdgcn_s_setprio(0); } while (0)
; #define PG8_WAIT_V(n) asm volatile("s_waitcnt vmcnt(" #n ")" ::: "memory")
; #define PG8_WAIT_L(n) asm volatile("s_waitcnt lgkmcnt(" #n ")" ::: "memory")
; #define PG8_BAR __builtin_amdgcn_s_barrier()
; #define PG8_SCHED __builtin_amdgcn_sched_barrier(0)
; template <class EpiT>
; __device__ __forceinline__ void gemm_phase(LAS unsigned char* lds, const Gemm g, const StaticOrder& S, const EpiT& E) {
;     ...
;             PG8_WAIT_V(8); PG8_WAIT_L(0); PG8_BAR; PG8_MMA(1, 0, At, B0); PG8_MMA(1, 1, At, B1); PG8_BAR; PG8_SCHED;
;             PG8_LDB(B0, 1, 0); PG8_LDB(B1, 1, 1); PG8_SCHED; PG8_LDA(At, 1, 0); PG8_STAGE(PG8_SA(0, 1), a2 + hstepA, voffA);
;             PG8_WAIT_V(8); PG8_WAIT_L(0); PG8_BAR; PG8_MMA(0, 0, At, B0); PG8_MMA(0, 1, At, B1); PG8_BAR; PG8_SCHED;
	s_setprio 1
	s_waitcnt lgkmcnt(0)
	v_mfma_f32_16x16x32_bf16 v[60:63], v[154:157], v[190:193], v[60:63]
	v_mfma_f32_16x16x32_bf16 v[60:63], v[158:161], v[194:197], v[60:63]
	v_mfma_f32_16x16x32_bf16 v[44:47], v[154:157], v[198:201], v[44:47]
	v_mfma_f32_16x16x32_bf16 v[44:47], v[158:161], v[202:205], v[44:47]
	v_mfma_f32_16x16x32_bf16 v[28:31], v[154:157], v[206:209], v[28:31]
	v_mfma_f32_16x16x32_bf16 v[28:31], v[158:161], v[210:213], v[28:31]
	v_mfma_f32_16x16x32_bf16 v[12:15], v[154:157], v[214:217], v[12:15]
	v_mfma_f32_16x16x32_bf16 v[12:15], v[158:161], v[218:221], v[12:15]
	v_mfma_f32_16x16x32_bf16 v[56:59], v[162:165], v[190:193], v[56:59]
	v_mfma_f32_16x16x32_bf16 v[56:59], v[170:173], v[194:197], v[56:59]
	v_mfma_f32_16x16x32_bf16 v[40:43], v[162:165], v[198:201], v[40:43]
	v_mfma_f32_16x16x32_bf16 v[40:43], v[170:173], v[202:205], v[40:43]
	v_mfma_f32_16x16x32_bf16 v[24:27], v[162:165], v[206:209], v[24:27]
	v_mfma_f32_16x16x32_bf16 v[24:27], v[170:173], v[210:213], v[24:27]
	v_mfma_f32_16x16x32_bf16 v[8:11], v[162:165], v[214:217], v[8:11]
	v_mfma_f32_16x16x32_bf16 v[8:11], v[170:173], v[218:221], v[8:11]
	v_mfma_f32_16x16x32_bf16 v[52:55], v[174:177], v[190:193], v[52:55]
	v_mfma_f32_16x16x32_bf16 v[52:55], v[178:181], v[194:197], v[52:55]
	v_mfma_f32_16x16x32_bf16 v[36:39], v[174:177], v[198:201], v[36:39]
	v_mfma_f32_16x16x32_bf16 v[36:39], v[178:181], v[202:205], v[36:39]
	v_mfma_f32_16x16x32_bf16 v[20:23], v[174:177], v[206:209], v[20:23]
	v_mfma_f32_16x16x32_bf16 v[20:23], v[178:181], v[210:213], v[20:23]
	v_mfma_f32_16x16x32_bf16 v[4:7], v[174:177], v[214:217], v[4:7]
	v_mfma_f32_16x16x32_bf16 v[4:7], v[178:181], v[218:221], v[4:7]
	v_mfma_f32_16x16x32_bf16 v[48:51], v[182:185], v[190:193], v[48:51]
	v_mfma_f32_16x16x32_bf16 v[48:51], v[186:189], v[194:197], v[48:51]
	v_mfma_f32_16x16x32_bf16 v[32:35], v[182:185], v[198:201], v[32:35]
	v_mfma_f32_16x16x32_bf16 v[32:35], v[186:189], v[202:205], v[32:35]
	v_mfma_f32_16x16x32_bf16 v[16:19], v[182:185], v[206:209], v[16:19]
	v_mfma_f32_16x16x32_bf16 v[16:19], v[186:189], v[210:213], v[16:19]
	v_mfma_f32_16x16x32_bf16 v[0:3], v[182:185], v[214:217], v[0:3]
	v_mfma_f32_16x16x32_bf16 v[0:3], v[186:189], v[218:221], v[0:3]
	s_setprio 0
	s_barrier
	s_add_i32 s56, 0, 0x18000
	s_add_i32 s57, 0, 0x1c000
	v_add_u32_e32 v170, s56, v146
	v_add_u32_e32 v186, s57, v146
	ds_read_b128 v[154:157], v170
	ds_read_b128 v[158:161], v170 offset:1024
	ds_read_b128 v[162:165], v170 offset:2048
	ds_read_b128 v[170:173], v170 offset:3072
	ds_read_b128 v[174:177], v186
	ds_read_b128 v[178:181], v186 offset:1024
	ds_read_b128 v[182:185], v186 offset:2048
	ds_read_b128 v[186:189], v186 offset:3072
	s_add_u32 s22, s22, 0x84000
	s_addc_u32 s23, s23, 0
	s_mov_b32 m0, s39
	v_lshl_add_u64 v[228:229], s[22:23], 0, v[128:129]
	ds_read_b128 v[190:193], v152 offset:32768
	ds_read_b128 v[194:197], v152 offset:33792
	ds_read_b128 v[198:201], v152 offset:34816
	ds_read_b128 v[202:205], v152 offset:35840
	ds_read_b128 v[206:209], v152 offset:36864
	ds_read_b128 v[210:213], v152 offset:37888
	ds_read_b128 v[214:217], v152 offset:38912
	ds_read_b128 v[218:221], v152 offset:39936
	global_load_lds_dwordx4 v[228:229], off
	v_lshl_add_u64 v[228:229], s[22:23], 0, v[132:133]
	s_mov_b32 m0, s40
	s_nop 0
	global_load_lds_dwordx4 v[228:229], off
	s_waitcnt vmcnt(8)
	s_waitcnt lgkmcnt(0)
	s_barrier
	s_setprio 1
	s_waitcnt lgkmcnt(0)
	v_mfma_f32_16x16x32_bf16 v[124:127], v[154:157], v[190:193], v[124:127]
	v_mfma_f32_16x16x32_bf16 v[124:127], v[158:161], v[194:197], v[124:127]
	v_mfma_f32_16x16x32_bf16 v[108:111], v[154:157], v[198:201], v[108:111]
	v_mfma_f32_16x16x32_bf16 v[108:111], v[158:161], v[202:205], v[108:111]
	v_mfma_f32_16x16x32_bf16 v[92:95], v[154:157], v[206:209], v[92:95]
	v_mfma_f32_16x16x32_bf16 v[92:95], v[158:161], v[210:213], v[92:95]
	v_mfma_f32_16x16x32_bf16 v[76:79], v[154:157], v[214:217], v[76:79]
	v_mfma_f32_16x16x32_bf16 v[76:79], v[158:161], v[218:221], v[76:79]
	v_mfma_f32_16x16x32_bf16 v[120:123], v[162:165], v[190:193], v[120:123]
	v_mfma_f32_16x16x32_bf16 v[120:123], v[170:173], v[194:197], v[120:123]
	v_mfma_f32_16x16x32_bf16 v[104:107], v[162:165], v[198:201], v[104:107]
	v_mfma_f32_16x16x32_bf16 v[104:107], v[170:173], v[202:205], v[104:107]
	v_mfma_f32_16x16x32_bf16 v[88:91], v[162:165], v[206:209], v[88:91]
	v_mfma_f32_16x16x32_bf16 v[88:91], v[170:173], v[210:213], v[88:91]
	v_mfma_f32_16x16x32_bf16 v[72:75], v[162:165], v[214:217], v[72:75]
	v_mfma_f32_16x16x32_bf16 v[72:75], v[170:173], v[218:221], v[72:75]
	v_mfma_f32_16x16x32_bf16 v[116:119], v[174:177], v[190:193], v[116:119]
	v_mfma_f32_16x16x32_bf16 v[116:119], v[178:181], v[194:197], v[116:119]
	v_mfma_f32_16x16x32_bf16 v[100:103], v[174:177], v[198:201], v[100:103]
	v_mfma_f32_16x16x32_bf16 v[100:103], v[178:181], v[202:205], v[100:103]
	v_mfma_f32_16x16x32_bf16 v[84:87], v[174:177], v[206:209], v[84:87]
	v_mfma_f32_16x16x32_bf16 v[84:87], v[178:181], v[210:213], v[84:87]
	v_mfma_f32_16x16x32_bf16 v[68:71], v[174:177], v[214:217], v[68:71]
	v_mfma_f32_16x16x32_bf16 v[68:71], v[178:181], v[218:221], v[68:71]
	v_mfma_f32_16x16x32_bf16 v[112:115], v[182:185], v[190:193], v[112:115]
	v_mfma_f32_16x16x32_bf16 v[112:115], v[186:189], v[194:197], v[112:115]
	v_mfma_f32_16x16x32_bf16 v[96:99], v[182:185], v[198:201], v[96:99]
	v_mfma_f32_16x16x32_bf16 v[96:99], v[186:189], v[202:205], v[96:99]
	v_mfma_f32_16x16x32_bf16 v[80:83], v[182:185], v[206:209], v[80:83]
	v_mfma_f32_16x16x32_bf16 v[80:83], v[186:189], v[210:213], v[80:83]
	v_mfma_f32_16x16x32_bf16 v[64:67], v[182:185], v[214:217], v[64:67]
	v_mfma_f32_16x16x32_bf16 v[64:67], v[186:189], v[218:221], v[64:67]
	s_setprio 0
	s_barrier
; #define PG8_STAGE(bufoff, gbase, voff) do { _Pragma("unroll") for (int _i = 0; _i < 2; ++_i) \
;         __builtin_amdgcn_global_load_lds((const unsigned*)((const char*)(gbase) + (voff)[_i]), (LAS unsigned*)(lds + (bufoff) + ldsw + _i * 8192), 16, 0, 0); } while (0)
; #define PG8_LDA(dst, b, h) do { _Pragma("unroll") for (int m = 0; m < 4; ++m) _Pragma("unroll") for (int k = 0; k < 2; ++k) dst[m][k] = *(const LAS bf16x8*)(lds + PG8_SA(b, h) + aoff + m * 2048 + k * 1024); } while (0)
; #define PG8_MMA(ai, bj, At, Bt) do { __builtin_amdgcn_s_setprio(1); _Pragma("unroll") for (int m = 0; m < 4; ++m) _Pragma("unroll") for (int n = 0; n < 2; ++n) _Pragma("unroll") for (int k = 0; k < 2; ++k) \
;         acc[ai][bj][m][n] = __builtin_amdgcn_mfma_f32_16x16x32_bf16(Bt[n][k], At[m][k], acc[ai][bj][m][n], 0, 0, 0); __builtin_amdgcn_s_setprio(0); } while (0)
; #define PG8_WAIT_V(n) asm volatile("s_waitcnt vmcnt(" #n ")" ::: "memory")
; #define PG8_WAIT_L(n) asm volatile("s_waitcnt lgkmcnt(" #n ")" ::: "memory")
; #define PG8_BAR __builtin_amdgcn_s_barrier()
; #define PG8_SCHED __builtin_amdgcn_sched_barrier(0)
; template <class EpiT>
; __device__ __forceinline__ void gemm_phase(LAS unsigned char* lds, const Gemm g, const StaticOrder& S, const EpiT& E) {
;     ...
;             PG8_LDA(At, 1, 1); PG8_STAGE(PG8_SB(1, 0), b3, voffB); PG8_STAGE(PG8_SB(1, 1), b3 + hstepB, voffB); PG8_STAGE(PG8_SA(1, 0), a3, voffA);
;             PG8_WAIT_V(8); PG8_WAIT_L(0); PG8_BAR; PG8_MMA(1, 0, At, B0); PG8_MMA(1, 1, At, B1); PG8_BAR; PG8_SCHED;
;         }
;         if (wr == 0) PG8_BAR;
	s_add_i32 s22, s56, s36
	v_lshl_add_u64 v[166:167], v[166:167], 0, s[12:13]
	s_mov_b32 m0, s22
	ds_read_b128 v[190:193], v152 offset:49152
	ds_read_b128 v[194:197], v152 offset:50176
	ds_read_b128 v[198:201], v152 offset:51200
	ds_read_b128 v[202:205], v152 offset:52224
	ds_read_b128 v[206:209], v152 offset:53248
	ds_read_b128 v[210:213], v152 offset:54272
	ds_read_b128 v[214:217], v152 offset:55296
	ds_read_b128 v[218:221], v152 offset:56320
	global_load_lds_dwordx4 v[166:167], off
	s_add_i32 m0, s22, 0x2000
	s_add_u32 s20, s20, 0x84080
	v_lshl_add_u64 v[166:167], v[222:223], 0, s[12:13]
	s_addc_u32 s21, s21, 0
	s_add_i32 s22, s57, s36
	global_load_lds_dwordx4 v[166:167], off
	v_lshl_add_u64 v[166:167], s[20:21], 0, v[130:131]
	s_mov_b32 m0, s22
	s_nop 0
	global_load_lds_dwordx4 v[166:167], off
	v_lshl_add_u64 v[166:167], s[20:21], 0, v[134:135]
	s_add_i32 m0, s22, 0x2000
	s_nop 0
	global_load_lds_dwordx4 v[166:167], off
	v_lshl_add_u64 v[166:167], v[224:225], 0, s[12:13]
	s_mov_b32 m0, s42
	s_nop 0
	global_load_lds_dwordx4 v[166:167], off
	v_lshl_add_u64 v[166:167], v[226:227], 0, s[12:13]
	s_mov_b32 m0, s43
	s_nop 0
	global_load_lds_dwordx4 v[166:167], off
	s_waitcnt vmcnt(8)
	s_waitcnt lgkmcnt(0)
	s_barrier
	s_setprio 1
	s_waitcnt lgkmcnt(0)
	v_mfma_f32_16x16x32_bf16 v[60:63], v[154:157], v[190:193], v[60:63]
	v_mfma_f32_16x16x32_bf16 v[60:63], v[158:161], v[194:197], v[60:63]
	v_mfma_f32_16x16x32_bf16 v[44:47], v[154:157], v[198:201], v[44:47]
	v_mfma_f32_16x16x32_bf16 v[44:47], v[158:161], v[202:205], v[44:47]
	v_mfma_f32_16x16x32_bf16 v[28:31], v[154:157], v[206:209], v[28:31]
	v_mfma_f32_16x16x32_bf16 v[28:31], v[158:161], v[210:213], v[28:31]
	v_mfma_f32_16x16x32_bf16 v[12:15], v[154:157], v[214:217], v[12:15]
	v_mfma_f32_16x16x32_bf16 v[12:15], v[158:161], v[218:221], v[12:15]
	v_mfma_f32_16x16x32_bf16 v[56:59], v[162:165], v[190:193], v[56:59]
	v_mfma_f32_16x16x32_bf16 v[56:59], v[170:173], v[194:197], v[56:59]
	v_mfma_f32_16x16x32_bf16 v[40:43], v[162:165], v[198:201], v[40:43]
	v_mfma_f32_16x16x32_bf16 v[40:43], v[170:173], v[202:205], v[40:43]
	v_mfma_f32_16x16x32_bf16 v[24:27], v[162:165], v[206:209], v[24:27]
	v_mfma_f32_16x16x32_bf16 v[24:27], v[170:173], v[210:213], v[24:27]
	v_mfma_f32_16x16x32_bf16 v[8:11], v[162:165], v[214:217], v[8:11]
	v_mfma_f32_16x16x32_bf16 v[8:11], v[170:173], v[218:221], v[8:11]
	v_mfma_f32_16x16x32_bf16 v[52:55], v[174:177], v[190:193], v[52:55]
	v_mfma_f32_16x16x32_bf16 v[52:55], v[178:181], v[194:197], v[52:55]
	v_mfma_f32_16x16x32_bf16 v[36:39], v[174:177], v[198:201], v[36:39]
	v_mfma_f32_16x16x32_bf16 v[36:39], v[178:181], v[202:205], v[36:39]
	v_mfma_f32_16x16x32_bf16 v[20:23], v[174:177], v[206:209], v[20:23]
	v_mfma_f32_16x16x32_bf16 v[20:23], v[178:181], v[210:213], v[20:23]
	v_mfma_f32_16x16x32_bf16 v[4:7], v[174:177], v[214:217], v[4:7]
	v_mfma_f32_16x16x32_bf16 v[4:7], v[178:181], v[218:221], v[4:7]
	v_mfma_f32_16x16x32_bf16 v[48:51], v[182:185], v[190:193], v[48:51]
	v_mfma_f32_16x16x32_bf16 v[48:51], v[186:189], v[194:197], v[48:51]
	v_mfma_f32_16x16x32_bf16 v[32:35], v[182:185], v[198:201], v[32:35]
	v_mfma_f32_16x16x32_bf16 v[32:35], v[186:189], v[202:205], v[32:35]
	v_mfma_f32_16x16x32_bf16 v[16:19], v[182:185], v[206:209], v[16:19]
	v_mfma_f32_16x16x32_bf16 v[16:19], v[186:189], v[210:213], v[16:19]
	v_mfma_f32_16x16x32_bf16 v[0:3], v[182:185], v[214:217], v[0:3]
	v_mfma_f32_16x16x32_bf16 v[0:3], v[186:189], v[218:221], v[0:3]
	s_setprio 0
	s_barrier
	s_add_i32 s55, s55, 2
	s_add_u32 s18, s18, 0x100
	s_addc_u32 s19, s19, 0
	s_add_u32 s53, s53, 0x100
	s_addc_u32 s54, s54, 0
	s_cmp_gt_u32 s55, 29
	s_cbranch_scc0 .LBB0_1032
	s_and_b64 vcc, exec, s[14:15]
	s_cbranch_vccz .LBB0_1035
	s_barrier

; #define PG8_STAGE(bufoff, gbase, voff) do { _Pragma("unroll") for (int _i = 0; _i < 2; ++_i) \
;         __builtin_amdgcn_global_load_lds((const unsigned*)((const char*)(gbase) + (voff)[_i]), (LAS unsigned*)(lds + (bufoff) + ldsw + _i * 8192), 16, 0, 0); } while (0)
; #define PG8_LDA(dst, b, h) do { _Pragma("unroll") for (int m = 0; m < 4; ++m) _Pragma("unroll") for (int k = 0; k < 2; ++k) dst[m][k] = *(const LAS bf16x8*)(lds + PG8_SA(b, h) + aoff + m * 2048 + k * 1024); } while (0)
; #define PG8_LDB(dst, b, h) do { _Pragma("unroll") for (int n = 0; n < 2; ++n) _Pragma("unroll") for (int k = 0; k < 2; ++k) dst[n][k] = *(const LAS bf16x8*)(lds + PG8_SB(b, h) + boff + n * 2048 + k * 1024); } while (0)
; #define PG8_MMA(ai, bj, At, Bt) do { __builtin_amdgcn_s_setprio(1); _Pragma("unroll") for (int m = 0; m < 4; ++m) _Pragma("unroll") for (int n = 0; n < 2; ++n) _Pragma("unroll") for (int k = 0; k < 2; ++k) \
;         acc[ai][bj][m][n] = __builtin_amdgcn_mfma_f32_16x16x32_bf16(Bt[n][k], At[m][k], acc[ai][bj][m][n], 0, 0, 0); __builtin_amdgcn_s_setprio(0); } while (0)
; #define PG8_WAIT_V(n) asm volatile("s_waitcnt vmcnt(" #n ")" ::: "memory")
; #define PG8_WAIT_L(n) asm volatile("s_waitcnt lgkmcnt(" #n ")" ::: "memory")
; #define PG8_BAR __builtin_amdgcn_s_barrier()
; #define PG8_SCHED __builtin_amdgcn_sched_barrier(0)
; template <class EpiT>
; __device__ __forceinline__ void gemm_phase(LAS unsigned char* lds, const Gemm g, const StaticOrder& S, const EpiT& E) {
;     ...
;             const char* a1 = cA + (size_t)(t + 1) * kstep;
;             const char* a2 = last ? nA : cA + (size_t)(t + 2) * kstep; const char* b2 = last ? nB : cB + (size_t)(t + 2) * kstep;
;             const char* a3 = a2 + kstep; const char* b3 = b2 + kstep;
;             PG8_LDB(B0, 0, 0); PG8_LDB(B1, 0, 1); PG8_SCHED; PG8_LDA(At, 0, 0); PG8_STAGE(PG8_SA(1, 1), a1 + hstepA, voffA);
;             PG8_WAIT_V(8); PG8_WAIT_L(0); PG8_BAR; PG8_MMA(0, 0, At, B0); PG8_MMA(0, 1, At, B1); PG8_BAR; PG8_SCHED;
;             PG8_LDA(At, 0, 1); PG8_STAGE(PG8_SB(0, 0), b2, voffB); PG8_STAGE(PG8_SB(0, 1), b2 + hstepB, voffB); PG8_STAGE(PG8_SA(0, 0), a2, voffA);
;             PG8_WAIT_V(8); PG8_WAIT_L(0); PG8_BAR; PG8_MMA(1, 0, At, B0); PG8_MMA(1, 1, At, B1); PG8_BAR; PG8_SCHED;
.LBB0_1156:
	ds_read_b128 v[154:157], v150
	ds_read_b128 v[158:161], v150 offset:1024
	ds_read_b128 v[162:165], v150 offset:2048
	ds_read_b128 v[170:173], v150 offset:3072
	ds_read_b128 v[174:177], v151
	ds_read_b128 v[178:181], v151 offset:1024
	ds_read_b128 v[182:185], v151 offset:2048
	ds_read_b128 v[186:189], v151 offset:3072
	s_add_u32 s18, s16, 0xfff7c080
	s_addc_u32 s19, s17, -1
	s_cmp_eq_u32 s53, 28
	s_cselect_b32 s21, s3, s19
	s_cselect_b32 s20, s2, s18
	s_cselect_b32 s19, s15, s52
	s_cselect_b32 s18, s14, s51
	v_lshl_add_u64 v[144:145], s[16:17], 0, v[136:137]
	s_add_i32 m0, s36, 0xc000
	ds_read_b128 v[190:193], v152
	ds_read_b128 v[194:197], v152 offset:1024
	ds_read_b128 v[198:201], v152 offset:2048
	ds_read_b128 v[202:205], v152 offset:3072
	ds_read_b128 v[206:209], v152 offset:4096
	ds_read_b128 v[210:213], v152 offset:5120
	ds_read_b128 v[214:217], v152 offset:6144
	ds_read_b128 v[218:221], v152 offset:7168
	global_load_lds_dwordx4 v[144:145], off
	v_lshl_add_u64 v[144:145], s[16:17], 0, v[138:139]
	s_add_i32 m0, s36, 0xe000
	s_nop 0
	global_load_lds_dwordx4 v[144:145], off
	s_waitcnt vmcnt(8)
	s_waitcnt lgkmcnt(0)
	s_barrier
	s_setprio 1
	s_waitcnt lgkmcnt(0)
	v_mfma_f32_16x16x32_bf16 v[124:127], v[154:157], v[190:193], v[124:127]
	v_mfma_f32_16x16x32_bf16 v[124:127], v[158:161], v[194:197], v[124:127]
	v_mfma_f32_16x16x32_bf16 v[108:111], v[154:157], v[198:201], v[108:111]
	v_mfma_f32_16x16x32_bf16 v[108:111], v[158:161], v[202:205], v[108:111]
	v_mfma_f32_16x16x32_bf16 v[92:95], v[154:157], v[206:209], v[92:95]
	v_mfma_f32_16x16x32_bf16 v[92:95], v[158:161], v[210:213], v[92:95]
	v_mfma_f32_16x16x32_bf16 v[76:79], v[154:157], v[214:217], v[76:79]
	v_mfma_f32_16x16x32_bf16 v[76:79], v[158:161], v[218:221], v[76:79]
	v_mfma_f32_16x16x32_bf16 v[120:123], v[162:165], v[190:193], v[120:123]
	v_mfma_f32_16x16x32_bf16 v[120:123], v[170:173], v[194:197], v[120:123]
	v_mfma_f32_16x16x32_bf16 v[104:107], v[162:165], v[198:201], v[104:107]
	v_mfma_f32_16x16x32_bf16 v[104:107], v[170:173], v[202:205], v[104:107]
	v_mfma_f32_16x16x32_bf16 v[88:91], v[162:165], v[206:209], v[88:91]
	v_mfma_f32_16x16x32_bf16 v[88:91], v[170:173], v[210:213], v[88:91]
	v_mfma_f32_16x16x32_bf16 v[72:75], v[162:165], v[214:217], v[72:75]
	v_mfma_f32_16x16x32_bf16 v[72:75], v[170:173], v[218:221], v[72:75]
	v_mfma_f32_16x16x32_bf16 v[116:119], v[174:177], v[190:193], v[116:119]
	v_mfma_f32_16x16x32_bf16 v[116:119], v[178:181], v[194:197], v[116:119]
	v_mfma_f32_16x16x32_bf16 v[100:103], v[174:177], v[198:201], v[100:103]
	v_mfma_f32_16x16x32_bf16 v[100:103], v[178:181], v[202:205], v[100:103]
	v_mfma_f32_16x16x32_bf16 v[84:87], v[174:177], v[206:209], v[84:87]
	v_mfma_f32_16x16x32_bf16 v[84:87], v[178:181], v[210:213], v[84:87]
	v_mfma_f32_16x16x32_bf16 v[68:71], v[174:177], v[214:217], v[68:71]
	v_mfma_f32_16x16x32_bf16 v[68:71], v[178:181], v[218:221], v[68:71]
	v_mfma_f32_16x16x32_bf16 v[112:115], v[182:185], v[190:193], v[112:115]
	v_mfma_f32_16x16x32_bf16 v[112:115], v[186:189], v[194:197], v[112:115]
	v_mfma_f32_16x16x32_bf16 v[96:99], v[182:185], v[198:201], v[96:99]
	v_mfma_f32_16x16x32_bf16 v[96:99], v[186:189], v[202:205], v[96:99]
	v_mfma_f32_16x16x32_bf16 v[80:83], v[182:185], v[206:209], v[80:83]
	v_mfma_f32_16x16x32_bf16 v[80:83], v[186:189], v[210:213], v[80:83]
	v_mfma_f32_16x16x32_bf16 v[64:67], v[182:185], v[214:217], v[64:67]
	v_mfma_f32_16x16x32_bf16 v[64:67], v[186:189], v[218:221], v[64:67]
	s_setprio 0
	s_barrier
	s_add_i32 s54, s44, s27
	v_lshl_add_u64 v[144:145], s[18:19], 0, v[132:133]
	s_mov_b32 m0, s54
	ds_read_b128 v[190:193], v152 offset:16384
	ds_read_b128 v[194:197], v152 offset:17408
	ds_read_b128 v[198:201], v152 offset:18432
	ds_read_b128 v[202:205], v152 offset:19456
	ds_read_b128 v[206:209], v152 offset:20480
	ds_read_b128 v[210:213], v152 offset:21504
	ds_read_b128 v[214:217], v152 offset:22528
	ds_read_b128 v[218:221], v152 offset:23552
	global_load_lds_dwordx4 v[144:145], off
	s_add_i32 m0, s54, 0x2000
	s_add_u32 s54, s18, 0x84000
	v_lshl_add_u64 v[166:167], s[18:19], 0, v[128:129]
	s_addc_u32 s55, s19, 0
	s_add_i32 s56, s45, s27
	global_load_lds_dwordx4 v[166:167], off
	v_lshl_add_u64 v[222:223], s[54:55], 0, v[132:133]
	s_mov_b32 m0, s56
	v_lshl_add_u64 v[224:225], s[20:21], 0, v[130:131]
	global_load_lds_dwordx4 v[222:223], off
	v_lshl_add_u64 v[222:223], s[54:55], 0, v[128:129]
	s_add_i32 m0, s56, 0x2000
	s_nop 0
	global_load_lds_dwordx4 v[222:223], off
	v_lshl_add_u64 v[222:223], s[20:21], 0, v[134:135]
	s_mov_b32 m0, s36
	s_nop 0
	global_load_lds_dwordx4 v[222:223], off
	s_mov_b32 m0, s37
	s_nop 0
	global_load_lds_dwordx4 v[224:225], off
	s_waitcnt vmcnt(8)
	s_waitcnt lgkmcnt(0)
	s_barrier
; #define PG8_STAGE(bufoff, gbase, voff) do { _Pragma("unroll") for (int _i = 0; _i < 2; ++_i) \
;         __builtin_amdgcn_global_load_lds((const unsigned*)((const char*)(gbase) + (voff)[_i]), (LAS unsigned*)(lds + (bufoff) + ldsw + _i * 8192), 16, 0, 0); } while (0)
; #define PG8_LDA(dst, b, h) do { _Pragma("unroll") for (int m = 0; m < 4; ++m) _Pragma("unroll") for (int k = 0; k < 2; ++k) dst[m][k] = *(const LAS bf16x8*)(lds + PG8_SA(b, h) + aoff + m * 2048 + k * 1024); } while (0)
; #define PG8_LDB(dst, b, h) do { _Pragma("unroll") for (int n = 0; n < 2; ++n) _Pragma("unroll") for (int k = 0; k < 2; ++k) dst[n][k] = *(const LAS bf16x8*)(lds + PG8_SB(b, h) + boff + n * 2048 + k * 1024); } while (0)
; #define PG8_MMA(ai, bj, At, Bt) do { __builtin_amdgcn_s_setprio(1); _Pragma("unroll") for (int m = 0; m < 4; ++m) _Pragma("unroll") for (int n = 0; n < 2; ++n) _Pragma("unroll") for (int k = 0; k < 2; ++k) \
;         acc[ai][bj][m][n] = __builtin_amdgcn_mfma_f32_16x16x32_bf16(Bt[n][k], At[m][k], acc[ai][bj][m][n], 0, 0, 0); __builtin_amdgcn_s_setprio(0); } while (0)
; #define PG8_WAIT_V(n) asm volatile("s_waitcnt vmcnt(" #n ")" ::: "memory")
; #define PG8_WAIT_L(n) asm volatile("s_waitcnt lgkmcnt(" #n ")" ::: "memory")
; #define PG8_BAR __builtin_amdgcn_s_barrier()
; #define PG8_SCHED __builtin_amdgcn_sched_barrier(0)
; template <class EpiT>
; __device__ __forceinline__ void gemm_phase(LAS unsigned char* lds, const Gemm g, const StaticOrder& S, const EpiT& E) {
;     ...
;             PG8_WAIT_V(8); PG8_WAIT_L(0); PG8_BAR; PG8_MMA(1, 0, At, B0); PG8_MMA(1, 1, At, B1); PG8_BAR; PG8_SCHED;
;             PG8_LDB(B0, 1, 0); PG8_LDB(B1, 1, 1); PG8_SCHED; PG8_LDA(At, 1, 0); PG8_STAGE(PG8_SA(0, 1), a2 + hstepA, voffA);
;             PG8_WAIT_V(8); PG8_WAIT_L(0); PG8_BAR; PG8_MMA(0, 0, At, B0); PG8_MMA(0, 1, At, B1); PG8_BAR; PG8_SCHED;
	s_setprio 1
	s_waitcnt lgkmcnt(0)
	v_mfma_f32_16x16x32_bf16 v[60:63], v[154:157], v[190:193], v[60:63]
	v_mfma_f32_16x16x32_bf16 v[60:63], v[158:161], v[194:197], v[60:63]
	v_mfma_f32_16x16x32_bf16 v[44:47], v[154:157], v[198:201], v[44:47]
	v_mfma_f32_16x16x32_bf16 v[44:47], v[158:161], v[202:205], v[44:47]
	v_mfma_f32_16x16x32_bf16 v[28:31], v[154:157], v[206:209], v[28:31]
	v_mfma_f32_16x16x32_bf16 v[28:31], v[158:161], v[210:213], v[28:31]
	v_mfma_f32_16x16x32_bf16 v[12:15], v[154:157], v[214:217], v[12:15]
	v_mfma_f32_16x16x32_bf16 v[12:15], v[158:161], v[218:221], v[12:15]
	v_mfma_f32_16x16x32_bf16 v[56:59], v[162:165], v[190:193], v[56:59]
	v_mfma_f32_16x16x32_bf16 v[56:59], v[170:173], v[194:197], v[56:59]
	v_mfma_f32_16x16x32_bf16 v[40:43], v[162:165], v[198:201], v[40:43]
	v_mfma_f32_16x16x32_bf16 v[40:43], v[170:173], v[202:205], v[40:43]
	v_mfma_f32_16x16x32_bf16 v[24:27], v[162:165], v[206:209], v[24:27]
	v_mfma_f32_16x16x32_bf16 v[24:27], v[170:173], v[210:213], v[24:27]
	v_mfma_f32_16x16x32_bf16 v[8:11], v[162:165], v[214:217], v[8:11]
	v_mfma_f32_16x16x32_bf16 v[8:11], v[170:173], v[218:221], v[8:11]
	v_mfma_f32_16x16x32_bf16 v[52:55], v[174:177], v[190:193], v[52:55]
	v_mfma_f32_16x16x32_bf16 v[52:55], v[178:181], v[194:197], v[52:55]
	v_mfma_f32_16x16x32_bf16 v[36:39], v[174:177], v[198:201], v[36:39]
	v_mfma_f32_16x16x32_bf16 v[36:39], v[178:181], v[202:205], v[36:39]
	v_mfma_f32_16x16x32_bf16 v[20:23], v[174:177], v[206:209], v[20:23]
	v_mfma_f32_16x16x32_bf16 v[20:23], v[178:181], v[210:213], v[20:23]
	v_mfma_f32_16x16x32_bf16 v[4:7], v[174:177], v[214:217], v[4:7]
	v_mfma_f32_16x16x32_bf16 v[4:7], v[178:181], v[218:221], v[4:7]
	v_mfma_f32_16x16x32_bf16 v[48:51], v[182:185], v[190:193], v[48:51]
	v_mfma_f32_16x16x32_bf16 v[48:51], v[186:189], v[194:197], v[48:51]
	v_mfma_f32_16x16x32_bf16 v[32:35], v[182:185], v[198:201], v[32:35]
	v_mfma_f32_16x16x32_bf16 v[32:35], v[186:189], v[202:205], v[32:35]
	v_mfma_f32_16x16x32_bf16 v[16:19], v[182:185], v[206:209], v[16:19]
	v_mfma_f32_16x16x32_bf16 v[16:19], v[186:189], v[210:213], v[16:19]
	v_mfma_f32_16x16x32_bf16 v[0:3], v[182:185], v[214:217], v[0:3]
	v_mfma_f32_16x16x32_bf16 v[0:3], v[186:189], v[218:221], v[0:3]
	s_setprio 0
	s_barrier
	s_add_i32 s54, 0, 0x18000
	v_add_u32_e32 v153, s54, v147
	s_add_i32 s55, 0, 0x1c000
	ds_read_b128 v[154:157], v153
	ds_read_b128 v[158:161], v153 offset:1024
	ds_read_b128 v[162:165], v153 offset:2048
	ds_read_b128 v[170:173], v153 offset:3072
	v_add_u32_e32 v153, s55, v147
	ds_read_b128 v[174:177], v153
	ds_read_b128 v[178:181], v153 offset:1024
	ds_read_b128 v[182:185], v153 offset:2048
	ds_read_b128 v[186:189], v153 offset:3072
	s_add_u32 s20, s20, 0x84000
	s_addc_u32 s21, s21, 0
	s_mov_b32 m0, s38
	v_lshl_add_u64 v[226:227], s[20:21], 0, v[134:135]
	ds_read_b128 v[190:193], v152 offset:32768
	ds_read_b128 v[194:197], v152 offset:33792
	ds_read_b128 v[198:201], v152 offset:34816
	ds_read_b128 v[202:205], v152 offset:35840
	ds_read_b128 v[206:209], v152 offset:36864
	ds_read_b128 v[210:213], v152 offset:37888
	ds_read_b128 v[214:217], v152 offset:38912
	ds_read_b128 v[218:221], v152 offset:39936
	global_load_lds_dwordx4 v[226:227], off
	v_lshl_add_u64 v[226:227], s[20:21], 0, v[130:131]
	s_mov_b32 m0, s39
	s_nop 0
	global_load_lds_dwordx4 v[226:227], off
	s_waitcnt vmcnt(8)
	s_waitcnt lgkmcnt(0)
	s_barrier
	s_setprio 1
	s_waitcnt lgkmcnt(0)
	v_mfma_f32_16x16x32_bf16 v[124:127], v[154:157], v[190:193], v[124:127]
	v_mfma_f32_16x16x32_bf16 v[124:127], v[158:161], v[194:197], v[124:127]
	v_mfma_f32_16x16x32_bf16 v[108:111], v[154:157], v[198:201], v[108:111]
	v_mfma_f32_16x16x32_bf16 v[108:111], v[158:161], v[202:205], v[108:111]
	v_mfma_f32_16x16x32_bf16 v[92:95], v[154:157], v[206:209], v[92:95]
	v_mfma_f32_16x16x32_bf16 v[92:95], v[158:161], v[210:213], v[92:95]
	v_mfma_f32_16x16x32_bf16 v[76:79], v[154:157], v[214:217], v[76:79]
	v_mfma_f32_16x16x32_bf16 v[76:79], v[158:161], v[218:221], v[76:79]
	v_mfma_f32_16x16x32_bf16 v[120:123], v[162:165], v[190:193], v[120:123]
	v_mfma_f32_16x16x32_bf16 v[120:123], v[170:173], v[194:197], v[120:123]
	v_mfma_f32_16x16x32_bf16 v[104:107], v[162:165], v[198:201], v[104:107]
	v_mfma_f32_16x16x32_bf16 v[104:107], v[170:173], v[202:205], v[104:107]
	v_mfma_f32_16x16x32_bf16 v[88:91], v[162:165], v[206:209], v[88:91]
	v_mfma_f32_16x16x32_bf16 v[88:91], v[170:173], v[210:213], v[88:91]
	v_mfma_f32_16x16x32_bf16 v[72:75], v[162:165], v[214:217], v[72:75]
	v_mfma_f32_16x16x32_bf16 v[72:75], v[170:173], v[218:221], v[72:75]
	v_mfma_f32_16x16x32_bf16 v[116:119], v[174:177], v[190:193], v[116:119]
	v_mfma_f32_16x16x32_bf16 v[116:119], v[178:181], v[194:197], v[116:119]
	v_mfma_f32_16x16x32_bf16 v[100:103], v[174:177], v[198:201], v[100:103]
	v_mfma_f32_16x16x32_bf16 v[100:103], v[178:181], v[202:205], v[100:103]
	v_mfma_f32_16x16x32_bf16 v[84:87], v[174:177], v[206:209], v[84:87]
	v_mfma_f32_16x16x32_bf16 v[84:87], v[178:181], v[210:213], v[84:87]
	v_mfma_f32_16x16x32_bf16 v[68:71], v[174:177], v[214:217], v[68:71]
	v_mfma_f32_16x16x32_bf16 v[68:71], v[178:181], v[218:221], v[68:71]
	v_mfma_f32_16x16x32_bf16 v[112:115], v[182:185], v[190:193], v[112:115]
	v_mfma_f32_16x16x32_bf16 v[112:115], v[186:189], v[194:197], v[112:115]
	v_mfma_f32_16x16x32_bf16 v[96:99], v[182:185], v[198:201], v[96:99]
	v_mfma_f32_16x16x32_bf16 v[96:99], v[186:189], v[202:205], v[96:99]
	v_mfma_f32_16x16x32_bf16 v[80:83], v[182:185], v[206:209], v[80:83]
	v_mfma_f32_16x16x32_bf16 v[80:83], v[186:189], v[210:213], v[80:83]
	v_mfma_f32_16x16x32_bf16 v[64:67], v[182:185], v[214:217], v[64:67]
	v_mfma_f32_16x16x32_bf16 v[64:67], v[186:189], v[218:221], v[64:67]
	s_setprio 0
	s_barrier
; #define PG8_STAGE(bufoff, gbase, voff) do { _Pragma("unroll") for (int _i = 0; _i < 2; ++_i) \
;         __builtin_amdgcn_global_load_lds((const unsigned*)((const char*)(gbase) + (voff)[_i]), (LAS unsigned*)(lds + (bufoff) + ldsw + _i * 8192), 16, 0, 0); } while (0)
; #define PG8_LDA(dst, b, h) do { _Pragma("unroll") for (int m = 0; m < 4; ++m) _Pragma("unroll") for (int k = 0; k < 2; ++k) dst[m][k] = *(const LAS bf16x8*)(lds + PG8_SA(b, h) + aoff + m * 2048 + k * 1024); } while (0)
; #define PG8_MMA(ai, bj, At, Bt) do { __builtin_amdgcn_s_setprio(1); _Pragma("unroll") for (int m = 0; m < 4; ++m) _Pragma("unroll") for (int n = 0; n < 2; ++n) _Pragma("unroll") for (int k = 0; k < 2; ++k) \
;         acc[ai][bj][m][n] = __builtin_amdgcn_mfma_f32_16x16x32_bf16(Bt[n][k], At[m][k], acc[ai][bj][m][n], 0, 0, 0); __builtin_amdgcn_s_setprio(0); } while (0)
; #define PG8_WAIT_V(n) asm volatile("s_waitcnt vmcnt(" #n ")" ::: "memory")
; #define PG8_WAIT_L(n) asm volatile("s_waitcnt lgkmcnt(" #n ")" ::: "memory")
; #define PG8_BAR __builtin_amdgcn_s_barrier()
; #define PG8_SCHED __builtin_amdgcn_sched_barrier(0)
; template <class EpiT>
; __device__ __forceinline__ void gemm_phase(LAS unsigned char* lds, const Gemm g, const StaticOrder& S, const EpiT& E) {
;     ...
;             PG8_LDA(At, 1, 1); PG8_STAGE(PG8_SB(1, 0), b3, voffB); PG8_STAGE(PG8_SB(1, 1), b3 + hstepB, voffB); PG8_STAGE(PG8_SA(1, 0), a3, voffA);
;             PG8_WAIT_V(8); PG8_WAIT_L(0); PG8_BAR; PG8_MMA(1, 0, At, B0); PG8_MMA(1, 1, At, B1); PG8_BAR; PG8_SCHED;
;         }
;         if (wr == 0) PG8_BAR;
	s_add_i32 s20, s54, s27
	v_lshl_add_u64 v[144:145], v[144:145], 0, s[10:11]
	s_mov_b32 m0, s20
	ds_read_b128 v[190:193], v152 offset:49152
	ds_read_b128 v[194:197], v152 offset:50176
	ds_read_b128 v[198:201], v152 offset:51200
	ds_read_b128 v[202:205], v152 offset:52224
	ds_read_b128 v[206:209], v152 offset:53248
	ds_read_b128 v[210:213], v152 offset:54272
	ds_read_b128 v[214:217], v152 offset:55296
	ds_read_b128 v[218:221], v152 offset:56320
	global_load_lds_dwordx4 v[144:145], off
	s_add_i32 m0, s20, 0x2000
	s_add_u32 s18, s18, 0x84080
	v_lshl_add_u64 v[144:145], v[166:167], 0, s[10:11]
	s_addc_u32 s19, s19, 0
	s_add_i32 s20, s55, s27
	global_load_lds_dwordx4 v[144:145], off
	v_lshl_add_u64 v[144:145], s[18:19], 0, v[132:133]
	s_mov_b32 m0, s20
	s_nop 0
	global_load_lds_dwordx4 v[144:145], off
	v_lshl_add_u64 v[144:145], s[18:19], 0, v[128:129]
	s_add_i32 m0, s20, 0x2000
	s_nop 0
	global_load_lds_dwordx4 v[144:145], off
	v_lshl_add_u64 v[144:145], v[222:223], 0, s[10:11]
	s_mov_b32 m0, s41
	s_nop 0
	global_load_lds_dwordx4 v[144:145], off
	v_lshl_add_u64 v[144:145], v[224:225], 0, s[10:11]
	s_mov_b32 m0, s42
	s_nop 0
	global_load_lds_dwordx4 v[144:145], off
	s_waitcnt vmcnt(8)
	s_waitcnt lgkmcnt(0)
	s_barrier
	s_setprio 1
	s_waitcnt lgkmcnt(0)
	v_mfma_f32_16x16x32_bf16 v[60:63], v[154:157], v[190:193], v[60:63]
	v_mfma_f32_16x16x32_bf16 v[60:63], v[158:161], v[194:197], v[60:63]
	v_mfma_f32_16x16x32_bf16 v[44:47], v[154:157], v[198:201], v[44:47]
	v_mfma_f32_16x16x32_bf16 v[44:47], v[158:161], v[202:205], v[44:47]
	v_mfma_f32_16x16x32_bf16 v[28:31], v[154:157], v[206:209], v[28:31]
	v_mfma_f32_16x16x32_bf16 v[28:31], v[158:161], v[210:213], v[28:31]
	v_mfma_f32_16x16x32_bf16 v[12:15], v[154:157], v[214:217], v[12:15]
	v_mfma_f32_16x16x32_bf16 v[12:15], v[158:161], v[218:221], v[12:15]
	v_mfma_f32_16x16x32_bf16 v[56:59], v[162:165], v[190:193], v[56:59]
	v_mfma_f32_16x16x32_bf16 v[56:59], v[170:173], v[194:197], v[56:59]
	v_mfma_f32_16x16x32_bf16 v[40:43], v[162:165], v[198:201], v[40:43]
	v_mfma_f32_16x16x32_bf16 v[40:43], v[170:173], v[202:205], v[40:43]
	v_mfma_f32_16x16x32_bf16 v[24:27], v[162:165], v[206:209], v[24:27]
	v_mfma_f32_16x16x32_bf16 v[24:27], v[170:173], v[210:213], v[24:27]
	v_mfma_f32_16x16x32_bf16 v[8:11], v[162:165], v[214:217], v[8:11]
	v_mfma_f32_16x16x32_bf16 v[8:11], v[170:173], v[218:221], v[8:11]
	v_mfma_f32_16x16x32_bf16 v[52:55], v[174:177], v[190:193], v[52:55]
	v_mfma_f32_16x16x32_bf16 v[52:55], v[178:181], v[194:197], v[52:55]
	v_mfma_f32_16x16x32_bf16 v[36:39], v[174:177], v[198:201], v[36:39]
	v_mfma_f32_16x16x32_bf16 v[36:39], v[178:181], v[202:205], v[36:39]
	v_mfma_f32_16x16x32_bf16 v[20:23], v[174:177], v[206:209], v[20:23]
	v_mfma_f32_16x16x32_bf16 v[20:23], v[178:181], v[210:213], v[20:23]
	v_mfma_f32_16x16x32_bf16 v[4:7], v[174:177], v[214:217], v[4:7]
	v_mfma_f32_16x16x32_bf16 v[4:7], v[178:181], v[218:221], v[4:7]
	v_mfma_f32_16x16x32_bf16 v[48:51], v[182:185], v[190:193], v[48:51]
	v_mfma_f32_16x16x32_bf16 v[48:51], v[186:189], v[194:197], v[48:51]
	v_mfma_f32_16x16x32_bf16 v[32:35], v[182:185], v[198:201], v[32:35]
	v_mfma_f32_16x16x32_bf16 v[32:35], v[186:189], v[202:205], v[32:35]
	v_mfma_f32_16x16x32_bf16 v[16:19], v[182:185], v[206:209], v[16:19]
	v_mfma_f32_16x16x32_bf16 v[16:19], v[186:189], v[210:213], v[16:19]
	v_mfma_f32_16x16x32_bf16 v[0:3], v[182:185], v[214:217], v[0:3]
	v_mfma_f32_16x16x32_bf16 v[0:3], v[186:189], v[218:221], v[0:3]
	s_setprio 0
	s_barrier
	s_add_i32 s53, s53, 2
	s_add_u32 s16, s16, 0x100
	s_addc_u32 s17, s17, 0
	s_add_u32 s51, s51, 0x100
	s_addc_u32 s52, s52, 0
	s_cmp_gt_u32 s53, 29
	s_cbranch_scc0 .LBB0_1156
	s_and_b64 vcc, exec, s[12:13]
	s_cbranch_vccz .LBB0_1159
	s_barrier

; #define PG8_STAGE(bufoff, gbase, voff) do { _Pragma("unroll") for (int _i = 0; _i < 2; ++_i) \
;         __builtin_amdgcn_global_load_lds((const unsigned*)((const char*)(gbase) + (voff)[_i]), (LAS unsigned*)(lds + (bufoff) + ldsw + _i * 8192), 16, 0, 0); } while (0)
; #define PG8_LDA(dst, b, h) do { _Pragma("unroll") for (int m = 0; m < 4; ++m) _Pragma("unroll") for (int k = 0; k < 2; ++k) dst[m][k] = *(const LAS bf16x8*)(lds + PG8_SA(b, h) + aoff + m * 2048 + k * 1024); } while (0)
; #define PG8_LDB(dst, b, h) do { _Pragma("unroll") for (int n = 0; n < 2; ++n) _Pragma("unroll") for (int k = 0; k < 2; ++k) dst[n][k] = *(const LAS bf16x8*)(lds + PG8_SB(b, h) + boff + n * 2048 + k * 1024); } while (0)
; #define PG8_MMA(ai, bj, At, Bt) do { __builtin_amdgcn_s_setprio(1); _Pragma("unroll") for (int m = 0; m < 4; ++m) _Pragma("unroll") for (int n = 0; n < 2; ++n) _Pragma("unroll") for (int k = 0; k < 2; ++k) \
;         acc[ai][bj][m][n] = __builtin_amdgcn_mfma_f32_16x16x32_bf16(Bt[n][k], At[m][k], acc[ai][bj][m][n], 0, 0, 0); __builtin_amdgcn_s_setprio(0); } while (0)
; #define PG8_WAIT_V(n) asm volatile("s_waitcnt vmcnt(" #n ")" ::: "memory")
; #define PG8_WAIT_L(n) asm volatile("s_waitcnt lgkmcnt(" #n ")" ::: "memory")
; #define PG8_BAR __builtin_amdgcn_s_barrier()
; #define PG8_SCHED __builtin_amdgcn_sched_barrier(0)
; template <class EpiT>
; __device__ __forceinline__ void gemm_phase(LAS unsigned char* lds, const Gemm g, const StaticOrder& S, const EpiT& E) {
;     ...
;             const char* a1 = cA + (size_t)(t + 1) * kstep;
;             const char* a2 = last ? nA : cA + (size_t)(t + 2) * kstep; const char* b2 = last ? nB : cB + (size_t)(t + 2) * kstep;
;             const char* a3 = a2 + kstep; const char* b3 = b2 + kstep;
;             PG8_LDB(B0, 0, 0); PG8_LDB(B1, 0, 1); PG8_SCHED; PG8_LDA(At, 0, 0); PG8_STAGE(PG8_SA(1, 1), a1 + hstepA, voffA);
;             PG8_WAIT_V(8); PG8_WAIT_L(0); PG8_BAR; PG8_MMA(0, 0, At, B0); PG8_MMA(0, 1, At, B1); PG8_BAR; PG8_SCHED;
;             PG8_LDA(At, 0, 1); PG8_STAGE(PG8_SB(0, 0), b2, voffB); PG8_STAGE(PG8_SB(0, 1), b2 + hstepB, voffB); PG8_STAGE(PG8_SA(0, 0), a2, voffA);
;             PG8_WAIT_V(8); PG8_WAIT_L(0); PG8_BAR; PG8_MMA(1, 0, At, B0); PG8_MMA(1, 1, At, B1); PG8_BAR; PG8_SCHED;
.LBB0_1235:
	ds_read_b128 v[154:157], v150
	ds_read_b128 v[158:161], v150 offset:1024
	ds_read_b128 v[162:165], v150 offset:2048
	ds_read_b128 v[170:173], v150 offset:3072
	ds_read_b128 v[174:177], v151
	ds_read_b128 v[178:181], v151 offset:1024
	ds_read_b128 v[182:185], v151 offset:2048
	ds_read_b128 v[186:189], v151 offset:3072
	s_add_u32 s20, s18, 0xffe9c080
	s_addc_u32 s21, s19, -1
	s_cmpk_eq_i32 s55, 0x54
	s_cselect_b32 s23, s5, s21
	s_cselect_b32 s22, s4, s20
	s_cselect_b32 s21, s17, s54
	s_cselect_b32 s20, s16, s53
	v_lshl_add_u64 v[166:167], s[18:19], 0, v[138:139]
	s_add_i32 m0, s37, 0xc000
	ds_read_b128 v[190:193], v152
	ds_read_b128 v[194:197], v152 offset:1024
	ds_read_b128 v[198:201], v152 offset:2048
	ds_read_b128 v[202:205], v152 offset:3072
	ds_read_b128 v[206:209], v152 offset:4096
	ds_read_b128 v[210:213], v152 offset:5120
	ds_read_b128 v[214:217], v152 offset:6144
	ds_read_b128 v[218:221], v152 offset:7168
	global_load_lds_dwordx4 v[166:167], off
	v_lshl_add_u64 v[166:167], s[18:19], 0, v[140:141]
	s_add_i32 m0, s37, 0xe000
	s_nop 0
	global_load_lds_dwordx4 v[166:167], off
	s_waitcnt vmcnt(8)
	s_waitcnt lgkmcnt(0)
	s_barrier
	s_setprio 1
	s_waitcnt lgkmcnt(0)
	v_mfma_f32_16x16x32_bf16 v[124:127], v[154:157], v[190:193], v[124:127]
	v_mfma_f32_16x16x32_bf16 v[124:127], v[158:161], v[194:197], v[124:127]
	v_mfma_f32_16x16x32_bf16 v[108:111], v[154:157], v[198:201], v[108:111]
	v_mfma_f32_16x16x32_bf16 v[108:111], v[158:161], v[202:205], v[108:111]
	v_mfma_f32_16x16x32_bf16 v[92:95], v[154:157], v[206:209], v[92:95]
	v_mfma_f32_16x16x32_bf16 v[92:95], v[158:161], v[210:213], v[92:95]
	v_mfma_f32_16x16x32_bf16 v[76:79], v[154:157], v[214:217], v[76:79]
	v_mfma_f32_16x16x32_bf16 v[76:79], v[158:161], v[218:221], v[76:79]
	v_mfma_f32_16x16x32_bf16 v[120:123], v[162:165], v[190:193], v[120:123]
	v_mfma_f32_16x16x32_bf16 v[120:123], v[170:173], v[194:197], v[120:123]
	v_mfma_f32_16x16x32_bf16 v[104:107], v[162:165], v[198:201], v[104:107]
	v_mfma_f32_16x16x32_bf16 v[104:107], v[170:173], v[202:205], v[104:107]
	v_mfma_f32_16x16x32_bf16 v[88:91], v[162:165], v[206:209], v[88:91]
	v_mfma_f32_16x16x32_bf16 v[88:91], v[170:173], v[210:213], v[88:91]
	v_mfma_f32_16x16x32_bf16 v[72:75], v[162:165], v[214:217], v[72:75]
	v_mfma_f32_16x16x32_bf16 v[72:75], v[170:173], v[218:221], v[72:75]
	v_mfma_f32_16x16x32_bf16 v[116:119], v[174:177], v[190:193], v[116:119]
	v_mfma_f32_16x16x32_bf16 v[116:119], v[178:181], v[194:197], v[116:119]
	v_mfma_f32_16x16x32_bf16 v[100:103], v[174:177], v[198:201], v[100:103]
	v_mfma_f32_16x16x32_bf16 v[100:103], v[178:181], v[202:205], v[100:103]
	v_mfma_f32_16x16x32_bf16 v[84:87], v[174:177], v[206:209], v[84:87]
	v_mfma_f32_16x16x32_bf16 v[84:87], v[178:181], v[210:213], v[84:87]
	v_mfma_f32_16x16x32_bf16 v[68:71], v[174:177], v[214:217], v[68:71]
	v_mfma_f32_16x16x32_bf16 v[68:71], v[178:181], v[218:221], v[68:71]
	v_mfma_f32_16x16x32_bf16 v[112:115], v[182:185], v[190:193], v[112:115]
	v_mfma_f32_16x16x32_bf16 v[112:115], v[186:189], v[194:197], v[112:115]
	v_mfma_f32_16x16x32_bf16 v[96:99], v[182:185], v[198:201], v[96:99]
	v_mfma_f32_16x16x32_bf16 v[96:99], v[186:189], v[202:205], v[96:99]
	v_mfma_f32_16x16x32_bf16 v[80:83], v[182:185], v[206:209], v[80:83]
	v_mfma_f32_16x16x32_bf16 v[80:83], v[186:189], v[210:213], v[80:83]
	v_mfma_f32_16x16x32_bf16 v[64:67], v[182:185], v[214:217], v[64:67]
	v_mfma_f32_16x16x32_bf16 v[64:67], v[186:189], v[218:221], v[64:67]
	s_setprio 0
	s_barrier
	s_add_i32 s56, s46, s36
	v_lshl_add_u64 v[166:167], s[20:21], 0, v[130:131]
	s_mov_b32 m0, s56
	ds_read_b128 v[190:193], v152 offset:16384
	ds_read_b128 v[194:197], v152 offset:17408
	ds_read_b128 v[198:201], v152 offset:18432
	ds_read_b128 v[202:205], v152 offset:19456
	ds_read_b128 v[206:209], v152 offset:20480
	ds_read_b128 v[210:213], v152 offset:21504
	ds_read_b128 v[214:217], v152 offset:22528
	ds_read_b128 v[218:221], v152 offset:23552
	global_load_lds_dwordx4 v[166:167], off
	s_add_i32 m0, s56, 0x2000
	s_add_u32 s56, s20, 0x164000
	v_lshl_add_u64 v[222:223], s[20:21], 0, v[134:135]
	s_addc_u32 s57, s21, 0
	s_add_i32 s58, s47, s36
	global_load_lds_dwordx4 v[222:223], off
	v_lshl_add_u64 v[224:225], s[56:57], 0, v[130:131]
	s_mov_b32 m0, s58
	v_lshl_add_u64 v[226:227], s[22:23], 0, v[132:133]
	global_load_lds_dwordx4 v[224:225], off
	v_lshl_add_u64 v[224:225], s[56:57], 0, v[134:135]
	s_add_i32 m0, s58, 0x2000
	s_nop 0
	global_load_lds_dwordx4 v[224:225], off
	v_lshl_add_u64 v[224:225], s[22:23], 0, v[128:129]
	s_mov_b32 m0, s37
	s_nop 0
	global_load_lds_dwordx4 v[224:225], off
	s_mov_b32 m0, s38
	s_nop 0
	global_load_lds_dwordx4 v[226:227], off
	s_waitcnt vmcnt(8)
	s_waitcnt lgkmcnt(0)
	s_barrier
; #define PG8_STAGE(bufoff, gbase, voff) do { _Pragma("unroll") for (int _i = 0; _i < 2; ++_i) \
;         __builtin_amdgcn_global_load_lds((const unsigned*)((const char*)(gbase) + (voff)[_i]), (LAS unsigned*)(lds + (bufoff) + ldsw + _i * 8192), 16, 0, 0); } while (0)
; #define PG8_LDA(dst, b, h) do { _Pragma("unroll") for (int m = 0; m < 4; ++m) _Pragma("unroll") for (int k = 0; k < 2; ++k) dst[m][k] = *(const LAS bf16x8*)(lds + PG8_SA(b, h) + aoff + m * 2048 + k * 1024); } while (0)
; #define PG8_LDB(dst, b, h) do { _Pragma("unroll") for (int n = 0; n < 2; ++n) _Pragma("unroll") for (int k = 0; k < 2; ++k) dst[n][k] = *(const LAS bf16x8*)(lds + PG8_SB(b, h) + boff + n * 2048 + k * 1024); } while (0)
; #define PG8_MMA(ai, bj, At, Bt) do { __builtin_amdgcn_s_setprio(1); _Pragma("unroll") for (int m = 0; m < 4; ++m) _Pragma("unroll") for (int n = 0; n < 2; ++n) _Pragma("unroll") for (int k = 0; k < 2; ++k) \
;         acc[ai][bj][m][n] = __builtin_amdgcn_mfma_f32_16x16x32_bf16(Bt[n][k], At[m][k], acc[ai][bj][m][n], 0, 0, 0); __builtin_amdgcn_s_setprio(0); } while (0)
; #define PG8_WAIT_V(n) asm volatile("s_waitcnt vmcnt(" #n ")" ::: "memory")
; #define PG8_WAIT_L(n) asm volatile("s_waitcnt lgkmcnt(" #n ")" ::: "memory")
; #define PG8_BAR __builtin_amdgcn_s_barrier()
; #define PG8_SCHED __builtin_amdgcn_sched_barrier(0)
; template <class EpiT>
; __device__ __forceinline__ void gemm_phase(LAS unsigned char* lds, const Gemm g, const StaticOrder& S, const EpiT& E) {
;     ...
;             PG8_WAIT_V(8); PG8_WAIT_L(0); PG8_BAR; PG8_MMA(1, 0, At, B0); PG8_MMA(1, 1, At, B1); PG8_BAR; PG8_SCHED;
;             PG8_LDB(B0, 1, 0); PG8_LDB(B1, 1, 1); PG8_SCHED; PG8_LDA(At, 1, 0); PG8_STAGE(PG8_SA(0, 1), a2 + hstepA, voffA);
;             PG8_WAIT_V(8); PG8_WAIT_L(0); PG8_BAR; PG8_MMA(0, 0, At, B0); PG8_MMA(0, 1, At, B1); PG8_BAR; PG8_SCHED;
	s_setprio 1
	s_waitcnt lgkmcnt(0)
	v_mfma_f32_16x16x32_bf16 v[60:63], v[154:157], v[190:193], v[60:63]
	v_mfma_f32_16x16x32_bf16 v[60:63], v[158:161], v[194:197], v[60:63]
	v_mfma_f32_16x16x32_bf16 v[44:47], v[154:157], v[198:201], v[44:47]
	v_mfma_f32_16x16x32_bf16 v[44:47], v[158:161], v[202:205], v[44:47]
	v_mfma_f32_16x16x32_bf16 v[28:31], v[154:157], v[206:209], v[28:31]
	v_mfma_f32_16x16x32_bf16 v[28:31], v[158:161], v[210:213], v[28:31]
	v_mfma_f32_16x16x32_bf16 v[12:15], v[154:157], v[214:217], v[12:15]
	v_mfma_f32_16x16x32_bf16 v[12:15], v[158:161], v[218:221], v[12:15]
	v_mfma_f32_16x16x32_bf16 v[56:59], v[162:165], v[190:193], v[56:59]
	v_mfma_f32_16x16x32_bf16 v[56:59], v[170:173], v[194:197], v[56:59]
	v_mfma_f32_16x16x32_bf16 v[40:43], v[162:165], v[198:201], v[40:43]
	v_mfma_f32_16x16x32_bf16 v[40:43], v[170:173], v[202:205], v[40:43]
	v_mfma_f32_16x16x32_bf16 v[24:27], v[162:165], v[206:209], v[24:27]
	v_mfma_f32_16x16x32_bf16 v[24:27], v[170:173], v[210:213], v[24:27]
	v_mfma_f32_16x16x32_bf16 v[8:11], v[162:165], v[214:217], v[8:11]
	v_mfma_f32_16x16x32_bf16 v[8:11], v[170:173], v[218:221], v[8:11]
	v_mfma_f32_16x16x32_bf16 v[52:55], v[174:177], v[190:193], v[52:55]
	v_mfma_f32_16x16x32_bf16 v[52:55], v[178:181], v[194:197], v[52:55]
	v_mfma_f32_16x16x32_bf16 v[36:39], v[174:177], v[198:201], v[36:39]
	v_mfma_f32_16x16x32_bf16 v[36:39], v[178:181], v[202:205], v[36:39]
	v_mfma_f32_16x16x32_bf16 v[20:23], v[174:177], v[206:209], v[20:23]
	v_mfma_f32_16x16x32_bf16 v[20:23], v[178:181], v[210:213], v[20:23]
	v_mfma_f32_16x16x32_bf16 v[4:7], v[174:177], v[214:217], v[4:7]
	v_mfma_f32_16x16x32_bf16 v[4:7], v[178:181], v[218:221], v[4:7]
	v_mfma_f32_16x16x32_bf16 v[48:51], v[182:185], v[190:193], v[48:51]
	v_mfma_f32_16x16x32_bf16 v[48:51], v[186:189], v[194:197], v[48:51]
	v_mfma_f32_16x16x32_bf16 v[32:35], v[182:185], v[198:201], v[32:35]
	v_mfma_f32_16x16x32_bf16 v[32:35], v[186:189], v[202:205], v[32:35]
	v_mfma_f32_16x16x32_bf16 v[16:19], v[182:185], v[206:209], v[16:19]
	v_mfma_f32_16x16x32_bf16 v[16:19], v[186:189], v[210:213], v[16:19]
	v_mfma_f32_16x16x32_bf16 v[0:3], v[182:185], v[214:217], v[0:3]
	v_mfma_f32_16x16x32_bf16 v[0:3], v[186:189], v[218:221], v[0:3]
	s_setprio 0
	s_barrier
	s_add_i32 s56, 0, 0x18000
	s_add_i32 s57, 0, 0x1c000
	v_add_u32_e32 v170, s56, v146
	v_add_u32_e32 v186, s57, v146
	ds_read_b128 v[154:157], v170
	ds_read_b128 v[158:161], v170 offset:1024
	ds_read_b128 v[162:165], v170 offset:2048
	ds_read_b128 v[170:173], v170 offset:3072
	ds_read_b128 v[174:177], v186
	ds_read_b128 v[178:181], v186 offset:1024
	ds_read_b128 v[182:185], v186 offset:2048
	ds_read_b128 v[186:189], v186 offset:3072
	s_add_u32 s22, s22, 0x164000
	s_addc_u32 s23, s23, 0
	s_mov_b32 m0, s39
	v_lshl_add_u64 v[228:229], s[22:23], 0, v[128:129]
	ds_read_b128 v[190:193], v152 offset:32768
	ds_read_b128 v[194:197], v152 offset:33792
	ds_read_b128 v[198:201], v152 offset:34816
	ds_read_b128 v[202:205], v152 offset:35840
	ds_read_b128 v[206:209], v152 offset:36864
	ds_read_b128 v[210:213], v152 offset:37888
	ds_read_b128 v[214:217], v152 offset:38912
	ds_read_b128 v[218:221], v152 offset:39936
	global_load_lds_dwordx4 v[228:229], off
	v_lshl_add_u64 v[228:229], s[22:23], 0, v[132:133]
	s_mov_b32 m0, s40
	s_nop 0
	global_load_lds_dwordx4 v[228:229], off
	s_waitcnt vmcnt(8)
	s_waitcnt lgkmcnt(0)
	s_barrier
	s_setprio 1
	s_waitcnt lgkmcnt(0)
	v_mfma_f32_16x16x32_bf16 v[124:127], v[154:157], v[190:193], v[124:127]
	v_mfma_f32_16x16x32_bf16 v[124:127], v[158:161], v[194:197], v[124:127]
	v_mfma_f32_16x16x32_bf16 v[108:111], v[154:157], v[198:201], v[108:111]
	v_mfma_f32_16x16x32_bf16 v[108:111], v[158:161], v[202:205], v[108:111]
	v_mfma_f32_16x16x32_bf16 v[92:95], v[154:157], v[206:209], v[92:95]
	v_mfma_f32_16x16x32_bf16 v[92:95], v[158:161], v[210:213], v[92:95]
	v_mfma_f32_16x16x32_bf16 v[76:79], v[154:157], v[214:217], v[76:79]
	v_mfma_f32_16x16x32_bf16 v[76:79], v[158:161], v[218:221], v[76:79]
	v_mfma_f32_16x16x32_bf16 v[120:123], v[162:165], v[190:193], v[120:123]
	v_mfma_f32_16x16x32_bf16 v[120:123], v[170:173], v[194:197], v[120:123]
	v_mfma_f32_16x16x32_bf16 v[104:107], v[162:165], v[198:201], v[104:107]
	v_mfma_f32_16x16x32_bf16 v[104:107], v[170:173], v[202:205], v[104:107]
	v_mfma_f32_16x16x32_bf16 v[88:91], v[162:165], v[206:209], v[88:91]
	v_mfma_f32_16x16x32_bf16 v[88:91], v[170:173], v[210:213], v[88:91]
	v_mfma_f32_16x16x32_bf16 v[72:75], v[162:165], v[214:217], v[72:75]
	v_mfma_f32_16x16x32_bf16 v[72:75], v[170:173], v[218:221], v[72:75]
	v_mfma_f32_16x16x32_bf16 v[116:119], v[174:177], v[190:193], v[116:119]
	v_mfma_f32_16x16x32_bf16 v[116:119], v[178:181], v[194:197], v[116:119]
	v_mfma_f32_16x16x32_bf16 v[100:103], v[174:177], v[198:201], v[100:103]
	v_mfma_f32_16x16x32_bf16 v[100:103], v[178:181], v[202:205], v[100:103]
	v_mfma_f32_16x16x32_bf16 v[84:87], v[174:177], v[206:209], v[84:87]
	v_mfma_f32_16x16x32_bf16 v[84:87], v[178:181], v[210:213], v[84:87]
	v_mfma_f32_16x16x32_bf16 v[68:71], v[174:177], v[214:217], v[68:71]
	v_mfma_f32_16x16x32_bf16 v[68:71], v[178:181], v[218:221], v[68:71]
	v_mfma_f32_16x16x32_bf16 v[112:115], v[182:185], v[190:193], v[112:115]
	v_mfma_f32_16x16x32_bf16 v[112:115], v[186:189], v[194:197], v[112:115]
	v_mfma_f32_16x16x32_bf16 v[96:99], v[182:185], v[198:201], v[96:99]
	v_mfma_f32_16x16x32_bf16 v[96:99], v[186:189], v[202:205], v[96:99]
	v_mfma_f32_16x16x32_bf16 v[80:83], v[182:185], v[206:209], v[80:83]
	v_mfma_f32_16x16x32_bf16 v[80:83], v[186:189], v[210:213], v[80:83]
	v_mfma_f32_16x16x32_bf16 v[64:67], v[182:185], v[214:217], v[64:67]
	v_mfma_f32_16x16x32_bf16 v[64:67], v[186:189], v[218:221], v[64:67]
	s_setprio 0
	s_barrier
; #define PG8_STAGE(bufoff, gbase, voff) do { _Pragma("unroll") for (int _i = 0; _i < 2; ++_i) \
;         __builtin_amdgcn_global_load_lds((const unsigned*)((const char*)(gbase) + (voff)[_i]), (LAS unsigned*)(lds + (bufoff) + ldsw + _i * 8192), 16, 0, 0); } while (0)
; #define PG8_LDA(dst, b, h) do { _Pragma("unroll") for (int m = 0; m < 4; ++m) _Pragma("unroll") for (int k = 0; k < 2; ++k) dst[m][k] = *(const LAS bf16x8*)(lds + PG8_SA(b, h) + aoff + m * 2048 + k * 1024); } while (0)
; #define PG8_MMA(ai, bj, At, Bt) do { __builtin_amdgcn_s_setprio(1); _Pragma("unroll") for (int m = 0; m < 4; ++m) _Pragma("unroll") for (int n = 0; n < 2; ++n) _Pragma("unroll") for (int k = 0; k < 2; ++k) \
;         acc[ai][bj][m][n] = __builtin_amdgcn_mfma_f32_16x16x32_bf16(Bt[n][k], At[m][k], acc[ai][bj][m][n], 0, 0, 0); __builtin_amdgcn_s_setprio(0); } while (0)
; #define PG8_WAIT_V(n) asm volatile("s_waitcnt vmcnt(" #n ")" ::: "memory")
; #define PG8_WAIT_L(n) asm volatile("s_waitcnt lgkmcnt(" #n ")" ::: "memory")
; #define PG8_BAR __builtin_amdgcn_s_barrier()
; #define PG8_SCHED __builtin_amdgcn_sched_barrier(0)
; template <class EpiT>
; __device__ __forceinline__ void gemm_phase(LAS unsigned char* lds, const Gemm g, const StaticOrder& S, const EpiT& E) {
;     ...
;             PG8_LDA(At, 1, 1); PG8_STAGE(PG8_SB(1, 0), b3, voffB); PG8_STAGE(PG8_SB(1, 1), b3 + hstepB, voffB); PG8_STAGE(PG8_SA(1, 0), a3, voffA);
;             PG8_WAIT_V(8); PG8_WAIT_L(0); PG8_BAR; PG8_MMA(1, 0, At, B0); PG8_MMA(1, 1, At, B1); PG8_BAR; PG8_SCHED;
;         }
;         if (wr == 0) PG8_BAR;
	s_add_i32 s22, s56, s36
	v_lshl_add_u64 v[166:167], v[166:167], 0, s[12:13]
	s_mov_b32 m0, s22
	ds_read_b128 v[190:193], v152 offset:49152
	ds_read_b128 v[194:197], v152 offset:50176
	ds_read_b128 v[198:201], v152 offset:51200
	ds_read_b128 v[202:205], v152 offset:52224
	ds_read_b128 v[206:209], v152 offset:53248
	ds_read_b128 v[210:213], v152 offset:54272
	ds_read_b128 v[214:217], v152 offset:55296
	ds_read_b128 v[218:221], v152 offset:56320
	global_load_lds_dwordx4 v[166:167], off
	s_add_i32 m0, s22, 0x2000
	s_add_u32 s20, s20, 0x164080
	v_lshl_add_u64 v[166:167], v[222:223], 0, s[12:13]
	s_addc_u32 s21, s21, 0
	s_add_i32 s22, s57, s36
	global_load_lds_dwordx4 v[166:167], off
	v_lshl_add_u64 v[166:167], s[20:21], 0, v[130:131]
	s_mov_b32 m0, s22
	s_nop 0
	global_load_lds_dwordx4 v[166:167], off
	v_lshl_add_u64 v[166:167], s[20:21], 0, v[134:135]
	s_add_i32 m0, s22, 0x2000
	s_nop 0
	global_load_lds_dwordx4 v[166:167], off
	v_lshl_add_u64 v[166:167], v[224:225], 0, s[12:13]
	s_mov_b32 m0, s42
	s_nop 0
	global_load_lds_dwordx4 v[166:167], off
	v_lshl_add_u64 v[166:167], v[226:227], 0, s[12:13]
	s_mov_b32 m0, s43
	s_nop 0
	global_load_lds_dwordx4 v[166:167], off
	s_waitcnt vmcnt(8)
	s_waitcnt lgkmcnt(0)
	s_barrier
	s_setprio 1
	s_waitcnt lgkmcnt(0)
	v_mfma_f32_16x16x32_bf16 v[60:63], v[154:157], v[190:193], v[60:63]
	v_mfma_f32_16x16x32_bf16 v[60:63], v[158:161], v[194:197], v[60:63]
	v_mfma_f32_16x16x32_bf16 v[44:47], v[154:157], v[198:201], v[44:47]
	v_mfma_f32_16x16x32_bf16 v[44:47], v[158:161], v[202:205], v[44:47]
	v_mfma_f32_16x16x32_bf16 v[28:31], v[154:157], v[206:209], v[28:31]
	v_mfma_f32_16x16x32_bf16 v[28:31], v[158:161], v[210:213], v[28:31]
	v_mfma_f32_16x16x32_bf16 v[12:15], v[154:157], v[214:217], v[12:15]
	v_mfma_f32_16x16x32_bf16 v[12:15], v[158:161], v[218:221], v[12:15]
	v_mfma_f32_16x16x32_bf16 v[56:59], v[162:165], v[190:193], v[56:59]
	v_mfma_f32_16x16x32_bf16 v[56:59], v[170:173], v[194:197], v[56:59]
	v_mfma_f32_16x16x32_bf16 v[40:43], v[162:165], v[198:201], v[40:43]
	v_mfma_f32_16x16x32_bf16 v[40:43], v[170:173], v[202:205], v[40:43]
	v_mfma_f32_16x16x32_bf16 v[24:27], v[162:165], v[206:209], v[24:27]
	v_mfma_f32_16x16x32_bf16 v[24:27], v[170:173], v[210:213], v[24:27]
	v_mfma_f32_16x16x32_bf16 v[8:11], v[162:165], v[214:217], v[8:11]
	v_mfma_f32_16x16x32_bf16 v[8:11], v[170:173], v[218:221], v[8:11]
	v_mfma_f32_16x16x32_bf16 v[52:55], v[174:177], v[190:193], v[52:55]
	v_mfma_f32_16x16x32_bf16 v[52:55], v[178:181], v[194:197], v[52:55]
	v_mfma_f32_16x16x32_bf16 v[36:39], v[174:177], v[198:201], v[36:39]
	v_mfma_f32_16x16x32_bf16 v[36:39], v[178:181], v[202:205], v[36:39]
	v_mfma_f32_16x16x32_bf16 v[20:23], v[174:177], v[206:209], v[20:23]
	v_mfma_f32_16x16x32_bf16 v[20:23], v[178:181], v[210:213], v[20:23]
	v_mfma_f32_16x16x32_bf16 v[4:7], v[174:177], v[214:217], v[4:7]
	v_mfma_f32_16x16x32_bf16 v[4:7], v[178:181], v[218:221], v[4:7]
	v_mfma_f32_16x16x32_bf16 v[48:51], v[182:185], v[190:193], v[48:51]
	v_mfma_f32_16x16x32_bf16 v[48:51], v[186:189], v[194:197], v[48:51]
	v_mfma_f32_16x16x32_bf16 v[32:35], v[182:185], v[198:201], v[32:35]
	v_mfma_f32_16x16x32_bf16 v[32:35], v[186:189], v[202:205], v[32:35]
	v_mfma_f32_16x16x32_bf16 v[16:19], v[182:185], v[206:209], v[16:19]
	v_mfma_f32_16x16x32_bf16 v[16:19], v[186:189], v[210:213], v[16:19]
	v_mfma_f32_16x16x32_bf16 v[0:3], v[182:185], v[214:217], v[0:3]
	v_mfma_f32_16x16x32_bf16 v[0:3], v[186:189], v[218:221], v[0:3]
	s_setprio 0
	s_barrier
	s_add_i32 s55, s55, 2
	s_add_u32 s18, s18, 0x100
	s_addc_u32 s19, s19, 0
	s_add_u32 s53, s53, 0x100
	s_addc_u32 s54, s54, 0
	s_cmpk_gt_u32 s55, 0x55
	s_cbranch_scc0 .LBB0_1235
	s_and_b64 vcc, exec, s[14:15]
	s_cbranch_vccz .LBB0_1238
	s_barrier
